# prowait + strategy 4 variant: removed the per-segment s_setprio 1/0 toggling around MFMA clusters in the five GEMM K-loops (120 instructions)
# baseline (speedup 1.0000x reference)
; #define PG8_STAGE(bufoff, gbase, voff) do { _Pragma("unroll") for (int _i = 0; _i < 2; ++_i) \
;         __builtin_amdgcn_global_load_lds((const unsigned*)((const char*)(gbase) + (voff)[_i]), (PG8_LAS unsigned*)(lds + (bufoff) + ldsw + _i * 8192), 16, 0, 0); } while (0)
; #define PG8_LDA(dst, b, h) do { _Pragma("unroll") for (int m = 0; m < 4; ++m) _Pragma("unroll") for (int k = 0; k < 2; ++k) dst[m][k] = *(const PG8_LAS bf16x8*)(lds + PG8_SA(b, h) + aoff + m * 2048 + k * 1024); } while (0)
; #define PG8_LDB(dst, b, h) do { _Pragma("unroll") for (int n = 0; n < 2; ++n) _Pragma("unroll") for (int k = 0; k < 2; ++k) dst[n][k] = *(const PG8_LAS bf16x8*)(lds + PG8_SB(b, h) + boff + n * 2048 + k * 1024); } while (0)
; #define PG8_MMA(ai, bj, At, Bt) do { __builtin_amdgcn_s_setprio(1); _Pragma("unroll") for (int m = 0; m < 4; ++m) _Pragma("unroll") for (int n = 0; n < 2; ++n) _Pragma("unroll") for (int k = 0; k < 2; ++k) \
;         acc[ai][bj][m][n] = __builtin_amdgcn_mfma_f32_16x16x32_bf16(Bt[n][k], At[m][k], acc[ai][bj][m][n], 0, 0, 0); __builtin_amdgcn_s_setprio(0); } while (0)
; #define PG8_WAIT_V(n) asm volatile("s_waitcnt vmcnt(" #n ")" ::: "memory")
; #define PG8_WAIT_L(n) asm volatile("s_waitcnt lgkmcnt(" #n ")" ::: "memory")
; template <class Epi, class Sched, bool ALIGN_EPI = false, bool SP2 = false>
; __device__ __forceinline__ void gemm_phase(PG8_LAS unsigned char* lds, const Gemm g, const Sched& S, const Epi& E) {
;     ...
;         for (int t = 0; t < nt; t += 2) {
;             const bool last = (t == nt - 2);
;             const char* a1 = cA + (size_t)(t + 1) * kstep;
;             const char* a2 = last ? nA : cA + (size_t)(t + 2) * kstep; const char* b2 = last ? nB : cB + (size_t)(t + 2) * kstep;
;             const char* a3 = a2 + kstep; const char* b3 = b2 + kstep;
;             if (last && has_next) S.a_ready(nxt);
;     ...
;             PG8_LDB(B0, 0, 0); PG8_LDB(B1, 0, 1); PG8_SCHED; PG8_LDA(At, 0, 0); PG8_STAGE(PG8_SA(1, 1), a1 + hstep, voffA);
;             PG8_WAIT_V(8); PG8_WAIT_L(0); PG8_BAR; PG8_MMA(0, 0, At, B0); PG8_MMA(0, 1, At, B1); PG8_BAR; PG8_SCHED;
;             PG8_LDA(At, 0, 1); PG8_STAGE(PG8_SB(0, 0), b2, voffB); PG8_STAGE(PG8_SB(0, 1), b2 + hstep, voffB); PG8_STAGE(PG8_SA(0, 0), a2, voffA);
;             PG8_WAIT_V(8); PG8_WAIT_L(0); PG8_BAR; PG8_MMA(1, 0, At, B0); PG8_MMA(1, 1, At, B1); PG8_BAR; PG8_SCHED;
.Lpeel_g1o:
	s_add_u32 s5, s44, 0xfffc0080
	s_addc_u32 s8, s45, -1
	s_add_i32 s10, 0, 0x10000
	s_cmp_eq_u32 s76, 12
	s_cselect_b32 s67, s26, s8
	s_cselect_b32 s66, s27, s5
	v_add_u32_e32 v154, s10, v157
	s_cselect_b32 s65, s36, s59
	s_cselect_b32 s64, s39, s57
	s_add_i32 s5, 0, 0x14000
	ds_read_b128 v[162:165], v154
	ds_read_b128 v[166:169], v154 offset:1024
	ds_read_b128 v[170:173], v154 offset:2048
	ds_read_b128 v[174:177], v154 offset:3072
	v_add_u32_e32 v154, s5, v157
	ds_read_b128 v[178:181], v154
	ds_read_b128 v[182:185], v154 offset:1024
	ds_read_b128 v[186:189], v154 offset:2048
	ds_read_b128 v[190:193], v154 offset:3072
	v_lshl_add_u64 v[194:195], s[44:45], 0, v[140:141]
	s_add_i32 m0, s69, 0xc000
	ds_read_b128 v[200:203], v161
	ds_read_b128 v[204:207], v161 offset:1024
	ds_read_b128 v[208:211], v161 offset:2048
	ds_read_b128 v[212:215], v161 offset:3072
	ds_read_b128 v[216:219], v161 offset:4096
	ds_read_b128 v[220:223], v161 offset:5120
	ds_read_b128 v[224:227], v161 offset:6144
	ds_read_b128 v[228:231], v161 offset:7168
	global_load_lds_dwordx4 v[194:195], off
	v_lshl_add_u64 v[194:195], s[44:45], 0, v[138:139]
	s_add_i32 m0, s69, 0xe000
	s_nop 0
	global_load_lds_dwordx4 v[194:195], off
	s_waitcnt vmcnt(10)
	s_waitcnt lgkmcnt(0)
	s_barrier
	s_waitcnt lgkmcnt(0)
	v_mfma_f32_16x16x32_bf16 v[124:127], v[162:165], v[200:203], 0
	v_mfma_f32_16x16x32_bf16 v[120:123], v[170:173], v[200:203], 0
	v_mfma_f32_16x16x32_bf16 v[108:111], v[162:165], v[208:211], 0
	v_mfma_f32_16x16x32_bf16 v[104:107], v[170:173], v[208:211], 0
	v_mfma_f32_16x16x32_bf16 v[92:95], v[162:165], v[216:219], 0
	v_mfma_f32_16x16x32_bf16 v[88:91], v[170:173], v[216:219], 0
	v_mfma_f32_16x16x32_bf16 v[76:79], v[162:165], v[224:227], 0
	v_mfma_f32_16x16x32_bf16 v[72:75], v[170:173], v[224:227], 0
	v_mfma_f32_16x16x32_bf16 v[124:127], v[166:169], v[204:207], v[124:127]
	v_mfma_f32_16x16x32_bf16 v[120:123], v[174:177], v[204:207], v[120:123]
	v_mfma_f32_16x16x32_bf16 v[108:111], v[166:169], v[212:215], v[108:111]
	v_mfma_f32_16x16x32_bf16 v[104:107], v[174:177], v[212:215], v[104:107]
	v_mfma_f32_16x16x32_bf16 v[92:95], v[166:169], v[220:223], v[92:95]
	v_mfma_f32_16x16x32_bf16 v[88:91], v[174:177], v[220:223], v[88:91]
	v_mfma_f32_16x16x32_bf16 v[76:79], v[166:169], v[228:231], v[76:79]
	v_mfma_f32_16x16x32_bf16 v[72:75], v[174:177], v[228:231], v[72:75]
	v_mfma_f32_16x16x32_bf16 v[116:119], v[178:181], v[200:203], 0
	v_mfma_f32_16x16x32_bf16 v[112:115], v[186:189], v[200:203], 0
	v_mfma_f32_16x16x32_bf16 v[100:103], v[178:181], v[208:211], 0
	v_mfma_f32_16x16x32_bf16 v[96:99], v[186:189], v[208:211], 0
	v_mfma_f32_16x16x32_bf16 v[84:87], v[178:181], v[216:219], 0
	v_mfma_f32_16x16x32_bf16 v[80:83], v[186:189], v[216:219], 0
	v_mfma_f32_16x16x32_bf16 v[68:71], v[178:181], v[224:227], 0
	v_mfma_f32_16x16x32_bf16 v[64:67], v[186:189], v[224:227], 0
	v_mfma_f32_16x16x32_bf16 v[116:119], v[182:185], v[204:207], v[116:119]
	v_mfma_f32_16x16x32_bf16 v[112:115], v[190:193], v[204:207], v[112:115]
	v_mfma_f32_16x16x32_bf16 v[100:103], v[182:185], v[212:215], v[100:103]
	v_mfma_f32_16x16x32_bf16 v[96:99], v[190:193], v[212:215], v[96:99]
	v_mfma_f32_16x16x32_bf16 v[84:87], v[182:185], v[220:223], v[84:87]
	v_mfma_f32_16x16x32_bf16 v[80:83], v[190:193], v[220:223], v[80:83]
	v_mfma_f32_16x16x32_bf16 v[68:71], v[182:185], v[228:231], v[68:71]
	v_mfma_f32_16x16x32_bf16 v[64:67], v[190:193], v[228:231], v[64:67]
	s_barrier
	s_add_i32 s8, s10, s68
	v_lshl_add_u64 v[194:195], s[64:65], 0, v[132:133]
	s_mov_b32 m0, s8
	ds_read_b128 v[200:203], v161 offset:16384
	ds_read_b128 v[204:207], v161 offset:17408
	ds_read_b128 v[208:211], v161 offset:18432
	ds_read_b128 v[212:215], v161 offset:19456
	ds_read_b128 v[216:219], v161 offset:20480
	ds_read_b128 v[220:223], v161 offset:21504
	ds_read_b128 v[224:227], v161 offset:22528
	ds_read_b128 v[228:231], v161 offset:23552
	global_load_lds_dwordx4 v[194:195], off
	s_add_i32 m0, s8, 0x2000
	s_add_u32 s20, s64, 0x40000
	v_lshl_add_u64 v[240:241], s[64:65], 0, v[128:129]
	s_addc_u32 s21, s65, 0
	s_add_i32 s5, s5, s68
	global_load_lds_dwordx4 v[240:241], off
	v_lshl_add_u64 v[242:243], s[20:21], 0, v[132:133]
	s_mov_b32 m0, s5
	v_lshl_add_u64 v[244:245], s[66:67], 0, v[130:131]
	global_load_lds_dwordx4 v[242:243], off
	v_lshl_add_u64 v[242:243], s[20:21], 0, v[128:129]
	s_add_i32 m0, s5, 0x2000
	s_nop 0
	global_load_lds_dwordx4 v[242:243], off
	v_lshl_add_u64 v[242:243], s[66:67], 0, v[134:135]
	s_mov_b32 m0, s69
	s_nop 0
	global_load_lds_dwordx4 v[242:243], off
	s_mov_b32 m0, s70
	s_nop 0
	global_load_lds_dwordx4 v[244:245], off
	s_waitcnt vmcnt(10)
	s_waitcnt lgkmcnt(0)
	s_barrier
	s_waitcnt lgkmcnt(0)
	v_mfma_f32_16x16x32_bf16 v[60:63], v[162:165], v[200:203], 0
	v_mfma_f32_16x16x32_bf16 v[56:59], v[170:173], v[200:203], 0
	v_mfma_f32_16x16x32_bf16 v[44:47], v[162:165], v[208:211], 0
	v_mfma_f32_16x16x32_bf16 v[40:43], v[170:173], v[208:211], 0
	v_mfma_f32_16x16x32_bf16 v[28:31], v[162:165], v[216:219], 0
	v_mfma_f32_16x16x32_bf16 v[24:27], v[170:173], v[216:219], 0
	v_mfma_f32_16x16x32_bf16 v[12:15], v[162:165], v[224:227], 0
	v_mfma_f32_16x16x32_bf16 v[8:11], v[170:173], v[224:227], 0
	v_mfma_f32_16x16x32_bf16 v[60:63], v[166:169], v[204:207], v[60:63]
	v_mfma_f32_16x16x32_bf16 v[56:59], v[174:177], v[204:207], v[56:59]
	v_mfma_f32_16x16x32_bf16 v[44:47], v[166:169], v[212:215], v[44:47]
	v_mfma_f32_16x16x32_bf16 v[40:43], v[174:177], v[212:215], v[40:43]
	v_mfma_f32_16x16x32_bf16 v[28:31], v[166:169], v[220:223], v[28:31]
	v_mfma_f32_16x16x32_bf16 v[24:27], v[174:177], v[220:223], v[24:27]
	v_mfma_f32_16x16x32_bf16 v[12:15], v[166:169], v[228:231], v[12:15]
	v_mfma_f32_16x16x32_bf16 v[8:11], v[174:177], v[228:231], v[8:11]
	v_mfma_f32_16x16x32_bf16 v[52:55], v[178:181], v[200:203], 0
	v_mfma_f32_16x16x32_bf16 v[48:51], v[186:189], v[200:203], 0
	v_mfma_f32_16x16x32_bf16 v[36:39], v[178:181], v[208:211], 0
	v_mfma_f32_16x16x32_bf16 v[32:35], v[186:189], v[208:211], 0
	v_mfma_f32_16x16x32_bf16 v[20:23], v[178:181], v[216:219], 0
	v_mfma_f32_16x16x32_bf16 v[16:19], v[186:189], v[216:219], 0
	v_mfma_f32_16x16x32_bf16 v[4:7], v[178:181], v[224:227], 0
	v_mfma_f32_16x16x32_bf16 v[0:3], v[186:189], v[224:227], 0
	v_mfma_f32_16x16x32_bf16 v[52:55], v[182:185], v[204:207], v[52:55]
	v_mfma_f32_16x16x32_bf16 v[48:51], v[190:193], v[204:207], v[48:51]
	v_mfma_f32_16x16x32_bf16 v[36:39], v[182:185], v[212:215], v[36:39]
	v_mfma_f32_16x16x32_bf16 v[32:35], v[190:193], v[212:215], v[32:35]
	v_mfma_f32_16x16x32_bf16 v[20:23], v[182:185], v[220:223], v[20:23]
	v_mfma_f32_16x16x32_bf16 v[16:19], v[190:193], v[220:223], v[16:19]
	v_mfma_f32_16x16x32_bf16 v[4:7], v[182:185], v[228:231], v[4:7]
	v_mfma_f32_16x16x32_bf16 v[0:3], v[190:193], v[228:231], v[0:3]
	s_barrier
	s_branch .Lmid_g1o

; #define PG8_STAGE(bufoff, gbase, voff) do { _Pragma("unroll") for (int _i = 0; _i < 2; ++_i) \
;         __builtin_amdgcn_global_load_lds((const unsigned*)((const char*)(gbase) + (voff)[_i]), (PG8_LAS unsigned*)(lds + (bufoff) + ldsw + _i * 8192), 16, 0, 0); } while (0)
; #define PG8_LDA(dst, b, h) do { _Pragma("unroll") for (int m = 0; m < 4; ++m) _Pragma("unroll") for (int k = 0; k < 2; ++k) dst[m][k] = *(const PG8_LAS bf16x8*)(lds + PG8_SA(b, h) + aoff + m * 2048 + k * 1024); } while (0)
; #define PG8_LDB(dst, b, h) do { _Pragma("unroll") for (int n = 0; n < 2; ++n) _Pragma("unroll") for (int k = 0; k < 2; ++k) dst[n][k] = *(const PG8_LAS bf16x8*)(lds + PG8_SB(b, h) + boff + n * 2048 + k * 1024); } while (0)
; #define PG8_MMA(ai, bj, At, Bt) do { __builtin_amdgcn_s_setprio(1); _Pragma("unroll") for (int m = 0; m < 4; ++m) _Pragma("unroll") for (int n = 0; n < 2; ++n) _Pragma("unroll") for (int k = 0; k < 2; ++k) \
;         acc[ai][bj][m][n] = __builtin_amdgcn_mfma_f32_16x16x32_bf16(Bt[n][k], At[m][k], acc[ai][bj][m][n], 0, 0, 0); __builtin_amdgcn_s_setprio(0); } while (0)
; #define PG8_WAIT_V(n) asm volatile("s_waitcnt vmcnt(" #n ")" ::: "memory")
; #define PG8_WAIT_L(n) asm volatile("s_waitcnt lgkmcnt(" #n ")" ::: "memory")
; #define PG8_BAR __builtin_amdgcn_s_barrier()
; #define PG8_SCHED __builtin_amdgcn_sched_barrier(0)
; template <class Epi, class Sched, bool ALIGN_EPI = false, bool SP2 = false>
; __device__ __forceinline__ void gemm_phase(PG8_LAS unsigned char* lds, const Gemm g, const Sched& S, const Epi& E) {
;     ...
;             PG8_LDB(B0, 0, 0); PG8_LDB(B1, 0, 1); PG8_SCHED; PG8_LDA(At, 0, 0); PG8_STAGE(PG8_SA(1, 1), a1 + hstep, voffA);
;             PG8_WAIT_V(8); PG8_WAIT_L(0); PG8_BAR; PG8_MMA(0, 0, At, B0); PG8_MMA(0, 1, At, B1); PG8_BAR; PG8_SCHED;
;             PG8_LDA(At, 0, 1); PG8_STAGE(PG8_SB(0, 0), b2, voffB); PG8_STAGE(PG8_SB(0, 1), b2 + hstep, voffB); PG8_STAGE(PG8_SA(0, 0), a2, voffA);
;             PG8_WAIT_V(8); PG8_WAIT_L(0); PG8_BAR; PG8_MMA(1, 0, At, B0); PG8_MMA(1, 1, At, B1); PG8_BAR; PG8_SCHED;
.LBB0_54:
	s_add_u32 s5, s44, 0xfffc0080
	s_addc_u32 s8, s45, -1
	s_add_i32 s10, 0, 0x10000
	s_cmp_eq_u32 s76, 12
	s_cselect_b32 s67, s26, s8
	s_cselect_b32 s66, s27, s5
	v_add_u32_e32 v154, s10, v157
	s_cselect_b32 s65, s36, s59
	s_cselect_b32 s64, s39, s57
	s_add_i32 s5, 0, 0x14000
	ds_read_b128 v[162:165], v154
	ds_read_b128 v[166:169], v154 offset:1024
	ds_read_b128 v[170:173], v154 offset:2048
	ds_read_b128 v[174:177], v154 offset:3072
	v_add_u32_e32 v154, s5, v157
	ds_read_b128 v[178:181], v154
	ds_read_b128 v[182:185], v154 offset:1024
	ds_read_b128 v[186:189], v154 offset:2048
	ds_read_b128 v[190:193], v154 offset:3072
	v_lshl_add_u64 v[194:195], s[44:45], 0, v[140:141]
	s_add_i32 m0, s69, 0xc000
	ds_read_b128 v[200:203], v161
	ds_read_b128 v[204:207], v161 offset:1024
	ds_read_b128 v[208:211], v161 offset:2048
	ds_read_b128 v[212:215], v161 offset:3072
	ds_read_b128 v[216:219], v161 offset:4096
	ds_read_b128 v[220:223], v161 offset:5120
	ds_read_b128 v[224:227], v161 offset:6144
	ds_read_b128 v[228:231], v161 offset:7168
	global_load_lds_dwordx4 v[194:195], off
	v_lshl_add_u64 v[194:195], s[44:45], 0, v[138:139]
	s_add_i32 m0, s69, 0xe000
	s_nop 0
	global_load_lds_dwordx4 v[194:195], off
	s_waitcnt vmcnt(8)
	s_waitcnt lgkmcnt(0)
	s_barrier
	s_waitcnt lgkmcnt(0)
	v_mfma_f32_16x16x32_bf16 v[124:127], v[162:165], v[200:203], v[124:127]
	v_mfma_f32_16x16x32_bf16 v[120:123], v[170:173], v[200:203], v[120:123]
	v_mfma_f32_16x16x32_bf16 v[108:111], v[162:165], v[208:211], v[108:111]
	v_mfma_f32_16x16x32_bf16 v[104:107], v[170:173], v[208:211], v[104:107]
	v_mfma_f32_16x16x32_bf16 v[92:95], v[162:165], v[216:219], v[92:95]
	v_mfma_f32_16x16x32_bf16 v[88:91], v[170:173], v[216:219], v[88:91]
	v_mfma_f32_16x16x32_bf16 v[76:79], v[162:165], v[224:227], v[76:79]
	v_mfma_f32_16x16x32_bf16 v[72:75], v[170:173], v[224:227], v[72:75]
	v_mfma_f32_16x16x32_bf16 v[124:127], v[166:169], v[204:207], v[124:127]
	v_mfma_f32_16x16x32_bf16 v[120:123], v[174:177], v[204:207], v[120:123]
	v_mfma_f32_16x16x32_bf16 v[108:111], v[166:169], v[212:215], v[108:111]
	v_mfma_f32_16x16x32_bf16 v[104:107], v[174:177], v[212:215], v[104:107]
	v_mfma_f32_16x16x32_bf16 v[92:95], v[166:169], v[220:223], v[92:95]
	v_mfma_f32_16x16x32_bf16 v[88:91], v[174:177], v[220:223], v[88:91]
	v_mfma_f32_16x16x32_bf16 v[76:79], v[166:169], v[228:231], v[76:79]
	v_mfma_f32_16x16x32_bf16 v[72:75], v[174:177], v[228:231], v[72:75]
	v_mfma_f32_16x16x32_bf16 v[116:119], v[178:181], v[200:203], v[116:119]
	v_mfma_f32_16x16x32_bf16 v[112:115], v[186:189], v[200:203], v[112:115]
	v_mfma_f32_16x16x32_bf16 v[100:103], v[178:181], v[208:211], v[100:103]
	v_mfma_f32_16x16x32_bf16 v[96:99], v[186:189], v[208:211], v[96:99]
	v_mfma_f32_16x16x32_bf16 v[84:87], v[178:181], v[216:219], v[84:87]
	v_mfma_f32_16x16x32_bf16 v[80:83], v[186:189], v[216:219], v[80:83]
	v_mfma_f32_16x16x32_bf16 v[68:71], v[178:181], v[224:227], v[68:71]
	v_mfma_f32_16x16x32_bf16 v[64:67], v[186:189], v[224:227], v[64:67]
	v_mfma_f32_16x16x32_bf16 v[116:119], v[182:185], v[204:207], v[116:119]
	v_mfma_f32_16x16x32_bf16 v[112:115], v[190:193], v[204:207], v[112:115]
	v_mfma_f32_16x16x32_bf16 v[100:103], v[182:185], v[212:215], v[100:103]
	v_mfma_f32_16x16x32_bf16 v[96:99], v[190:193], v[212:215], v[96:99]
	v_mfma_f32_16x16x32_bf16 v[84:87], v[182:185], v[220:223], v[84:87]
	v_mfma_f32_16x16x32_bf16 v[80:83], v[190:193], v[220:223], v[80:83]
	v_mfma_f32_16x16x32_bf16 v[68:71], v[182:185], v[228:231], v[68:71]
	v_mfma_f32_16x16x32_bf16 v[64:67], v[190:193], v[228:231], v[64:67]
	s_barrier
	s_add_i32 s8, s10, s68
	v_lshl_add_u64 v[194:195], s[64:65], 0, v[132:133]
	s_mov_b32 m0, s8
	ds_read_b128 v[200:203], v161 offset:16384
	ds_read_b128 v[204:207], v161 offset:17408
	ds_read_b128 v[208:211], v161 offset:18432
	ds_read_b128 v[212:215], v161 offset:19456
	ds_read_b128 v[216:219], v161 offset:20480
	ds_read_b128 v[220:223], v161 offset:21504
	ds_read_b128 v[224:227], v161 offset:22528
	ds_read_b128 v[228:231], v161 offset:23552
	global_load_lds_dwordx4 v[194:195], off
	s_add_i32 m0, s8, 0x2000
	s_add_u32 s20, s64, 0x40000
	v_lshl_add_u64 v[240:241], s[64:65], 0, v[128:129]
	s_addc_u32 s21, s65, 0
	s_add_i32 s5, s5, s68
	global_load_lds_dwordx4 v[240:241], off
	v_lshl_add_u64 v[242:243], s[20:21], 0, v[132:133]
	s_mov_b32 m0, s5
	v_lshl_add_u64 v[244:245], s[66:67], 0, v[130:131]
	global_load_lds_dwordx4 v[242:243], off
	v_lshl_add_u64 v[242:243], s[20:21], 0, v[128:129]
	s_add_i32 m0, s5, 0x2000
	s_nop 0
	global_load_lds_dwordx4 v[242:243], off
	v_lshl_add_u64 v[242:243], s[66:67], 0, v[134:135]
	s_mov_b32 m0, s69
	s_nop 0
	global_load_lds_dwordx4 v[242:243], off
	s_mov_b32 m0, s70
	s_nop 0
	global_load_lds_dwordx4 v[244:245], off
	s_waitcnt vmcnt(8)
	s_waitcnt lgkmcnt(0)
	s_barrier
	s_waitcnt lgkmcnt(0)
	v_mfma_f32_16x16x32_bf16 v[60:63], v[162:165], v[200:203], v[60:63]
	v_mfma_f32_16x16x32_bf16 v[56:59], v[170:173], v[200:203], v[56:59]
	v_mfma_f32_16x16x32_bf16 v[44:47], v[162:165], v[208:211], v[44:47]
	v_mfma_f32_16x16x32_bf16 v[40:43], v[170:173], v[208:211], v[40:43]
	v_mfma_f32_16x16x32_bf16 v[28:31], v[162:165], v[216:219], v[28:31]
	v_mfma_f32_16x16x32_bf16 v[24:27], v[170:173], v[216:219], v[24:27]
	v_mfma_f32_16x16x32_bf16 v[12:15], v[162:165], v[224:227], v[12:15]
	v_mfma_f32_16x16x32_bf16 v[8:11], v[170:173], v[224:227], v[8:11]
	v_mfma_f32_16x16x32_bf16 v[60:63], v[166:169], v[204:207], v[60:63]
	v_mfma_f32_16x16x32_bf16 v[56:59], v[174:177], v[204:207], v[56:59]
	v_mfma_f32_16x16x32_bf16 v[44:47], v[166:169], v[212:215], v[44:47]
	v_mfma_f32_16x16x32_bf16 v[40:43], v[174:177], v[212:215], v[40:43]
	v_mfma_f32_16x16x32_bf16 v[28:31], v[166:169], v[220:223], v[28:31]
	v_mfma_f32_16x16x32_bf16 v[24:27], v[174:177], v[220:223], v[24:27]
	v_mfma_f32_16x16x32_bf16 v[12:15], v[166:169], v[228:231], v[12:15]
	v_mfma_f32_16x16x32_bf16 v[8:11], v[174:177], v[228:231], v[8:11]
	v_mfma_f32_16x16x32_bf16 v[52:55], v[178:181], v[200:203], v[52:55]
	v_mfma_f32_16x16x32_bf16 v[48:51], v[186:189], v[200:203], v[48:51]
	v_mfma_f32_16x16x32_bf16 v[36:39], v[178:181], v[208:211], v[36:39]
	v_mfma_f32_16x16x32_bf16 v[32:35], v[186:189], v[208:211], v[32:35]
	v_mfma_f32_16x16x32_bf16 v[20:23], v[178:181], v[216:219], v[20:23]
	v_mfma_f32_16x16x32_bf16 v[16:19], v[186:189], v[216:219], v[16:19]
	v_mfma_f32_16x16x32_bf16 v[4:7], v[178:181], v[224:227], v[4:7]
	v_mfma_f32_16x16x32_bf16 v[0:3], v[186:189], v[224:227], v[0:3]
	v_mfma_f32_16x16x32_bf16 v[52:55], v[182:185], v[204:207], v[52:55]
	v_mfma_f32_16x16x32_bf16 v[48:51], v[190:193], v[204:207], v[48:51]
	v_mfma_f32_16x16x32_bf16 v[36:39], v[182:185], v[212:215], v[36:39]
	v_mfma_f32_16x16x32_bf16 v[32:35], v[190:193], v[212:215], v[32:35]
	v_mfma_f32_16x16x32_bf16 v[20:23], v[182:185], v[220:223], v[20:23]
	v_mfma_f32_16x16x32_bf16 v[16:19], v[190:193], v[220:223], v[16:19]
	v_mfma_f32_16x16x32_bf16 v[4:7], v[182:185], v[228:231], v[4:7]
	v_mfma_f32_16x16x32_bf16 v[0:3], v[190:193], v[228:231], v[0:3]
	s_barrier
; #define PG8_STAGE(bufoff, gbase, voff) do { _Pragma("unroll") for (int _i = 0; _i < 2; ++_i) \
;         __builtin_amdgcn_global_load_lds((const unsigned*)((const char*)(gbase) + (voff)[_i]), (PG8_LAS unsigned*)(lds + (bufoff) + ldsw + _i * 8192), 16, 0, 0); } while (0)
; #define PG8_LDA(dst, b, h) do { _Pragma("unroll") for (int m = 0; m < 4; ++m) _Pragma("unroll") for (int k = 0; k < 2; ++k) dst[m][k] = *(const PG8_LAS bf16x8*)(lds + PG8_SA(b, h) + aoff + m * 2048 + k * 1024); } while (0)
; #define PG8_LDB(dst, b, h) do { _Pragma("unroll") for (int n = 0; n < 2; ++n) _Pragma("unroll") for (int k = 0; k < 2; ++k) dst[n][k] = *(const PG8_LAS bf16x8*)(lds + PG8_SB(b, h) + boff + n * 2048 + k * 1024); } while (0)
; #define PG8_MMA(ai, bj, At, Bt) do { __builtin_amdgcn_s_setprio(1); _Pragma("unroll") for (int m = 0; m < 4; ++m) _Pragma("unroll") for (int n = 0; n < 2; ++n) _Pragma("unroll") for (int k = 0; k < 2; ++k) \
;         acc[ai][bj][m][n] = __builtin_amdgcn_mfma_f32_16x16x32_bf16(Bt[n][k], At[m][k], acc[ai][bj][m][n], 0, 0, 0); __builtin_amdgcn_s_setprio(0); } while (0)
; #define PG8_WAIT_V(n) asm volatile("s_waitcnt vmcnt(" #n ")" ::: "memory")
; #define PG8_WAIT_L(n) asm volatile("s_waitcnt lgkmcnt(" #n ")" ::: "memory")
; #define PG8_BAR __builtin_amdgcn_s_barrier()
; #define PG8_SCHED __builtin_amdgcn_sched_barrier(0)
; template <class Epi, class Sched, bool ALIGN_EPI = false, bool SP2 = false>
; __device__ __forceinline__ void gemm_phase(PG8_LAS unsigned char* lds, const Gemm g, const Sched& S, const Epi& E) {
;     ...
;             PG8_LDB(B0, 1, 0); PG8_LDB(B1, 1, 1); PG8_SCHED; PG8_LDA(At, 1, 0); PG8_STAGE(PG8_SA(0, 1), a2 + hstep, voffA);
;             PG8_WAIT_V(8); PG8_WAIT_L(0); PG8_BAR; PG8_MMA(0, 0, At, B0); PG8_MMA(0, 1, At, B1); PG8_BAR; PG8_SCHED;
.Lmid_g1o:
	s_add_i32 s5, 0, 0x18000
	v_add_u32_e32 v154, s5, v157
	s_add_i32 s8, 0, 0x1c000
	ds_read_b128 v[162:165], v154
	ds_read_b128 v[166:169], v154 offset:1024
	ds_read_b128 v[170:173], v154 offset:2048
	ds_read_b128 v[174:177], v154 offset:3072
	v_add_u32_e32 v154, s8, v157
	ds_read_b128 v[178:181], v154
	ds_read_b128 v[182:185], v154 offset:1024
	ds_read_b128 v[186:189], v154 offset:2048
	ds_read_b128 v[190:193], v154 offset:3072
	s_add_u32 s20, s66, 0x40000
	s_addc_u32 s21, s67, 0
	s_mov_b32 m0, s71
	v_lshl_add_u64 v[246:247], s[20:21], 0, v[134:135]
	ds_read_b128 v[200:203], v161 offset:32768
	ds_read_b128 v[204:207], v161 offset:33792
	ds_read_b128 v[208:211], v161 offset:34816
	ds_read_b128 v[212:215], v161 offset:35840
	ds_read_b128 v[216:219], v161 offset:36864
	ds_read_b128 v[220:223], v161 offset:37888
	ds_read_b128 v[224:227], v161 offset:38912
	ds_read_b128 v[228:231], v161 offset:39936
	global_load_lds_dwordx4 v[246:247], off
	v_lshl_add_u64 v[246:247], s[20:21], 0, v[130:131]
	s_mov_b32 m0, s72
	s_nop 0
	global_load_lds_dwordx4 v[246:247], off
	s_waitcnt vmcnt(8)
	s_waitcnt lgkmcnt(0)
	s_barrier
	s_waitcnt lgkmcnt(0)
	v_mfma_f32_16x16x32_bf16 v[124:127], v[162:165], v[200:203], v[124:127]
	v_mfma_f32_16x16x32_bf16 v[120:123], v[170:173], v[200:203], v[120:123]
	v_mfma_f32_16x16x32_bf16 v[108:111], v[162:165], v[208:211], v[108:111]
	v_mfma_f32_16x16x32_bf16 v[104:107], v[170:173], v[208:211], v[104:107]
	v_mfma_f32_16x16x32_bf16 v[92:95], v[162:165], v[216:219], v[92:95]
	v_mfma_f32_16x16x32_bf16 v[88:91], v[170:173], v[216:219], v[88:91]
	v_mfma_f32_16x16x32_bf16 v[76:79], v[162:165], v[224:227], v[76:79]
	v_mfma_f32_16x16x32_bf16 v[72:75], v[170:173], v[224:227], v[72:75]
	v_mfma_f32_16x16x32_bf16 v[124:127], v[166:169], v[204:207], v[124:127]
	v_mfma_f32_16x16x32_bf16 v[120:123], v[174:177], v[204:207], v[120:123]
	v_mfma_f32_16x16x32_bf16 v[108:111], v[166:169], v[212:215], v[108:111]
	v_mfma_f32_16x16x32_bf16 v[104:107], v[174:177], v[212:215], v[104:107]
	v_mfma_f32_16x16x32_bf16 v[92:95], v[166:169], v[220:223], v[92:95]
	v_mfma_f32_16x16x32_bf16 v[88:91], v[174:177], v[220:223], v[88:91]
	v_mfma_f32_16x16x32_bf16 v[76:79], v[166:169], v[228:231], v[76:79]
	v_mfma_f32_16x16x32_bf16 v[72:75], v[174:177], v[228:231], v[72:75]
	v_mfma_f32_16x16x32_bf16 v[116:119], v[178:181], v[200:203], v[116:119]
	v_mfma_f32_16x16x32_bf16 v[112:115], v[186:189], v[200:203], v[112:115]
	v_mfma_f32_16x16x32_bf16 v[100:103], v[178:181], v[208:211], v[100:103]
	v_mfma_f32_16x16x32_bf16 v[96:99], v[186:189], v[208:211], v[96:99]
	v_mfma_f32_16x16x32_bf16 v[84:87], v[178:181], v[216:219], v[84:87]
	v_mfma_f32_16x16x32_bf16 v[80:83], v[186:189], v[216:219], v[80:83]
	v_mfma_f32_16x16x32_bf16 v[68:71], v[178:181], v[224:227], v[68:71]
	v_mfma_f32_16x16x32_bf16 v[64:67], v[186:189], v[224:227], v[64:67]
	v_mfma_f32_16x16x32_bf16 v[116:119], v[182:185], v[204:207], v[116:119]
	v_mfma_f32_16x16x32_bf16 v[112:115], v[190:193], v[204:207], v[112:115]
	v_mfma_f32_16x16x32_bf16 v[100:103], v[182:185], v[212:215], v[100:103]
	v_mfma_f32_16x16x32_bf16 v[96:99], v[190:193], v[212:215], v[96:99]
	v_mfma_f32_16x16x32_bf16 v[84:87], v[182:185], v[220:223], v[84:87]
	v_mfma_f32_16x16x32_bf16 v[80:83], v[190:193], v[220:223], v[80:83]
	v_mfma_f32_16x16x32_bf16 v[68:71], v[182:185], v[228:231], v[68:71]
	v_mfma_f32_16x16x32_bf16 v[64:67], v[190:193], v[228:231], v[64:67]
	s_barrier
; #define PG8_STAGE(bufoff, gbase, voff) do { _Pragma("unroll") for (int _i = 0; _i < 2; ++_i) \
;         __builtin_amdgcn_global_load_lds((const unsigned*)((const char*)(gbase) + (voff)[_i]), (PG8_LAS unsigned*)(lds + (bufoff) + ldsw + _i * 8192), 16, 0, 0); } while (0)
; #define PG8_LDA(dst, b, h) do { _Pragma("unroll") for (int m = 0; m < 4; ++m) _Pragma("unroll") for (int k = 0; k < 2; ++k) dst[m][k] = *(const PG8_LAS bf16x8*)(lds + PG8_SA(b, h) + aoff + m * 2048 + k * 1024); } while (0)
; #define PG8_MMA(ai, bj, At, Bt) do { __builtin_amdgcn_s_setprio(1); _Pragma("unroll") for (int m = 0; m < 4; ++m) _Pragma("unroll") for (int n = 0; n < 2; ++n) _Pragma("unroll") for (int k = 0; k < 2; ++k) \
;         acc[ai][bj][m][n] = __builtin_amdgcn_mfma_f32_16x16x32_bf16(Bt[n][k], At[m][k], acc[ai][bj][m][n], 0, 0, 0); __builtin_amdgcn_s_setprio(0); } while (0)
; #define PG8_WAIT_V(n) asm volatile("s_waitcnt vmcnt(" #n ")" ::: "memory")
; #define PG8_WAIT_L(n) asm volatile("s_waitcnt lgkmcnt(" #n ")" ::: "memory")
; #define PG8_BAR __builtin_amdgcn_s_barrier()
; #define PG8_SCHED __builtin_amdgcn_sched_barrier(0)
; template <class Epi, class Sched, bool ALIGN_EPI = false, bool SP2 = false>
; __device__ __forceinline__ void gemm_phase(PG8_LAS unsigned char* lds, const Gemm g, const Sched& S, const Epi& E) {
;     ...
;         for (int t = 0; t < nt; t += 2) {
;             const bool last = (t == nt - 2);
;             const char* a1 = cA + (size_t)(t + 1) * kstep;
;             const char* a2 = last ? nA : cA + (size_t)(t + 2) * kstep; const char* b2 = last ? nB : cB + (size_t)(t + 2) * kstep;
;     ...
;             PG8_LDA(At, 1, 1); PG8_STAGE(PG8_SB(1, 0), b3, voffB); PG8_STAGE(PG8_SB(1, 1), b3 + hstep, voffB); PG8_STAGE(PG8_SA(1, 0), a3, voffA);
;             PG8_WAIT_V(8); PG8_WAIT_L(0); PG8_BAR; PG8_MMA(1, 0, At, B0); PG8_MMA(1, 1, At, B1); PG8_BAR; PG8_SCHED;
	s_add_i32 s5, s5, s68
	v_lshl_add_u64 v[194:195], v[194:195], 0, s[22:23]
	s_mov_b32 m0, s5
	ds_read_b128 v[200:203], v161 offset:49152
	ds_read_b128 v[204:207], v161 offset:50176
	ds_read_b128 v[208:211], v161 offset:51200
	ds_read_b128 v[212:215], v161 offset:52224
	ds_read_b128 v[216:219], v161 offset:53248
	ds_read_b128 v[220:223], v161 offset:54272
	ds_read_b128 v[224:227], v161 offset:55296
	ds_read_b128 v[228:231], v161 offset:56320
	global_load_lds_dwordx4 v[194:195], off
	s_add_i32 m0, s5, 0x2000
	s_add_u32 s20, s64, 0x40080
	v_lshl_add_u64 v[194:195], v[240:241], 0, s[22:23]
	s_addc_u32 s21, s65, 0
	s_add_i32 s5, s8, s68
	global_load_lds_dwordx4 v[194:195], off
	v_lshl_add_u64 v[194:195], s[20:21], 0, v[132:133]
	s_mov_b32 m0, s5
	s_nop 0
	global_load_lds_dwordx4 v[194:195], off
	v_lshl_add_u64 v[194:195], s[20:21], 0, v[128:129]
	s_add_i32 m0, s5, 0x2000
	s_nop 0
	global_load_lds_dwordx4 v[194:195], off
	v_lshl_add_u64 v[194:195], v[242:243], 0, s[22:23]
	s_mov_b32 m0, s73
	s_nop 0
	global_load_lds_dwordx4 v[194:195], off
	v_lshl_add_u64 v[194:195], v[244:245], 0, s[22:23]
	s_mov_b32 m0, s74
	s_nop 0
	global_load_lds_dwordx4 v[194:195], off
	s_waitcnt vmcnt(8)
	s_waitcnt lgkmcnt(0)
	s_barrier
	s_waitcnt lgkmcnt(0)
	v_mfma_f32_16x16x32_bf16 v[60:63], v[162:165], v[200:203], v[60:63]
	v_mfma_f32_16x16x32_bf16 v[56:59], v[170:173], v[200:203], v[56:59]
	v_mfma_f32_16x16x32_bf16 v[44:47], v[162:165], v[208:211], v[44:47]
	v_mfma_f32_16x16x32_bf16 v[40:43], v[170:173], v[208:211], v[40:43]
	v_mfma_f32_16x16x32_bf16 v[28:31], v[162:165], v[216:219], v[28:31]
	v_mfma_f32_16x16x32_bf16 v[24:27], v[170:173], v[216:219], v[24:27]
	v_mfma_f32_16x16x32_bf16 v[12:15], v[162:165], v[224:227], v[12:15]
	v_mfma_f32_16x16x32_bf16 v[8:11], v[170:173], v[224:227], v[8:11]
	v_mfma_f32_16x16x32_bf16 v[60:63], v[166:169], v[204:207], v[60:63]
	v_mfma_f32_16x16x32_bf16 v[56:59], v[174:177], v[204:207], v[56:59]
	v_mfma_f32_16x16x32_bf16 v[44:47], v[166:169], v[212:215], v[44:47]
	v_mfma_f32_16x16x32_bf16 v[40:43], v[174:177], v[212:215], v[40:43]
	v_mfma_f32_16x16x32_bf16 v[28:31], v[166:169], v[220:223], v[28:31]
	v_mfma_f32_16x16x32_bf16 v[24:27], v[174:177], v[220:223], v[24:27]
	v_mfma_f32_16x16x32_bf16 v[12:15], v[166:169], v[228:231], v[12:15]
	v_mfma_f32_16x16x32_bf16 v[8:11], v[174:177], v[228:231], v[8:11]
	v_mfma_f32_16x16x32_bf16 v[52:55], v[178:181], v[200:203], v[52:55]
	v_mfma_f32_16x16x32_bf16 v[48:51], v[186:189], v[200:203], v[48:51]
	v_mfma_f32_16x16x32_bf16 v[36:39], v[178:181], v[208:211], v[36:39]
	v_mfma_f32_16x16x32_bf16 v[32:35], v[186:189], v[208:211], v[32:35]
	v_mfma_f32_16x16x32_bf16 v[20:23], v[178:181], v[216:219], v[20:23]
	v_mfma_f32_16x16x32_bf16 v[16:19], v[186:189], v[216:219], v[16:19]
	v_mfma_f32_16x16x32_bf16 v[4:7], v[178:181], v[224:227], v[4:7]
	v_mfma_f32_16x16x32_bf16 v[0:3], v[186:189], v[224:227], v[0:3]
	v_mfma_f32_16x16x32_bf16 v[52:55], v[182:185], v[204:207], v[52:55]
	v_mfma_f32_16x16x32_bf16 v[48:51], v[190:193], v[204:207], v[48:51]
	v_mfma_f32_16x16x32_bf16 v[36:39], v[182:185], v[212:215], v[36:39]
	v_mfma_f32_16x16x32_bf16 v[32:35], v[190:193], v[212:215], v[32:35]
	v_mfma_f32_16x16x32_bf16 v[20:23], v[182:185], v[220:223], v[20:23]
	v_mfma_f32_16x16x32_bf16 v[16:19], v[190:193], v[220:223], v[16:19]
	v_mfma_f32_16x16x32_bf16 v[4:7], v[182:185], v[228:231], v[4:7]
	v_mfma_f32_16x16x32_bf16 v[0:3], v[190:193], v[228:231], v[0:3]
	s_barrier
	s_add_i32 s76, s76, 2
	s_add_u32 s57, s57, 0x100
	s_addc_u32 s59, s59, 0
	s_add_u32 s44, s44, 0x100
	s_addc_u32 s45, s45, 0
	s_cmp_gt_u32 s76, 13
	s_cbranch_scc0 .LBB0_54
	s_and_b64 vcc, exec, s[54:55]
	s_cbranch_vccz .LBB0_57
	s_barrier

; #define PG8_STAGE(bufoff, gbase, voff) do { _Pragma("unroll") for (int _i = 0; _i < 2; ++_i) \
;         __builtin_amdgcn_global_load_lds((const unsigned*)((const char*)(gbase) + (voff)[_i]), (PG8_LAS unsigned*)(lds + (bufoff) + ldsw + _i * 8192), 16, 0, 0); } while (0)
; #define PG8_LDA(dst, b, h) do { _Pragma("unroll") for (int m = 0; m < 4; ++m) _Pragma("unroll") for (int k = 0; k < 2; ++k) dst[m][k] = *(const PG8_LAS bf16x8*)(lds + PG8_SA(b, h) + aoff + m * 2048 + k * 1024); } while (0)
; #define PG8_LDB(dst, b, h) do { _Pragma("unroll") for (int n = 0; n < 2; ++n) _Pragma("unroll") for (int k = 0; k < 2; ++k) dst[n][k] = *(const PG8_LAS bf16x8*)(lds + PG8_SB(b, h) + boff + n * 2048 + k * 1024); } while (0)
; #define PG8_MMA(ai, bj, At, Bt) do { __builtin_amdgcn_s_setprio(1); _Pragma("unroll") for (int m = 0; m < 4; ++m) _Pragma("unroll") for (int n = 0; n < 2; ++n) _Pragma("unroll") for (int k = 0; k < 2; ++k) \
;         acc[ai][bj][m][n] = __builtin_amdgcn_mfma_f32_16x16x32_bf16(Bt[n][k], At[m][k], acc[ai][bj][m][n], 0, 0, 0); __builtin_amdgcn_s_setprio(0); } while (0)
; #define PG8_WAIT_V(n) asm volatile("s_waitcnt vmcnt(" #n ")" ::: "memory")
; #define PG8_BAR __builtin_amdgcn_s_barrier()
; template <class Epi, class Sched, bool ALIGN_EPI = false, bool SP2 = false>
; __device__ __forceinline__ void gemm_phase(PG8_LAS unsigned char* lds, const Gemm g, const Sched& S, const Epi& E) {
;     ...
;         for (int t = 0; t < nt; t += 2) {
;             const bool last = (t == nt - 2);
;             const char* a1 = cA + (size_t)(t + 1) * kstep;
;             const char* a2 = last ? nA : cA + (size_t)(t + 2) * kstep; const char* b2 = last ? nB : cB + (size_t)(t + 2) * kstep;
;             const char* a3 = a2 + kstep; const char* b3 = b2 + kstep;
;             if (last && has_next) S.a_ready(nxt);
;             if constexpr (SP2) {
;             PG8_LDB(B0, 0, 0); PG8_LDB(B1, 0, 1); PG8_SCHED; PG8_LDA(At, 0, 0); PG8_STAGE(PG8_SA(1, 1), a1 + hstep, voffA);
;             PG8_WAIT_V(8); PG8_WAIT_L(0); PG8_BAR; PG8_MMA(0, 0, At, B0); PG8_MMA(0, 1, At, B1); PG8_BAR; PG8_SCHED;
;             PG8_LDA(At, 0, 1); PG8_STAGE(PG8_SB(0, 0), b2, voffB); PG8_STAGE(PG8_SB(0, 1), b2 + hstep, voffB); PG8_STAGE(PG8_SA(0, 0), a2, voffA);
;             PG8_WAIT_V(8); PG8_WAIT_L(0); PG8_BAR; PG8_MMA(1, 0, At, B0); PG8_MMA(1, 1, At, B1); PG8_BAR; PG8_SCHED;
.Lpeel_g4:
	s_add_u32 s60, s58, 0x100
	s_addc_u32 s61, s59, 0
	s_add_i32 s5, 0, 0x10000
	s_cmp_eq_u32 s39, 40
	s_cselect_b32 s65, s1, s61
	s_cselect_b32 s64, s0, s60
	s_cselect_b32 s63, s57, s27
	s_cselect_b32 s62, s56, s26
	s_add_i32 s8, 0, 0x14000
	v_add_u32_e32 v124, s5, v240
	v_add_u32_e32 v156, s8, v240
	ds_read_b128 v[112:115], v124
	ds_read_b128 v[116:119], v124 offset:1024
	ds_read_b128 v[120:123], v124 offset:2048
	ds_read_b128 v[124:127], v124 offset:3072
	ds_read_b128 v[132:135], v156
	ds_read_b128 v[140:143], v156 offset:1024
	ds_read_b128 v[152:155], v156 offset:2048
	ds_read_b128 v[156:159], v156 offset:3072
	v_lshl_add_u64 v[214:215], s[58:59], 0, v[208:209]
	s_add_i32 m0, s67, 0xc000
	ds_read_b128 v[164:167], v242
	ds_read_b128 v[172:175], v242 offset:1024
	ds_read_b128 v[176:179], v242 offset:2048
	ds_read_b128 v[180:183], v242 offset:3072
	ds_read_b128 v[184:187], v242 offset:4096
	ds_read_b128 v[188:191], v242 offset:5120
	ds_read_b128 v[192:195], v242 offset:6144
	ds_read_b128 v[210:213], v242 offset:7168
	global_load_lds_dwordx4 v[214:215], off
	v_lshl_add_u64 v[214:215], s[58:59], 0, v[206:207]
	s_add_i32 m0, s67, 0xe000
	s_nop 0
	global_load_lds_dwordx4 v[214:215], off
	s_waitcnt vmcnt(8)
	s_waitcnt lgkmcnt(0)
	s_barrier
	s_waitcnt lgkmcnt(0)
	v_mfma_f32_16x16x32_bf16 v[168:171], v[112:115], v[164:167], 0
	v_mfma_f32_16x16x32_bf16 v[160:163], v[120:123], v[164:167], 0
	v_mfma_f32_16x16x32_bf16 v[108:111], v[112:115], v[176:179], 0
	v_mfma_f32_16x16x32_bf16 v[104:107], v[120:123], v[176:179], 0
	v_mfma_f32_16x16x32_bf16 v[92:95], v[112:115], v[184:187], 0
	v_mfma_f32_16x16x32_bf16 v[88:91], v[120:123], v[184:187], 0
	v_mfma_f32_16x16x32_bf16 v[76:79], v[112:115], v[192:195], 0
	v_mfma_f32_16x16x32_bf16 v[72:75], v[120:123], v[192:195], 0
	v_mfma_f32_16x16x32_bf16 v[168:171], v[116:119], v[172:175], v[168:171]
	v_mfma_f32_16x16x32_bf16 v[160:163], v[124:127], v[172:175], v[160:163]
	v_mfma_f32_16x16x32_bf16 v[108:111], v[116:119], v[180:183], v[108:111]
	v_mfma_f32_16x16x32_bf16 v[104:107], v[124:127], v[180:183], v[104:107]
	v_mfma_f32_16x16x32_bf16 v[92:95], v[116:119], v[188:191], v[92:95]
	v_mfma_f32_16x16x32_bf16 v[88:91], v[124:127], v[188:191], v[88:91]
	v_mfma_f32_16x16x32_bf16 v[76:79], v[116:119], v[210:213], v[76:79]
	v_mfma_f32_16x16x32_bf16 v[72:75], v[124:127], v[210:213], v[72:75]
	v_mfma_f32_16x16x32_bf16 v[136:139], v[132:135], v[164:167], 0
	v_mfma_f32_16x16x32_bf16 v[128:131], v[152:155], v[164:167], 0
	v_mfma_f32_16x16x32_bf16 v[100:103], v[132:135], v[176:179], 0
	v_mfma_f32_16x16x32_bf16 v[96:99], v[152:155], v[176:179], 0
	v_mfma_f32_16x16x32_bf16 v[84:87], v[132:135], v[184:187], 0
	v_mfma_f32_16x16x32_bf16 v[80:83], v[152:155], v[184:187], 0
	v_mfma_f32_16x16x32_bf16 v[68:71], v[132:135], v[192:195], 0
	v_mfma_f32_16x16x32_bf16 v[64:67], v[152:155], v[192:195], 0
	v_mfma_f32_16x16x32_bf16 v[136:139], v[140:143], v[172:175], v[136:139]
	v_mfma_f32_16x16x32_bf16 v[128:131], v[156:159], v[172:175], v[128:131]
	v_mfma_f32_16x16x32_bf16 v[100:103], v[140:143], v[180:183], v[100:103]
	v_mfma_f32_16x16x32_bf16 v[96:99], v[156:159], v[180:183], v[96:99]
	v_mfma_f32_16x16x32_bf16 v[84:87], v[140:143], v[188:191], v[84:87]
	v_mfma_f32_16x16x32_bf16 v[80:83], v[156:159], v[188:191], v[80:83]
	v_mfma_f32_16x16x32_bf16 v[68:71], v[140:143], v[210:213], v[68:71]
	v_mfma_f32_16x16x32_bf16 v[64:67], v[156:159], v[210:213], v[64:67]
	s_barrier
	s_add_i32 s5, s5, s66
	v_lshl_add_u64 v[214:215], s[62:63], 0, v[202:203]
	s_mov_b32 m0, s5
	ds_read_b128 v[164:167], v242 offset:16384
	ds_read_b128 v[172:175], v242 offset:17408
	ds_read_b128 v[176:179], v242 offset:18432
	ds_read_b128 v[180:183], v242 offset:19456
	ds_read_b128 v[184:187], v242 offset:20480
	ds_read_b128 v[188:191], v242 offset:21504
	ds_read_b128 v[192:195], v242 offset:22528
	ds_read_b128 v[210:213], v242 offset:23552
	global_load_lds_dwordx4 v[214:215], off
	s_add_i32 m0, s5, 0x2000
	s_add_u32 s20, s62, 0xb0000
	v_lshl_add_u64 v[216:217], s[62:63], 0, v[146:147]
	s_addc_u32 s21, s63, 0
	s_add_i32 s5, s8, s66
	global_load_lds_dwordx4 v[216:217], off
	v_lshl_add_u64 v[218:219], s[20:21], 0, v[202:203]
	s_mov_b32 m0, s5
	v_lshl_add_u64 v[220:221], s[64:65], 0, v[200:201]
	global_load_lds_dwordx4 v[218:219], off
	v_lshl_add_u64 v[218:219], s[20:21], 0, v[146:147]
	s_add_i32 m0, s5, 0x2000
	s_nop 0
	global_load_lds_dwordx4 v[218:219], off
	v_lshl_add_u64 v[218:219], s[64:65], 0, v[204:205]
	s_mov_b32 m0, s67
	s_nop 0
	global_load_lds_dwordx4 v[218:219], off
	s_mov_b32 m0, s68
	s_nop 0
	global_load_lds_dwordx4 v[220:221], off
	s_waitcnt vmcnt(8)
	s_waitcnt lgkmcnt(0)
	s_barrier
	s_waitcnt lgkmcnt(0)
	v_mfma_f32_16x16x32_bf16 v[60:63], v[112:115], v[164:167], 0
	v_mfma_f32_16x16x32_bf16 v[56:59], v[120:123], v[164:167], 0
	v_mfma_f32_16x16x32_bf16 v[44:47], v[112:115], v[176:179], 0
	v_mfma_f32_16x16x32_bf16 v[40:43], v[120:123], v[176:179], 0
	v_mfma_f32_16x16x32_bf16 v[28:31], v[112:115], v[184:187], 0
	v_mfma_f32_16x16x32_bf16 v[24:27], v[120:123], v[184:187], 0
	v_mfma_f32_16x16x32_bf16 v[12:15], v[112:115], v[192:195], 0
	v_mfma_f32_16x16x32_bf16 v[8:11], v[120:123], v[192:195], 0
	v_mfma_f32_16x16x32_bf16 v[60:63], v[116:119], v[172:175], v[60:63]
	v_mfma_f32_16x16x32_bf16 v[56:59], v[124:127], v[172:175], v[56:59]
	v_mfma_f32_16x16x32_bf16 v[44:47], v[116:119], v[180:183], v[44:47]
	v_mfma_f32_16x16x32_bf16 v[40:43], v[124:127], v[180:183], v[40:43]
	v_mfma_f32_16x16x32_bf16 v[28:31], v[116:119], v[188:191], v[28:31]
	v_mfma_f32_16x16x32_bf16 v[24:27], v[124:127], v[188:191], v[24:27]
	v_mfma_f32_16x16x32_bf16 v[12:15], v[116:119], v[210:213], v[12:15]
	v_mfma_f32_16x16x32_bf16 v[8:11], v[124:127], v[210:213], v[8:11]
	v_mfma_f32_16x16x32_bf16 v[52:55], v[132:135], v[164:167], 0
	v_mfma_f32_16x16x32_bf16 v[48:51], v[152:155], v[164:167], 0
	v_mfma_f32_16x16x32_bf16 v[36:39], v[132:135], v[176:179], 0
	v_mfma_f32_16x16x32_bf16 v[32:35], v[152:155], v[176:179], 0
	v_mfma_f32_16x16x32_bf16 v[20:23], v[132:135], v[184:187], 0
	v_mfma_f32_16x16x32_bf16 v[16:19], v[152:155], v[184:187], 0
	v_mfma_f32_16x16x32_bf16 v[4:7], v[132:135], v[192:195], 0
	v_mfma_f32_16x16x32_bf16 v[0:3], v[152:155], v[192:195], 0
	v_mfma_f32_16x16x32_bf16 v[52:55], v[140:143], v[172:175], v[52:55]
	v_mfma_f32_16x16x32_bf16 v[48:51], v[156:159], v[172:175], v[48:51]
	v_mfma_f32_16x16x32_bf16 v[36:39], v[140:143], v[180:183], v[36:39]
	v_mfma_f32_16x16x32_bf16 v[32:35], v[156:159], v[180:183], v[32:35]
	v_mfma_f32_16x16x32_bf16 v[20:23], v[140:143], v[188:191], v[20:23]
	v_mfma_f32_16x16x32_bf16 v[16:19], v[156:159], v[188:191], v[16:19]
	v_mfma_f32_16x16x32_bf16 v[4:7], v[140:143], v[210:213], v[4:7]
	v_mfma_f32_16x16x32_bf16 v[0:3], v[156:159], v[210:213], v[0:3]
	s_barrier
	s_branch .Lmid_g4

; #define PG8_STAGE(bufoff, gbase, voff) do { _Pragma("unroll") for (int _i = 0; _i < 2; ++_i) \
;         __builtin_amdgcn_global_load_lds((const unsigned*)((const char*)(gbase) + (voff)[_i]), (PG8_LAS unsigned*)(lds + (bufoff) + ldsw + _i * 8192), 16, 0, 0); } while (0)
; #define PG8_LDA(dst, b, h) do { _Pragma("unroll") for (int m = 0; m < 4; ++m) _Pragma("unroll") for (int k = 0; k < 2; ++k) dst[m][k] = *(const PG8_LAS bf16x8*)(lds + PG8_SA(b, h) + aoff + m * 2048 + k * 1024); } while (0)
; #define PG8_LDB(dst, b, h) do { _Pragma("unroll") for (int n = 0; n < 2; ++n) _Pragma("unroll") for (int k = 0; k < 2; ++k) dst[n][k] = *(const PG8_LAS bf16x8*)(lds + PG8_SB(b, h) + boff + n * 2048 + k * 1024); } while (0)
; #define PG8_MMA(ai, bj, At, Bt) do { __builtin_amdgcn_s_setprio(1); _Pragma("unroll") for (int m = 0; m < 4; ++m) _Pragma("unroll") for (int n = 0; n < 2; ++n) _Pragma("unroll") for (int k = 0; k < 2; ++k) \
;         acc[ai][bj][m][n] = __builtin_amdgcn_mfma_f32_16x16x32_bf16(Bt[n][k], At[m][k], acc[ai][bj][m][n], 0, 0, 0); __builtin_amdgcn_s_setprio(0); } while (0)
; #define PG8_WAIT_V(n) asm volatile("s_waitcnt vmcnt(" #n ")" ::: "memory")
; #define PG8_BAR __builtin_amdgcn_s_barrier()
; template <class Epi, class Sched, bool ALIGN_EPI = false, bool SP2 = false>
; __device__ __forceinline__ void gemm_phase(PG8_LAS unsigned char* lds, const Gemm g, const Sched& S, const Epi& E) {
;     ...
;         for (int t = 0; t < nt; t += 2) {
;             const bool last = (t == nt - 2);
;             const char* a1 = cA + (size_t)(t + 1) * kstep;
;             const char* a2 = last ? nA : cA + (size_t)(t + 2) * kstep; const char* b2 = last ? nB : cB + (size_t)(t + 2) * kstep;
;             const char* a3 = a2 + kstep; const char* b3 = b2 + kstep;
;             if (last && has_next) S.a_ready(nxt);
;             if constexpr (SP2) {
;             PG8_LDB(B0, 0, 0); PG8_LDB(B1, 0, 1); PG8_SCHED; PG8_LDA(At, 0, 0); PG8_STAGE(PG8_SA(1, 1), a1 + hstep, voffA);
;             PG8_WAIT_V(8); PG8_WAIT_L(0); PG8_BAR; PG8_MMA(0, 0, At, B0); PG8_MMA(0, 1, At, B1); PG8_BAR; PG8_SCHED;
;             PG8_LDA(At, 0, 1); PG8_STAGE(PG8_SB(0, 0), b2, voffB); PG8_STAGE(PG8_SB(0, 1), b2 + hstep, voffB); PG8_STAGE(PG8_SA(0, 0), a2, voffA);
;             PG8_WAIT_V(8); PG8_WAIT_L(0); PG8_BAR; PG8_MMA(1, 0, At, B0); PG8_MMA(1, 1, At, B1); PG8_BAR; PG8_SCHED;
.LBB0_112:
	s_add_u32 s60, s58, 0x100
	s_addc_u32 s61, s59, 0
	s_add_i32 s5, 0, 0x10000
	s_cmp_eq_u32 s39, 40
	s_cselect_b32 s65, s1, s61
	s_cselect_b32 s64, s0, s60
	s_cselect_b32 s63, s57, s27
	s_cselect_b32 s62, s56, s26
	s_add_i32 s8, 0, 0x14000
	v_add_u32_e32 v124, s5, v240
	v_add_u32_e32 v156, s8, v240
	ds_read_b128 v[112:115], v124
	ds_read_b128 v[116:119], v124 offset:1024
	ds_read_b128 v[120:123], v124 offset:2048
	ds_read_b128 v[124:127], v124 offset:3072
	ds_read_b128 v[132:135], v156
	ds_read_b128 v[140:143], v156 offset:1024
	ds_read_b128 v[152:155], v156 offset:2048
	ds_read_b128 v[156:159], v156 offset:3072
	v_lshl_add_u64 v[214:215], s[58:59], 0, v[208:209]
	s_add_i32 m0, s67, 0xc000
	ds_read_b128 v[164:167], v242
	ds_read_b128 v[172:175], v242 offset:1024
	ds_read_b128 v[176:179], v242 offset:2048
	ds_read_b128 v[180:183], v242 offset:3072
	ds_read_b128 v[184:187], v242 offset:4096
	ds_read_b128 v[188:191], v242 offset:5120
	ds_read_b128 v[192:195], v242 offset:6144
	ds_read_b128 v[210:213], v242 offset:7168
	global_load_lds_dwordx4 v[214:215], off
	v_lshl_add_u64 v[214:215], s[58:59], 0, v[206:207]
	s_add_i32 m0, s67, 0xe000
	s_nop 0
	global_load_lds_dwordx4 v[214:215], off
	s_waitcnt vmcnt(8)
	s_waitcnt lgkmcnt(0)
	s_barrier
	s_waitcnt lgkmcnt(0)
	v_mfma_f32_16x16x32_bf16 v[168:171], v[112:115], v[164:167], v[168:171]
	v_mfma_f32_16x16x32_bf16 v[160:163], v[120:123], v[164:167], v[160:163]
	v_mfma_f32_16x16x32_bf16 v[108:111], v[112:115], v[176:179], v[108:111]
	v_mfma_f32_16x16x32_bf16 v[104:107], v[120:123], v[176:179], v[104:107]
	v_mfma_f32_16x16x32_bf16 v[92:95], v[112:115], v[184:187], v[92:95]
	v_mfma_f32_16x16x32_bf16 v[88:91], v[120:123], v[184:187], v[88:91]
	v_mfma_f32_16x16x32_bf16 v[76:79], v[112:115], v[192:195], v[76:79]
	v_mfma_f32_16x16x32_bf16 v[72:75], v[120:123], v[192:195], v[72:75]
	v_mfma_f32_16x16x32_bf16 v[168:171], v[116:119], v[172:175], v[168:171]
	v_mfma_f32_16x16x32_bf16 v[160:163], v[124:127], v[172:175], v[160:163]
	v_mfma_f32_16x16x32_bf16 v[108:111], v[116:119], v[180:183], v[108:111]
	v_mfma_f32_16x16x32_bf16 v[104:107], v[124:127], v[180:183], v[104:107]
	v_mfma_f32_16x16x32_bf16 v[92:95], v[116:119], v[188:191], v[92:95]
	v_mfma_f32_16x16x32_bf16 v[88:91], v[124:127], v[188:191], v[88:91]
	v_mfma_f32_16x16x32_bf16 v[76:79], v[116:119], v[210:213], v[76:79]
	v_mfma_f32_16x16x32_bf16 v[72:75], v[124:127], v[210:213], v[72:75]
	v_mfma_f32_16x16x32_bf16 v[136:139], v[132:135], v[164:167], v[136:139]
	v_mfma_f32_16x16x32_bf16 v[128:131], v[152:155], v[164:167], v[128:131]
	v_mfma_f32_16x16x32_bf16 v[100:103], v[132:135], v[176:179], v[100:103]
	v_mfma_f32_16x16x32_bf16 v[96:99], v[152:155], v[176:179], v[96:99]
	v_mfma_f32_16x16x32_bf16 v[84:87], v[132:135], v[184:187], v[84:87]
	v_mfma_f32_16x16x32_bf16 v[80:83], v[152:155], v[184:187], v[80:83]
	v_mfma_f32_16x16x32_bf16 v[68:71], v[132:135], v[192:195], v[68:71]
	v_mfma_f32_16x16x32_bf16 v[64:67], v[152:155], v[192:195], v[64:67]
	v_mfma_f32_16x16x32_bf16 v[136:139], v[140:143], v[172:175], v[136:139]
	v_mfma_f32_16x16x32_bf16 v[128:131], v[156:159], v[172:175], v[128:131]
	v_mfma_f32_16x16x32_bf16 v[100:103], v[140:143], v[180:183], v[100:103]
	v_mfma_f32_16x16x32_bf16 v[96:99], v[156:159], v[180:183], v[96:99]
	v_mfma_f32_16x16x32_bf16 v[84:87], v[140:143], v[188:191], v[84:87]
	v_mfma_f32_16x16x32_bf16 v[80:83], v[156:159], v[188:191], v[80:83]
	v_mfma_f32_16x16x32_bf16 v[68:71], v[140:143], v[210:213], v[68:71]
	v_mfma_f32_16x16x32_bf16 v[64:67], v[156:159], v[210:213], v[64:67]
	s_barrier
	s_add_i32 s5, s5, s66
	v_lshl_add_u64 v[214:215], s[62:63], 0, v[202:203]
	s_mov_b32 m0, s5
	ds_read_b128 v[164:167], v242 offset:16384
	ds_read_b128 v[172:175], v242 offset:17408
	ds_read_b128 v[176:179], v242 offset:18432
	ds_read_b128 v[180:183], v242 offset:19456
	ds_read_b128 v[184:187], v242 offset:20480
	ds_read_b128 v[188:191], v242 offset:21504
	ds_read_b128 v[192:195], v242 offset:22528
	ds_read_b128 v[210:213], v242 offset:23552
	global_load_lds_dwordx4 v[214:215], off
	s_add_i32 m0, s5, 0x2000
	s_add_u32 s20, s62, 0xb0000
	v_lshl_add_u64 v[216:217], s[62:63], 0, v[146:147]
	s_addc_u32 s21, s63, 0
	s_add_i32 s5, s8, s66
	global_load_lds_dwordx4 v[216:217], off
	v_lshl_add_u64 v[218:219], s[20:21], 0, v[202:203]
	s_mov_b32 m0, s5
	v_lshl_add_u64 v[220:221], s[64:65], 0, v[200:201]
	global_load_lds_dwordx4 v[218:219], off
	v_lshl_add_u64 v[218:219], s[20:21], 0, v[146:147]
	s_add_i32 m0, s5, 0x2000
	s_nop 0
	global_load_lds_dwordx4 v[218:219], off
	v_lshl_add_u64 v[218:219], s[64:65], 0, v[204:205]
	s_mov_b32 m0, s67
	s_nop 0
	global_load_lds_dwordx4 v[218:219], off
	s_mov_b32 m0, s68
	s_nop 0
	global_load_lds_dwordx4 v[220:221], off
	s_waitcnt vmcnt(8)
	s_waitcnt lgkmcnt(0)
	s_barrier
	s_waitcnt lgkmcnt(0)
	v_mfma_f32_16x16x32_bf16 v[60:63], v[112:115], v[164:167], v[60:63]
	v_mfma_f32_16x16x32_bf16 v[56:59], v[120:123], v[164:167], v[56:59]
	v_mfma_f32_16x16x32_bf16 v[44:47], v[112:115], v[176:179], v[44:47]
	v_mfma_f32_16x16x32_bf16 v[40:43], v[120:123], v[176:179], v[40:43]
	v_mfma_f32_16x16x32_bf16 v[28:31], v[112:115], v[184:187], v[28:31]
	v_mfma_f32_16x16x32_bf16 v[24:27], v[120:123], v[184:187], v[24:27]
	v_mfma_f32_16x16x32_bf16 v[12:15], v[112:115], v[192:195], v[12:15]
	v_mfma_f32_16x16x32_bf16 v[8:11], v[120:123], v[192:195], v[8:11]
	v_mfma_f32_16x16x32_bf16 v[60:63], v[116:119], v[172:175], v[60:63]
	v_mfma_f32_16x16x32_bf16 v[56:59], v[124:127], v[172:175], v[56:59]
	v_mfma_f32_16x16x32_bf16 v[44:47], v[116:119], v[180:183], v[44:47]
	v_mfma_f32_16x16x32_bf16 v[40:43], v[124:127], v[180:183], v[40:43]
	v_mfma_f32_16x16x32_bf16 v[28:31], v[116:119], v[188:191], v[28:31]
	v_mfma_f32_16x16x32_bf16 v[24:27], v[124:127], v[188:191], v[24:27]
	v_mfma_f32_16x16x32_bf16 v[12:15], v[116:119], v[210:213], v[12:15]
	v_mfma_f32_16x16x32_bf16 v[8:11], v[124:127], v[210:213], v[8:11]
	v_mfma_f32_16x16x32_bf16 v[52:55], v[132:135], v[164:167], v[52:55]
	v_mfma_f32_16x16x32_bf16 v[48:51], v[152:155], v[164:167], v[48:51]
	v_mfma_f32_16x16x32_bf16 v[36:39], v[132:135], v[176:179], v[36:39]
	v_mfma_f32_16x16x32_bf16 v[32:35], v[152:155], v[176:179], v[32:35]
	v_mfma_f32_16x16x32_bf16 v[20:23], v[132:135], v[184:187], v[20:23]
	v_mfma_f32_16x16x32_bf16 v[16:19], v[152:155], v[184:187], v[16:19]
	v_mfma_f32_16x16x32_bf16 v[4:7], v[132:135], v[192:195], v[4:7]
	v_mfma_f32_16x16x32_bf16 v[0:3], v[152:155], v[192:195], v[0:3]
	v_mfma_f32_16x16x32_bf16 v[52:55], v[140:143], v[172:175], v[52:55]
	v_mfma_f32_16x16x32_bf16 v[48:51], v[156:159], v[172:175], v[48:51]
	v_mfma_f32_16x16x32_bf16 v[36:39], v[140:143], v[180:183], v[36:39]
	v_mfma_f32_16x16x32_bf16 v[32:35], v[156:159], v[180:183], v[32:35]
	v_mfma_f32_16x16x32_bf16 v[20:23], v[140:143], v[188:191], v[20:23]
	v_mfma_f32_16x16x32_bf16 v[16:19], v[156:159], v[188:191], v[16:19]
	v_mfma_f32_16x16x32_bf16 v[4:7], v[140:143], v[210:213], v[4:7]
	v_mfma_f32_16x16x32_bf16 v[0:3], v[156:159], v[210:213], v[0:3]
	s_barrier
; #define PG8_STAGE(bufoff, gbase, voff) do { _Pragma("unroll") for (int _i = 0; _i < 2; ++_i) \
;         __builtin_amdgcn_global_load_lds((const unsigned*)((const char*)(gbase) + (voff)[_i]), (PG8_LAS unsigned*)(lds + (bufoff) + ldsw + _i * 8192), 16, 0, 0); } while (0)
; #define PG8_LDA(dst, b, h) do { _Pragma("unroll") for (int m = 0; m < 4; ++m) _Pragma("unroll") for (int k = 0; k < 2; ++k) dst[m][k] = *(const PG8_LAS bf16x8*)(lds + PG8_SA(b, h) + aoff + m * 2048 + k * 1024); } while (0)
; #define PG8_LDB(dst, b, h) do { _Pragma("unroll") for (int n = 0; n < 2; ++n) _Pragma("unroll") for (int k = 0; k < 2; ++k) dst[n][k] = *(const PG8_LAS bf16x8*)(lds + PG8_SB(b, h) + boff + n * 2048 + k * 1024); } while (0)
; #define PG8_MMA(ai, bj, At, Bt) do { __builtin_amdgcn_s_setprio(1); _Pragma("unroll") for (int m = 0; m < 4; ++m) _Pragma("unroll") for (int n = 0; n < 2; ++n) _Pragma("unroll") for (int k = 0; k < 2; ++k) \
;         acc[ai][bj][m][n] = __builtin_amdgcn_mfma_f32_16x16x32_bf16(Bt[n][k], At[m][k], acc[ai][bj][m][n], 0, 0, 0); __builtin_amdgcn_s_setprio(0); } while (0)
; #define PG8_WAIT_V(n) asm volatile("s_waitcnt vmcnt(" #n ")" ::: "memory")
; #define PG8_WAIT_L(n) asm volatile("s_waitcnt lgkmcnt(" #n ")" ::: "memory")
; #define PG8_BAR __builtin_amdgcn_s_barrier()
; #define PG8_SCHED __builtin_amdgcn_sched_barrier(0)
; template <class Epi, class Sched, bool ALIGN_EPI = false, bool SP2 = false>
; __device__ __forceinline__ void gemm_phase(PG8_LAS unsigned char* lds, const Gemm g, const Sched& S, const Epi& E) {
;     ...
;             PG8_LDB(B0, 1, 0); PG8_LDB(B1, 1, 1); PG8_SCHED; PG8_LDA(At, 1, 0); PG8_STAGE(PG8_SA(0, 1), a2 + hstep, voffA);
;             PG8_WAIT_V(8); PG8_WAIT_L(0); PG8_BAR; PG8_MMA(0, 0, At, B0); PG8_MMA(0, 1, At, B1); PG8_BAR; PG8_SCHED;
.Lmid_g4:
	s_add_i32 s5, 0, 0x18000
	s_add_i32 s8, 0, 0x1c000
	v_add_u32_e32 v124, s5, v240
	v_add_u32_e32 v156, s8, v240
	ds_read_b128 v[112:115], v124
	ds_read_b128 v[116:119], v124 offset:1024
	ds_read_b128 v[120:123], v124 offset:2048
	ds_read_b128 v[124:127], v124 offset:3072
	ds_read_b128 v[132:135], v156
	ds_read_b128 v[140:143], v156 offset:1024
	ds_read_b128 v[152:155], v156 offset:2048
	ds_read_b128 v[156:159], v156 offset:3072
	s_add_u32 s20, s64, 0xb0000
	s_addc_u32 s21, s65, 0
	s_mov_b32 m0, s69
	v_lshl_add_u64 v[222:223], s[20:21], 0, v[204:205]
	ds_read_b128 v[164:167], v242 offset:32768
	ds_read_b128 v[172:175], v242 offset:33792
	ds_read_b128 v[176:179], v242 offset:34816
	ds_read_b128 v[180:183], v242 offset:35840
	ds_read_b128 v[184:187], v242 offset:36864
	ds_read_b128 v[188:191], v242 offset:37888
	ds_read_b128 v[192:195], v242 offset:38912
	ds_read_b128 v[210:213], v242 offset:39936
	global_load_lds_dwordx4 v[222:223], off
	v_lshl_add_u64 v[222:223], s[20:21], 0, v[200:201]
	s_mov_b32 m0, s70
	s_nop 0
	global_load_lds_dwordx4 v[222:223], off
	s_waitcnt vmcnt(8)
	s_waitcnt lgkmcnt(0)
	s_barrier
	s_waitcnt lgkmcnt(0)
	v_mfma_f32_16x16x32_bf16 v[168:171], v[112:115], v[164:167], v[168:171]
	v_mfma_f32_16x16x32_bf16 v[160:163], v[120:123], v[164:167], v[160:163]
	v_mfma_f32_16x16x32_bf16 v[108:111], v[112:115], v[176:179], v[108:111]
	v_mfma_f32_16x16x32_bf16 v[104:107], v[120:123], v[176:179], v[104:107]
	v_mfma_f32_16x16x32_bf16 v[92:95], v[112:115], v[184:187], v[92:95]
	v_mfma_f32_16x16x32_bf16 v[88:91], v[120:123], v[184:187], v[88:91]
	v_mfma_f32_16x16x32_bf16 v[76:79], v[112:115], v[192:195], v[76:79]
	v_mfma_f32_16x16x32_bf16 v[72:75], v[120:123], v[192:195], v[72:75]
	v_mfma_f32_16x16x32_bf16 v[168:171], v[116:119], v[172:175], v[168:171]
	v_mfma_f32_16x16x32_bf16 v[160:163], v[124:127], v[172:175], v[160:163]
	v_mfma_f32_16x16x32_bf16 v[108:111], v[116:119], v[180:183], v[108:111]
	v_mfma_f32_16x16x32_bf16 v[104:107], v[124:127], v[180:183], v[104:107]
	v_mfma_f32_16x16x32_bf16 v[92:95], v[116:119], v[188:191], v[92:95]
	v_mfma_f32_16x16x32_bf16 v[88:91], v[124:127], v[188:191], v[88:91]
	v_mfma_f32_16x16x32_bf16 v[76:79], v[116:119], v[210:213], v[76:79]
	v_mfma_f32_16x16x32_bf16 v[72:75], v[124:127], v[210:213], v[72:75]
	v_mfma_f32_16x16x32_bf16 v[136:139], v[132:135], v[164:167], v[136:139]
	v_mfma_f32_16x16x32_bf16 v[128:131], v[152:155], v[164:167], v[128:131]
	v_mfma_f32_16x16x32_bf16 v[100:103], v[132:135], v[176:179], v[100:103]
	v_mfma_f32_16x16x32_bf16 v[96:99], v[152:155], v[176:179], v[96:99]
	v_mfma_f32_16x16x32_bf16 v[84:87], v[132:135], v[184:187], v[84:87]
	v_mfma_f32_16x16x32_bf16 v[80:83], v[152:155], v[184:187], v[80:83]
	v_mfma_f32_16x16x32_bf16 v[68:71], v[132:135], v[192:195], v[68:71]
	v_mfma_f32_16x16x32_bf16 v[64:67], v[152:155], v[192:195], v[64:67]
	v_mfma_f32_16x16x32_bf16 v[136:139], v[140:143], v[172:175], v[136:139]
	v_mfma_f32_16x16x32_bf16 v[128:131], v[156:159], v[172:175], v[128:131]
	v_mfma_f32_16x16x32_bf16 v[100:103], v[140:143], v[180:183], v[100:103]
	v_mfma_f32_16x16x32_bf16 v[96:99], v[156:159], v[180:183], v[96:99]
	v_mfma_f32_16x16x32_bf16 v[84:87], v[140:143], v[188:191], v[84:87]
	v_mfma_f32_16x16x32_bf16 v[80:83], v[156:159], v[188:191], v[80:83]
	v_mfma_f32_16x16x32_bf16 v[68:71], v[140:143], v[210:213], v[68:71]
	v_mfma_f32_16x16x32_bf16 v[64:67], v[156:159], v[210:213], v[64:67]
	s_barrier
; #define PG8_STAGE(bufoff, gbase, voff) do { _Pragma("unroll") for (int _i = 0; _i < 2; ++_i) \
;         __builtin_amdgcn_global_load_lds((const unsigned*)((const char*)(gbase) + (voff)[_i]), (PG8_LAS unsigned*)(lds + (bufoff) + ldsw + _i * 8192), 16, 0, 0); } while (0)
; #define PG8_LDA(dst, b, h) do { _Pragma("unroll") for (int m = 0; m < 4; ++m) _Pragma("unroll") for (int k = 0; k < 2; ++k) dst[m][k] = *(const PG8_LAS bf16x8*)(lds + PG8_SA(b, h) + aoff + m * 2048 + k * 1024); } while (0)
; #define PG8_MMA(ai, bj, At, Bt) do { __builtin_amdgcn_s_setprio(1); _Pragma("unroll") for (int m = 0; m < 4; ++m) _Pragma("unroll") for (int n = 0; n < 2; ++n) _Pragma("unroll") for (int k = 0; k < 2; ++k) \
;         acc[ai][bj][m][n] = __builtin_amdgcn_mfma_f32_16x16x32_bf16(Bt[n][k], At[m][k], acc[ai][bj][m][n], 0, 0, 0); __builtin_amdgcn_s_setprio(0); } while (0)
; #define PG8_WAIT_V(n) asm volatile("s_waitcnt vmcnt(" #n ")" ::: "memory")
; #define PG8_WAIT_L(n) asm volatile("s_waitcnt lgkmcnt(" #n ")" ::: "memory")
; #define PG8_BAR __builtin_amdgcn_s_barrier()
; #define PG8_SCHED __builtin_amdgcn_sched_barrier(0)
; template <class Epi, class Sched, bool ALIGN_EPI = false, bool SP2 = false>
; __device__ __forceinline__ void gemm_phase(PG8_LAS unsigned char* lds, const Gemm g, const Sched& S, const Epi& E) {
;     ...
;             PG8_LDA(At, 1, 1); PG8_STAGE(PG8_SB(1, 0), b3, voffB); PG8_STAGE(PG8_SB(1, 1), b3 + hstep, voffB); PG8_STAGE(PG8_SA(1, 0), a3, voffA);
;             PG8_WAIT_V(8); PG8_WAIT_L(0); PG8_BAR; PG8_MMA(1, 0, At, B0); PG8_MMA(1, 1, At, B1); PG8_BAR; PG8_SCHED;
	s_add_i32 s5, s5, s66
	v_lshl_add_u64 v[214:215], v[214:215], 0, s[22:23]
	s_mov_b32 m0, s5
	ds_read_b128 v[164:167], v242 offset:49152
	ds_read_b128 v[172:175], v242 offset:50176
	ds_read_b128 v[176:179], v242 offset:51200
	ds_read_b128 v[180:183], v242 offset:52224
	ds_read_b128 v[184:187], v242 offset:53248
	ds_read_b128 v[188:191], v242 offset:54272
	ds_read_b128 v[192:195], v242 offset:55296
	ds_read_b128 v[210:213], v242 offset:56320
	global_load_lds_dwordx4 v[214:215], off
	s_add_i32 m0, s5, 0x2000
	s_add_u32 s20, s62, 0xb0080
	v_lshl_add_u64 v[214:215], v[216:217], 0, s[22:23]
	s_addc_u32 s21, s63, 0
	s_add_i32 s5, s8, s66
	global_load_lds_dwordx4 v[214:215], off
	v_lshl_add_u64 v[214:215], s[20:21], 0, v[202:203]
	s_mov_b32 m0, s5
	s_nop 0
	global_load_lds_dwordx4 v[214:215], off
	v_lshl_add_u64 v[214:215], s[20:21], 0, v[146:147]
	s_add_i32 m0, s5, 0x2000
	s_nop 0
	global_load_lds_dwordx4 v[214:215], off
	v_lshl_add_u64 v[214:215], v[218:219], 0, s[22:23]
	s_mov_b32 m0, s71
	s_nop 0
	global_load_lds_dwordx4 v[214:215], off
	v_lshl_add_u64 v[214:215], v[220:221], 0, s[22:23]
	s_mov_b32 m0, s72
	s_nop 0
	global_load_lds_dwordx4 v[214:215], off
	s_waitcnt vmcnt(8)
	s_waitcnt lgkmcnt(0)
	s_barrier
	s_waitcnt lgkmcnt(0)
	v_mfma_f32_16x16x32_bf16 v[60:63], v[112:115], v[164:167], v[60:63]
	v_mfma_f32_16x16x32_bf16 v[56:59], v[120:123], v[164:167], v[56:59]
	v_mfma_f32_16x16x32_bf16 v[44:47], v[112:115], v[176:179], v[44:47]
	v_mfma_f32_16x16x32_bf16 v[40:43], v[120:123], v[176:179], v[40:43]
	v_mfma_f32_16x16x32_bf16 v[28:31], v[112:115], v[184:187], v[28:31]
	v_mfma_f32_16x16x32_bf16 v[24:27], v[120:123], v[184:187], v[24:27]
	v_mfma_f32_16x16x32_bf16 v[12:15], v[112:115], v[192:195], v[12:15]
	v_mfma_f32_16x16x32_bf16 v[8:11], v[120:123], v[192:195], v[8:11]
	v_mfma_f32_16x16x32_bf16 v[60:63], v[116:119], v[172:175], v[60:63]
	v_mfma_f32_16x16x32_bf16 v[56:59], v[124:127], v[172:175], v[56:59]
	v_mfma_f32_16x16x32_bf16 v[44:47], v[116:119], v[180:183], v[44:47]
	v_mfma_f32_16x16x32_bf16 v[40:43], v[124:127], v[180:183], v[40:43]
	v_mfma_f32_16x16x32_bf16 v[28:31], v[116:119], v[188:191], v[28:31]
	v_mfma_f32_16x16x32_bf16 v[24:27], v[124:127], v[188:191], v[24:27]
	v_mfma_f32_16x16x32_bf16 v[12:15], v[116:119], v[210:213], v[12:15]
	v_mfma_f32_16x16x32_bf16 v[8:11], v[124:127], v[210:213], v[8:11]
	v_mfma_f32_16x16x32_bf16 v[52:55], v[132:135], v[164:167], v[52:55]
	v_mfma_f32_16x16x32_bf16 v[48:51], v[152:155], v[164:167], v[48:51]
	v_mfma_f32_16x16x32_bf16 v[36:39], v[132:135], v[176:179], v[36:39]
	v_mfma_f32_16x16x32_bf16 v[32:35], v[152:155], v[176:179], v[32:35]
	v_mfma_f32_16x16x32_bf16 v[20:23], v[132:135], v[184:187], v[20:23]
	v_mfma_f32_16x16x32_bf16 v[16:19], v[152:155], v[184:187], v[16:19]
	v_mfma_f32_16x16x32_bf16 v[4:7], v[132:135], v[192:195], v[4:7]
	v_mfma_f32_16x16x32_bf16 v[0:3], v[152:155], v[192:195], v[0:3]
	v_mfma_f32_16x16x32_bf16 v[52:55], v[140:143], v[172:175], v[52:55]
	v_mfma_f32_16x16x32_bf16 v[48:51], v[156:159], v[172:175], v[48:51]
	v_mfma_f32_16x16x32_bf16 v[36:39], v[140:143], v[180:183], v[36:39]
	v_mfma_f32_16x16x32_bf16 v[32:35], v[156:159], v[180:183], v[32:35]
	v_mfma_f32_16x16x32_bf16 v[20:23], v[140:143], v[188:191], v[20:23]
	v_mfma_f32_16x16x32_bf16 v[16:19], v[156:159], v[188:191], v[16:19]
	v_mfma_f32_16x16x32_bf16 v[4:7], v[140:143], v[210:213], v[4:7]
	v_mfma_f32_16x16x32_bf16 v[0:3], v[156:159], v[210:213], v[0:3]
	s_barrier
	s_add_i32 s39, s39, 2
	s_add_u32 s26, s26, 0x100
	s_addc_u32 s27, s27, 0
	s_cmp_gt_u32 s39, 41
	s_mov_b64 s[58:59], s[60:61]
	s_cbranch_scc0 .LBB0_112
	s_and_b64 vcc, exec, s[54:55]
	s_cbranch_vccz .LBB0_115
	s_barrier

; #define PG8_STAGE(bufoff, gbase, voff) do { _Pragma("unroll") for (int _i = 0; _i < 2; ++_i) \
;         __builtin_amdgcn_global_load_lds((const unsigned*)((const char*)(gbase) + (voff)[_i]), (PG8_LAS unsigned*)(lds + (bufoff) + ldsw + _i * 8192), 16, 0, 0); } while (0)
; #define PG8_LDA(dst, b, h) do { _Pragma("unroll") for (int m = 0; m < 4; ++m) _Pragma("unroll") for (int k = 0; k < 2; ++k) dst[m][k] = *(const PG8_LAS bf16x8*)(lds + PG8_SA(b, h) + aoff + m * 2048 + k * 1024); } while (0)
; #define PG8_LDB(dst, b, h) do { _Pragma("unroll") for (int n = 0; n < 2; ++n) _Pragma("unroll") for (int k = 0; k < 2; ++k) dst[n][k] = *(const PG8_LAS bf16x8*)(lds + PG8_SB(b, h) + boff + n * 2048 + k * 1024); } while (0)
; #define PG8_MMA(ai, bj, At, Bt) do { __builtin_amdgcn_s_setprio(1); _Pragma("unroll") for (int m = 0; m < 4; ++m) _Pragma("unroll") for (int n = 0; n < 2; ++n) _Pragma("unroll") for (int k = 0; k < 2; ++k) \
;         acc[ai][bj][m][n] = __builtin_amdgcn_mfma_f32_16x16x32_bf16(Bt[n][k], At[m][k], acc[ai][bj][m][n], 0, 0, 0); __builtin_amdgcn_s_setprio(0); } while (0)
; #define PG8_WAIT_V(n) asm volatile("s_waitcnt vmcnt(" #n ")" ::: "memory")
; #define PG8_BAR __builtin_amdgcn_s_barrier()
; template <class Epi, class Sched, bool ALIGN_EPI = false, bool SP2 = false>
; __device__ __forceinline__ void gemm_phase(PG8_LAS unsigned char* lds, const Gemm g, const Sched& S, const Epi& E) {
;     ...
;         for (int t = 0; t < nt; t += 2) {
;             const bool last = (t == nt - 2);
;             const char* a1 = cA + (size_t)(t + 1) * kstep;
;             const char* a2 = last ? nA : cA + (size_t)(t + 2) * kstep; const char* b2 = last ? nB : cB + (size_t)(t + 2) * kstep;
;             const char* a3 = a2 + kstep; const char* b3 = b2 + kstep;
;             if (last && has_next) S.a_ready(nxt);
;             if constexpr (SP2) {
;             PG8_LDB(B0, 0, 0); PG8_LDB(B1, 0, 1); PG8_SCHED; PG8_LDA(At, 0, 0); PG8_STAGE(PG8_SA(1, 1), a1 + hstep, voffA);
;             PG8_WAIT_V(8); PG8_WAIT_L(0); PG8_BAR; PG8_MMA(0, 0, At, B0); PG8_MMA(0, 1, At, B1); PG8_BAR; PG8_SCHED;
;             PG8_LDA(At, 0, 1); PG8_STAGE(PG8_SB(0, 0), b2, voffB); PG8_STAGE(PG8_SB(0, 1), b2 + hstep, voffB); PG8_STAGE(PG8_SA(0, 0), a2, voffA);
;             PG8_WAIT_V(8); PG8_WAIT_L(0); PG8_BAR; PG8_MMA(1, 0, At, B0); PG8_MMA(1, 1, At, B1); PG8_BAR; PG8_SCHED;
.Lpeel_g3:
	s_add_u32 s5, s58, 0xfffc0080
	s_addc_u32 s8, s59, -1
	s_add_i32 s10, 0, 0x10000
	s_cmp_eq_u32 s72, 12
	s_cselect_b32 s63, s26, s8
	s_cselect_b32 s62, s27, s5
	v_add_u32_e32 v143, s10, v157
	s_cselect_b32 s61, s36, s53
	s_cselect_b32 s60, s39, s51
	s_add_i32 s5, 0, 0x14000
	ds_read_b128 v[162:165], v143
	ds_read_b128 v[166:169], v143 offset:1024
	ds_read_b128 v[170:173], v143 offset:2048
	ds_read_b128 v[174:177], v143 offset:3072
	v_add_u32_e32 v143, s5, v157
	ds_read_b128 v[178:181], v143
	ds_read_b128 v[182:185], v143 offset:1024
	ds_read_b128 v[186:189], v143 offset:2048
	ds_read_b128 v[190:193], v143 offset:3072
	v_lshl_add_u64 v[194:195], s[58:59], 0, v[140:141]
	s_add_i32 m0, s65, 0xc000
	ds_read_b128 v[200:203], v161
	ds_read_b128 v[204:207], v161 offset:1024
	ds_read_b128 v[208:211], v161 offset:2048
	ds_read_b128 v[212:215], v161 offset:3072
	ds_read_b128 v[216:219], v161 offset:4096
	ds_read_b128 v[220:223], v161 offset:5120
	ds_read_b128 v[224:227], v161 offset:6144
	ds_read_b128 v[228:231], v161 offset:7168
	global_load_lds_dwordx4 v[194:195], off
	v_lshl_add_u64 v[194:195], s[58:59], 0, v[138:139]
	s_add_i32 m0, s65, 0xe000
	s_nop 0
	global_load_lds_dwordx4 v[194:195], off
	s_waitcnt vmcnt(10)
	s_waitcnt lgkmcnt(0)
	s_barrier
	s_waitcnt lgkmcnt(0)
	v_mfma_f32_16x16x32_bf16 v[124:127], v[162:165], v[200:203], 0
	v_mfma_f32_16x16x32_bf16 v[120:123], v[170:173], v[200:203], 0
	v_mfma_f32_16x16x32_bf16 v[108:111], v[162:165], v[208:211], 0
	v_mfma_f32_16x16x32_bf16 v[104:107], v[170:173], v[208:211], 0
	v_mfma_f32_16x16x32_bf16 v[92:95], v[162:165], v[216:219], 0
	v_mfma_f32_16x16x32_bf16 v[88:91], v[170:173], v[216:219], 0
	v_mfma_f32_16x16x32_bf16 v[76:79], v[162:165], v[224:227], 0
	v_mfma_f32_16x16x32_bf16 v[72:75], v[170:173], v[224:227], 0
	v_mfma_f32_16x16x32_bf16 v[124:127], v[166:169], v[204:207], v[124:127]
	v_mfma_f32_16x16x32_bf16 v[120:123], v[174:177], v[204:207], v[120:123]
	v_mfma_f32_16x16x32_bf16 v[108:111], v[166:169], v[212:215], v[108:111]
	v_mfma_f32_16x16x32_bf16 v[104:107], v[174:177], v[212:215], v[104:107]
	v_mfma_f32_16x16x32_bf16 v[92:95], v[166:169], v[220:223], v[92:95]
	v_mfma_f32_16x16x32_bf16 v[88:91], v[174:177], v[220:223], v[88:91]
	v_mfma_f32_16x16x32_bf16 v[76:79], v[166:169], v[228:231], v[76:79]
	v_mfma_f32_16x16x32_bf16 v[72:75], v[174:177], v[228:231], v[72:75]
	v_mfma_f32_16x16x32_bf16 v[116:119], v[178:181], v[200:203], 0
	v_mfma_f32_16x16x32_bf16 v[112:115], v[186:189], v[200:203], 0
	v_mfma_f32_16x16x32_bf16 v[100:103], v[178:181], v[208:211], 0
	v_mfma_f32_16x16x32_bf16 v[96:99], v[186:189], v[208:211], 0
	v_mfma_f32_16x16x32_bf16 v[84:87], v[178:181], v[216:219], 0
	v_mfma_f32_16x16x32_bf16 v[80:83], v[186:189], v[216:219], 0
	v_mfma_f32_16x16x32_bf16 v[68:71], v[178:181], v[224:227], 0
	v_mfma_f32_16x16x32_bf16 v[64:67], v[186:189], v[224:227], 0
	v_mfma_f32_16x16x32_bf16 v[116:119], v[182:185], v[204:207], v[116:119]
	v_mfma_f32_16x16x32_bf16 v[112:115], v[190:193], v[204:207], v[112:115]
	v_mfma_f32_16x16x32_bf16 v[100:103], v[182:185], v[212:215], v[100:103]
	v_mfma_f32_16x16x32_bf16 v[96:99], v[190:193], v[212:215], v[96:99]
	v_mfma_f32_16x16x32_bf16 v[84:87], v[182:185], v[220:223], v[84:87]
	v_mfma_f32_16x16x32_bf16 v[80:83], v[190:193], v[220:223], v[80:83]
	v_mfma_f32_16x16x32_bf16 v[68:71], v[182:185], v[228:231], v[68:71]
	v_mfma_f32_16x16x32_bf16 v[64:67], v[190:193], v[228:231], v[64:67]
	s_barrier
	s_add_i32 s8, s10, s64
	v_lshl_add_u64 v[194:195], s[60:61], 0, v[132:133]
	s_mov_b32 m0, s8
	ds_read_b128 v[200:203], v161 offset:16384
	ds_read_b128 v[204:207], v161 offset:17408
	ds_read_b128 v[208:211], v161 offset:18432
	ds_read_b128 v[212:215], v161 offset:19456
	ds_read_b128 v[216:219], v161 offset:20480
	ds_read_b128 v[220:223], v161 offset:21504
	ds_read_b128 v[224:227], v161 offset:22528
	ds_read_b128 v[228:231], v161 offset:23552
	global_load_lds_dwordx4 v[194:195], off
	s_add_i32 m0, s8, 0x2000
	s_add_u32 s20, s60, 0x40000
	v_lshl_add_u64 v[240:241], s[60:61], 0, v[128:129]
	s_addc_u32 s21, s61, 0
	s_add_i32 s5, s5, s64
	global_load_lds_dwordx4 v[240:241], off
	v_lshl_add_u64 v[242:243], s[20:21], 0, v[132:133]
	s_mov_b32 m0, s5
	v_lshl_add_u64 v[244:245], s[62:63], 0, v[130:131]
	global_load_lds_dwordx4 v[242:243], off
	v_lshl_add_u64 v[242:243], s[20:21], 0, v[128:129]
	s_add_i32 m0, s5, 0x2000
	s_nop 0
	global_load_lds_dwordx4 v[242:243], off
	v_lshl_add_u64 v[242:243], s[62:63], 0, v[134:135]
	s_mov_b32 m0, s65
	s_nop 0
	global_load_lds_dwordx4 v[242:243], off
	s_mov_b32 m0, s66
	s_nop 0
	global_load_lds_dwordx4 v[244:245], off
	s_waitcnt vmcnt(10)
	s_waitcnt lgkmcnt(0)
	s_barrier
	s_waitcnt lgkmcnt(0)
	v_mfma_f32_16x16x32_bf16 v[60:63], v[162:165], v[200:203], 0
	v_mfma_f32_16x16x32_bf16 v[56:59], v[170:173], v[200:203], 0
	v_mfma_f32_16x16x32_bf16 v[44:47], v[162:165], v[208:211], 0
	v_mfma_f32_16x16x32_bf16 v[40:43], v[170:173], v[208:211], 0
	v_mfma_f32_16x16x32_bf16 v[28:31], v[162:165], v[216:219], 0
	v_mfma_f32_16x16x32_bf16 v[24:27], v[170:173], v[216:219], 0
	v_mfma_f32_16x16x32_bf16 v[12:15], v[162:165], v[224:227], 0
	v_mfma_f32_16x16x32_bf16 v[8:11], v[170:173], v[224:227], 0
	v_mfma_f32_16x16x32_bf16 v[60:63], v[166:169], v[204:207], v[60:63]
	v_mfma_f32_16x16x32_bf16 v[56:59], v[174:177], v[204:207], v[56:59]
	v_mfma_f32_16x16x32_bf16 v[44:47], v[166:169], v[212:215], v[44:47]
	v_mfma_f32_16x16x32_bf16 v[40:43], v[174:177], v[212:215], v[40:43]
	v_mfma_f32_16x16x32_bf16 v[28:31], v[166:169], v[220:223], v[28:31]
	v_mfma_f32_16x16x32_bf16 v[24:27], v[174:177], v[220:223], v[24:27]
	v_mfma_f32_16x16x32_bf16 v[12:15], v[166:169], v[228:231], v[12:15]
	v_mfma_f32_16x16x32_bf16 v[8:11], v[174:177], v[228:231], v[8:11]
	v_mfma_f32_16x16x32_bf16 v[52:55], v[178:181], v[200:203], 0
	v_mfma_f32_16x16x32_bf16 v[48:51], v[186:189], v[200:203], 0
	v_mfma_f32_16x16x32_bf16 v[36:39], v[178:181], v[208:211], 0
	v_mfma_f32_16x16x32_bf16 v[32:35], v[186:189], v[208:211], 0
	v_mfma_f32_16x16x32_bf16 v[20:23], v[178:181], v[216:219], 0
	v_mfma_f32_16x16x32_bf16 v[16:19], v[186:189], v[216:219], 0
	v_mfma_f32_16x16x32_bf16 v[4:7], v[178:181], v[224:227], 0
	v_mfma_f32_16x16x32_bf16 v[0:3], v[186:189], v[224:227], 0
	v_mfma_f32_16x16x32_bf16 v[52:55], v[182:185], v[204:207], v[52:55]
	v_mfma_f32_16x16x32_bf16 v[48:51], v[190:193], v[204:207], v[48:51]
	v_mfma_f32_16x16x32_bf16 v[36:39], v[182:185], v[212:215], v[36:39]
	v_mfma_f32_16x16x32_bf16 v[32:35], v[190:193], v[212:215], v[32:35]
	v_mfma_f32_16x16x32_bf16 v[20:23], v[182:185], v[220:223], v[20:23]
	v_mfma_f32_16x16x32_bf16 v[16:19], v[190:193], v[220:223], v[16:19]
	v_mfma_f32_16x16x32_bf16 v[4:7], v[182:185], v[228:231], v[4:7]
	v_mfma_f32_16x16x32_bf16 v[0:3], v[190:193], v[228:231], v[0:3]
	s_barrier
	s_branch .Lmid_g3

; #define PG8_STAGE(bufoff, gbase, voff) do { _Pragma("unroll") for (int _i = 0; _i < 2; ++_i) \
;         __builtin_amdgcn_global_load_lds((const unsigned*)((const char*)(gbase) + (voff)[_i]), (PG8_LAS unsigned*)(lds + (bufoff) + ldsw + _i * 8192), 16, 0, 0); } while (0)
; #define PG8_LDA(dst, b, h) do { _Pragma("unroll") for (int m = 0; m < 4; ++m) _Pragma("unroll") for (int k = 0; k < 2; ++k) dst[m][k] = *(const PG8_LAS bf16x8*)(lds + PG8_SA(b, h) + aoff + m * 2048 + k * 1024); } while (0)
; #define PG8_LDB(dst, b, h) do { _Pragma("unroll") for (int n = 0; n < 2; ++n) _Pragma("unroll") for (int k = 0; k < 2; ++k) dst[n][k] = *(const PG8_LAS bf16x8*)(lds + PG8_SB(b, h) + boff + n * 2048 + k * 1024); } while (0)
; #define PG8_MMA(ai, bj, At, Bt) do { __builtin_amdgcn_s_setprio(1); _Pragma("unroll") for (int m = 0; m < 4; ++m) _Pragma("unroll") for (int n = 0; n < 2; ++n) _Pragma("unroll") for (int k = 0; k < 2; ++k) \
;         acc[ai][bj][m][n] = __builtin_amdgcn_mfma_f32_16x16x32_bf16(Bt[n][k], At[m][k], acc[ai][bj][m][n], 0, 0, 0); __builtin_amdgcn_s_setprio(0); } while (0)
; #define PG8_WAIT_V(n) asm volatile("s_waitcnt vmcnt(" #n ")" ::: "memory")
; #define PG8_WAIT_L(n) asm volatile("s_waitcnt lgkmcnt(" #n ")" ::: "memory")
; #define PG8_BAR __builtin_amdgcn_s_barrier()
; #define PG8_SCHED __builtin_amdgcn_sched_barrier(0)
; template <class Epi, class Sched, bool ALIGN_EPI = false, bool SP2 = false>
; __device__ __forceinline__ void gemm_phase(PG8_LAS unsigned char* lds, const Gemm g, const Sched& S, const Epi& E) {
;     ...
;             PG8_LDB(B0, 0, 0); PG8_LDB(B1, 0, 1); PG8_SCHED; PG8_LDA(At, 0, 0); PG8_STAGE(PG8_SA(1, 1), a1 + hstep, voffA);
;             PG8_WAIT_V(8); PG8_WAIT_L(0); PG8_BAR; PG8_MMA(0, 0, At, B0); PG8_MMA(0, 1, At, B1); PG8_BAR; PG8_SCHED;
;             PG8_LDA(At, 0, 1); PG8_STAGE(PG8_SB(0, 0), b2, voffB); PG8_STAGE(PG8_SB(0, 1), b2 + hstep, voffB); PG8_STAGE(PG8_SA(0, 0), a2, voffA);
;             PG8_WAIT_V(8); PG8_WAIT_L(0); PG8_BAR; PG8_MMA(1, 0, At, B0); PG8_MMA(1, 1, At, B1); PG8_BAR; PG8_SCHED;
.LBB0_152:
	s_add_u32 s5, s58, 0xfffc0080
	s_addc_u32 s8, s59, -1
	s_add_i32 s10, 0, 0x10000
	s_cmp_eq_u32 s72, 12
	s_cselect_b32 s63, s26, s8
	s_cselect_b32 s62, s27, s5
	v_add_u32_e32 v143, s10, v157
	s_cselect_b32 s61, s36, s53
	s_cselect_b32 s60, s39, s51
	s_add_i32 s5, 0, 0x14000
	ds_read_b128 v[162:165], v143
	ds_read_b128 v[166:169], v143 offset:1024
	ds_read_b128 v[170:173], v143 offset:2048
	ds_read_b128 v[174:177], v143 offset:3072
	v_add_u32_e32 v143, s5, v157
	ds_read_b128 v[178:181], v143
	ds_read_b128 v[182:185], v143 offset:1024
	ds_read_b128 v[186:189], v143 offset:2048
	ds_read_b128 v[190:193], v143 offset:3072
	v_lshl_add_u64 v[194:195], s[58:59], 0, v[140:141]
	s_add_i32 m0, s65, 0xc000
	ds_read_b128 v[200:203], v161
	ds_read_b128 v[204:207], v161 offset:1024
	ds_read_b128 v[208:211], v161 offset:2048
	ds_read_b128 v[212:215], v161 offset:3072
	ds_read_b128 v[216:219], v161 offset:4096
	ds_read_b128 v[220:223], v161 offset:5120
	ds_read_b128 v[224:227], v161 offset:6144
	ds_read_b128 v[228:231], v161 offset:7168
	global_load_lds_dwordx4 v[194:195], off
	v_lshl_add_u64 v[194:195], s[58:59], 0, v[138:139]
	s_add_i32 m0, s65, 0xe000
	s_nop 0
	global_load_lds_dwordx4 v[194:195], off
	s_waitcnt vmcnt(8)
	s_waitcnt lgkmcnt(0)
	s_barrier
	s_waitcnt lgkmcnt(0)
	v_mfma_f32_16x16x32_bf16 v[124:127], v[162:165], v[200:203], v[124:127]
	v_mfma_f32_16x16x32_bf16 v[120:123], v[170:173], v[200:203], v[120:123]
	v_mfma_f32_16x16x32_bf16 v[108:111], v[162:165], v[208:211], v[108:111]
	v_mfma_f32_16x16x32_bf16 v[104:107], v[170:173], v[208:211], v[104:107]
	v_mfma_f32_16x16x32_bf16 v[92:95], v[162:165], v[216:219], v[92:95]
	v_mfma_f32_16x16x32_bf16 v[88:91], v[170:173], v[216:219], v[88:91]
	v_mfma_f32_16x16x32_bf16 v[76:79], v[162:165], v[224:227], v[76:79]
	v_mfma_f32_16x16x32_bf16 v[72:75], v[170:173], v[224:227], v[72:75]
	v_mfma_f32_16x16x32_bf16 v[124:127], v[166:169], v[204:207], v[124:127]
	v_mfma_f32_16x16x32_bf16 v[120:123], v[174:177], v[204:207], v[120:123]
	v_mfma_f32_16x16x32_bf16 v[108:111], v[166:169], v[212:215], v[108:111]
	v_mfma_f32_16x16x32_bf16 v[104:107], v[174:177], v[212:215], v[104:107]
	v_mfma_f32_16x16x32_bf16 v[92:95], v[166:169], v[220:223], v[92:95]
	v_mfma_f32_16x16x32_bf16 v[88:91], v[174:177], v[220:223], v[88:91]
	v_mfma_f32_16x16x32_bf16 v[76:79], v[166:169], v[228:231], v[76:79]
	v_mfma_f32_16x16x32_bf16 v[72:75], v[174:177], v[228:231], v[72:75]
	v_mfma_f32_16x16x32_bf16 v[116:119], v[178:181], v[200:203], v[116:119]
	v_mfma_f32_16x16x32_bf16 v[112:115], v[186:189], v[200:203], v[112:115]
	v_mfma_f32_16x16x32_bf16 v[100:103], v[178:181], v[208:211], v[100:103]
	v_mfma_f32_16x16x32_bf16 v[96:99], v[186:189], v[208:211], v[96:99]
	v_mfma_f32_16x16x32_bf16 v[84:87], v[178:181], v[216:219], v[84:87]
	v_mfma_f32_16x16x32_bf16 v[80:83], v[186:189], v[216:219], v[80:83]
	v_mfma_f32_16x16x32_bf16 v[68:71], v[178:181], v[224:227], v[68:71]
	v_mfma_f32_16x16x32_bf16 v[64:67], v[186:189], v[224:227], v[64:67]
	v_mfma_f32_16x16x32_bf16 v[116:119], v[182:185], v[204:207], v[116:119]
	v_mfma_f32_16x16x32_bf16 v[112:115], v[190:193], v[204:207], v[112:115]
	v_mfma_f32_16x16x32_bf16 v[100:103], v[182:185], v[212:215], v[100:103]
	v_mfma_f32_16x16x32_bf16 v[96:99], v[190:193], v[212:215], v[96:99]
	v_mfma_f32_16x16x32_bf16 v[84:87], v[182:185], v[220:223], v[84:87]
	v_mfma_f32_16x16x32_bf16 v[80:83], v[190:193], v[220:223], v[80:83]
	v_mfma_f32_16x16x32_bf16 v[68:71], v[182:185], v[228:231], v[68:71]
	v_mfma_f32_16x16x32_bf16 v[64:67], v[190:193], v[228:231], v[64:67]
	s_barrier
	s_add_i32 s8, s10, s64
	v_lshl_add_u64 v[194:195], s[60:61], 0, v[132:133]
	s_mov_b32 m0, s8
	ds_read_b128 v[200:203], v161 offset:16384
	ds_read_b128 v[204:207], v161 offset:17408
	ds_read_b128 v[208:211], v161 offset:18432
	ds_read_b128 v[212:215], v161 offset:19456
	ds_read_b128 v[216:219], v161 offset:20480
	ds_read_b128 v[220:223], v161 offset:21504
	ds_read_b128 v[224:227], v161 offset:22528
	ds_read_b128 v[228:231], v161 offset:23552
	global_load_lds_dwordx4 v[194:195], off
	s_add_i32 m0, s8, 0x2000
	s_add_u32 s20, s60, 0x40000
	v_lshl_add_u64 v[240:241], s[60:61], 0, v[128:129]
	s_addc_u32 s21, s61, 0
	s_add_i32 s5, s5, s64
	global_load_lds_dwordx4 v[240:241], off
	v_lshl_add_u64 v[242:243], s[20:21], 0, v[132:133]
	s_mov_b32 m0, s5
	v_lshl_add_u64 v[244:245], s[62:63], 0, v[130:131]
	global_load_lds_dwordx4 v[242:243], off
	v_lshl_add_u64 v[242:243], s[20:21], 0, v[128:129]
	s_add_i32 m0, s5, 0x2000
	s_nop 0
	global_load_lds_dwordx4 v[242:243], off
	v_lshl_add_u64 v[242:243], s[62:63], 0, v[134:135]
	s_mov_b32 m0, s65
	s_nop 0
	global_load_lds_dwordx4 v[242:243], off
	s_mov_b32 m0, s66
	s_nop 0
	global_load_lds_dwordx4 v[244:245], off
	s_waitcnt vmcnt(8)
	s_waitcnt lgkmcnt(0)
	s_barrier
	s_waitcnt lgkmcnt(0)
	v_mfma_f32_16x16x32_bf16 v[60:63], v[162:165], v[200:203], v[60:63]
	v_mfma_f32_16x16x32_bf16 v[56:59], v[170:173], v[200:203], v[56:59]
	v_mfma_f32_16x16x32_bf16 v[44:47], v[162:165], v[208:211], v[44:47]
	v_mfma_f32_16x16x32_bf16 v[40:43], v[170:173], v[208:211], v[40:43]
	v_mfma_f32_16x16x32_bf16 v[28:31], v[162:165], v[216:219], v[28:31]
	v_mfma_f32_16x16x32_bf16 v[24:27], v[170:173], v[216:219], v[24:27]
	v_mfma_f32_16x16x32_bf16 v[12:15], v[162:165], v[224:227], v[12:15]
	v_mfma_f32_16x16x32_bf16 v[8:11], v[170:173], v[224:227], v[8:11]
	v_mfma_f32_16x16x32_bf16 v[60:63], v[166:169], v[204:207], v[60:63]
	v_mfma_f32_16x16x32_bf16 v[56:59], v[174:177], v[204:207], v[56:59]
	v_mfma_f32_16x16x32_bf16 v[44:47], v[166:169], v[212:215], v[44:47]
	v_mfma_f32_16x16x32_bf16 v[40:43], v[174:177], v[212:215], v[40:43]
	v_mfma_f32_16x16x32_bf16 v[28:31], v[166:169], v[220:223], v[28:31]
	v_mfma_f32_16x16x32_bf16 v[24:27], v[174:177], v[220:223], v[24:27]
	v_mfma_f32_16x16x32_bf16 v[12:15], v[166:169], v[228:231], v[12:15]
	v_mfma_f32_16x16x32_bf16 v[8:11], v[174:177], v[228:231], v[8:11]
	v_mfma_f32_16x16x32_bf16 v[52:55], v[178:181], v[200:203], v[52:55]
	v_mfma_f32_16x16x32_bf16 v[48:51], v[186:189], v[200:203], v[48:51]
	v_mfma_f32_16x16x32_bf16 v[36:39], v[178:181], v[208:211], v[36:39]
	v_mfma_f32_16x16x32_bf16 v[32:35], v[186:189], v[208:211], v[32:35]
	v_mfma_f32_16x16x32_bf16 v[20:23], v[178:181], v[216:219], v[20:23]
	v_mfma_f32_16x16x32_bf16 v[16:19], v[186:189], v[216:219], v[16:19]
	v_mfma_f32_16x16x32_bf16 v[4:7], v[178:181], v[224:227], v[4:7]
	v_mfma_f32_16x16x32_bf16 v[0:3], v[186:189], v[224:227], v[0:3]
	v_mfma_f32_16x16x32_bf16 v[52:55], v[182:185], v[204:207], v[52:55]
	v_mfma_f32_16x16x32_bf16 v[48:51], v[190:193], v[204:207], v[48:51]
	v_mfma_f32_16x16x32_bf16 v[36:39], v[182:185], v[212:215], v[36:39]
	v_mfma_f32_16x16x32_bf16 v[32:35], v[190:193], v[212:215], v[32:35]
	v_mfma_f32_16x16x32_bf16 v[20:23], v[182:185], v[220:223], v[20:23]
	v_mfma_f32_16x16x32_bf16 v[16:19], v[190:193], v[220:223], v[16:19]
	v_mfma_f32_16x16x32_bf16 v[4:7], v[182:185], v[228:231], v[4:7]
	v_mfma_f32_16x16x32_bf16 v[0:3], v[190:193], v[228:231], v[0:3]
	s_barrier
; #define PG8_STAGE(bufoff, gbase, voff) do { _Pragma("unroll") for (int _i = 0; _i < 2; ++_i) \
;         __builtin_amdgcn_global_load_lds((const unsigned*)((const char*)(gbase) + (voff)[_i]), (PG8_LAS unsigned*)(lds + (bufoff) + ldsw + _i * 8192), 16, 0, 0); } while (0)
; #define PG8_LDA(dst, b, h) do { _Pragma("unroll") for (int m = 0; m < 4; ++m) _Pragma("unroll") for (int k = 0; k < 2; ++k) dst[m][k] = *(const PG8_LAS bf16x8*)(lds + PG8_SA(b, h) + aoff + m * 2048 + k * 1024); } while (0)
; #define PG8_LDB(dst, b, h) do { _Pragma("unroll") for (int n = 0; n < 2; ++n) _Pragma("unroll") for (int k = 0; k < 2; ++k) dst[n][k] = *(const PG8_LAS bf16x8*)(lds + PG8_SB(b, h) + boff + n * 2048 + k * 1024); } while (0)
; #define PG8_MMA(ai, bj, At, Bt) do { __builtin_amdgcn_s_setprio(1); _Pragma("unroll") for (int m = 0; m < 4; ++m) _Pragma("unroll") for (int n = 0; n < 2; ++n) _Pragma("unroll") for (int k = 0; k < 2; ++k) \
;         acc[ai][bj][m][n] = __builtin_amdgcn_mfma_f32_16x16x32_bf16(Bt[n][k], At[m][k], acc[ai][bj][m][n], 0, 0, 0); __builtin_amdgcn_s_setprio(0); } while (0)
; #define PG8_WAIT_V(n) asm volatile("s_waitcnt vmcnt(" #n ")" ::: "memory")
; #define PG8_WAIT_L(n) asm volatile("s_waitcnt lgkmcnt(" #n ")" ::: "memory")
; #define PG8_BAR __builtin_amdgcn_s_barrier()
; #define PG8_SCHED __builtin_amdgcn_sched_barrier(0)
; template <class Epi, class Sched, bool ALIGN_EPI = false, bool SP2 = false>
; __device__ __forceinline__ void gemm_phase(PG8_LAS unsigned char* lds, const Gemm g, const Sched& S, const Epi& E) {
;     ...
;             PG8_LDB(B0, 1, 0); PG8_LDB(B1, 1, 1); PG8_SCHED; PG8_LDA(At, 1, 0); PG8_STAGE(PG8_SA(0, 1), a2 + hstep, voffA);
;             PG8_WAIT_V(8); PG8_WAIT_L(0); PG8_BAR; PG8_MMA(0, 0, At, B0); PG8_MMA(0, 1, At, B1); PG8_BAR; PG8_SCHED;
.Lmid_g3:
	s_add_i32 s5, 0, 0x18000
	v_add_u32_e32 v143, s5, v157
	s_add_i32 s8, 0, 0x1c000
	ds_read_b128 v[162:165], v143
	ds_read_b128 v[166:169], v143 offset:1024
	ds_read_b128 v[170:173], v143 offset:2048
	ds_read_b128 v[174:177], v143 offset:3072
	v_add_u32_e32 v143, s8, v157
	ds_read_b128 v[178:181], v143
	ds_read_b128 v[182:185], v143 offset:1024
	ds_read_b128 v[186:189], v143 offset:2048
	ds_read_b128 v[190:193], v143 offset:3072
	s_add_u32 s20, s62, 0x40000
	s_addc_u32 s21, s63, 0
	s_mov_b32 m0, s67
	v_lshl_add_u64 v[246:247], s[20:21], 0, v[134:135]
	ds_read_b128 v[200:203], v161 offset:32768
	ds_read_b128 v[204:207], v161 offset:33792
	ds_read_b128 v[208:211], v161 offset:34816
	ds_read_b128 v[212:215], v161 offset:35840
	ds_read_b128 v[216:219], v161 offset:36864
	ds_read_b128 v[220:223], v161 offset:37888
	ds_read_b128 v[224:227], v161 offset:38912
	ds_read_b128 v[228:231], v161 offset:39936
	global_load_lds_dwordx4 v[246:247], off
	v_lshl_add_u64 v[246:247], s[20:21], 0, v[130:131]
	s_mov_b32 m0, s68
	s_nop 0
	global_load_lds_dwordx4 v[246:247], off
	s_waitcnt vmcnt(8)
	s_waitcnt lgkmcnt(0)
	s_barrier
	s_waitcnt lgkmcnt(0)
	v_mfma_f32_16x16x32_bf16 v[124:127], v[162:165], v[200:203], v[124:127]
	v_mfma_f32_16x16x32_bf16 v[120:123], v[170:173], v[200:203], v[120:123]
	v_mfma_f32_16x16x32_bf16 v[108:111], v[162:165], v[208:211], v[108:111]
	v_mfma_f32_16x16x32_bf16 v[104:107], v[170:173], v[208:211], v[104:107]
	v_mfma_f32_16x16x32_bf16 v[92:95], v[162:165], v[216:219], v[92:95]
	v_mfma_f32_16x16x32_bf16 v[88:91], v[170:173], v[216:219], v[88:91]
	v_mfma_f32_16x16x32_bf16 v[76:79], v[162:165], v[224:227], v[76:79]
	v_mfma_f32_16x16x32_bf16 v[72:75], v[170:173], v[224:227], v[72:75]
	v_mfma_f32_16x16x32_bf16 v[124:127], v[166:169], v[204:207], v[124:127]
	v_mfma_f32_16x16x32_bf16 v[120:123], v[174:177], v[204:207], v[120:123]
	v_mfma_f32_16x16x32_bf16 v[108:111], v[166:169], v[212:215], v[108:111]
	v_mfma_f32_16x16x32_bf16 v[104:107], v[174:177], v[212:215], v[104:107]
	v_mfma_f32_16x16x32_bf16 v[92:95], v[166:169], v[220:223], v[92:95]
	v_mfma_f32_16x16x32_bf16 v[88:91], v[174:177], v[220:223], v[88:91]
	v_mfma_f32_16x16x32_bf16 v[76:79], v[166:169], v[228:231], v[76:79]
	v_mfma_f32_16x16x32_bf16 v[72:75], v[174:177], v[228:231], v[72:75]
	v_mfma_f32_16x16x32_bf16 v[116:119], v[178:181], v[200:203], v[116:119]
	v_mfma_f32_16x16x32_bf16 v[112:115], v[186:189], v[200:203], v[112:115]
	v_mfma_f32_16x16x32_bf16 v[100:103], v[178:181], v[208:211], v[100:103]
	v_mfma_f32_16x16x32_bf16 v[96:99], v[186:189], v[208:211], v[96:99]
	v_mfma_f32_16x16x32_bf16 v[84:87], v[178:181], v[216:219], v[84:87]
	v_mfma_f32_16x16x32_bf16 v[80:83], v[186:189], v[216:219], v[80:83]
	v_mfma_f32_16x16x32_bf16 v[68:71], v[178:181], v[224:227], v[68:71]
	v_mfma_f32_16x16x32_bf16 v[64:67], v[186:189], v[224:227], v[64:67]
	v_mfma_f32_16x16x32_bf16 v[116:119], v[182:185], v[204:207], v[116:119]
	v_mfma_f32_16x16x32_bf16 v[112:115], v[190:193], v[204:207], v[112:115]
	v_mfma_f32_16x16x32_bf16 v[100:103], v[182:185], v[212:215], v[100:103]
	v_mfma_f32_16x16x32_bf16 v[96:99], v[190:193], v[212:215], v[96:99]
	v_mfma_f32_16x16x32_bf16 v[84:87], v[182:185], v[220:223], v[84:87]
	v_mfma_f32_16x16x32_bf16 v[80:83], v[190:193], v[220:223], v[80:83]
	v_mfma_f32_16x16x32_bf16 v[68:71], v[182:185], v[228:231], v[68:71]
	v_mfma_f32_16x16x32_bf16 v[64:67], v[190:193], v[228:231], v[64:67]
	s_barrier
; #define PG8_STAGE(bufoff, gbase, voff) do { _Pragma("unroll") for (int _i = 0; _i < 2; ++_i) \
;         __builtin_amdgcn_global_load_lds((const unsigned*)((const char*)(gbase) + (voff)[_i]), (PG8_LAS unsigned*)(lds + (bufoff) + ldsw + _i * 8192), 16, 0, 0); } while (0)
; #define PG8_LDA(dst, b, h) do { _Pragma("unroll") for (int m = 0; m < 4; ++m) _Pragma("unroll") for (int k = 0; k < 2; ++k) dst[m][k] = *(const PG8_LAS bf16x8*)(lds + PG8_SA(b, h) + aoff + m * 2048 + k * 1024); } while (0)
; #define PG8_MMA(ai, bj, At, Bt) do { __builtin_amdgcn_s_setprio(1); _Pragma("unroll") for (int m = 0; m < 4; ++m) _Pragma("unroll") for (int n = 0; n < 2; ++n) _Pragma("unroll") for (int k = 0; k < 2; ++k) \
;         acc[ai][bj][m][n] = __builtin_amdgcn_mfma_f32_16x16x32_bf16(Bt[n][k], At[m][k], acc[ai][bj][m][n], 0, 0, 0); __builtin_amdgcn_s_setprio(0); } while (0)
; #define PG8_WAIT_V(n) asm volatile("s_waitcnt vmcnt(" #n ")" ::: "memory")
; #define PG8_WAIT_L(n) asm volatile("s_waitcnt lgkmcnt(" #n ")" ::: "memory")
; #define PG8_BAR __builtin_amdgcn_s_barrier()
; #define PG8_SCHED __builtin_amdgcn_sched_barrier(0)
; template <class Epi, class Sched, bool ALIGN_EPI = false, bool SP2 = false>
; __device__ __forceinline__ void gemm_phase(PG8_LAS unsigned char* lds, const Gemm g, const Sched& S, const Epi& E) {
;     ...
;             PG8_LDA(At, 1, 1); PG8_STAGE(PG8_SB(1, 0), b3, voffB); PG8_STAGE(PG8_SB(1, 1), b3 + hstep, voffB); PG8_STAGE(PG8_SA(1, 0), a3, voffA);
;             PG8_WAIT_V(8); PG8_WAIT_L(0); PG8_BAR; PG8_MMA(1, 0, At, B0); PG8_MMA(1, 1, At, B1); PG8_BAR; PG8_SCHED;
	s_add_i32 s5, s5, s64
	v_lshl_add_u64 v[194:195], v[194:195], 0, s[22:23]
	s_mov_b32 m0, s5
	ds_read_b128 v[200:203], v161 offset:49152
	ds_read_b128 v[204:207], v161 offset:50176
	ds_read_b128 v[208:211], v161 offset:51200
	ds_read_b128 v[212:215], v161 offset:52224
	ds_read_b128 v[216:219], v161 offset:53248
	ds_read_b128 v[220:223], v161 offset:54272
	ds_read_b128 v[224:227], v161 offset:55296
	ds_read_b128 v[228:231], v161 offset:56320
	global_load_lds_dwordx4 v[194:195], off
	s_add_i32 m0, s5, 0x2000
	s_add_u32 s20, s60, 0x40080
	v_lshl_add_u64 v[194:195], v[240:241], 0, s[22:23]
	s_addc_u32 s21, s61, 0
	s_add_i32 s5, s8, s64
	global_load_lds_dwordx4 v[194:195], off
	v_lshl_add_u64 v[194:195], s[20:21], 0, v[132:133]
	s_mov_b32 m0, s5
	s_nop 0
	global_load_lds_dwordx4 v[194:195], off
	v_lshl_add_u64 v[194:195], s[20:21], 0, v[128:129]
	s_add_i32 m0, s5, 0x2000
	s_nop 0
	global_load_lds_dwordx4 v[194:195], off
	v_lshl_add_u64 v[194:195], v[242:243], 0, s[22:23]
	s_mov_b32 m0, s69
	s_nop 0
	global_load_lds_dwordx4 v[194:195], off
	v_lshl_add_u64 v[194:195], v[244:245], 0, s[22:23]
	s_mov_b32 m0, s70
	s_nop 0
	global_load_lds_dwordx4 v[194:195], off
	s_waitcnt vmcnt(8)
	s_waitcnt lgkmcnt(0)
	s_barrier
	s_waitcnt lgkmcnt(0)
	v_mfma_f32_16x16x32_bf16 v[60:63], v[162:165], v[200:203], v[60:63]
	v_mfma_f32_16x16x32_bf16 v[56:59], v[170:173], v[200:203], v[56:59]
	v_mfma_f32_16x16x32_bf16 v[44:47], v[162:165], v[208:211], v[44:47]
	v_mfma_f32_16x16x32_bf16 v[40:43], v[170:173], v[208:211], v[40:43]
	v_mfma_f32_16x16x32_bf16 v[28:31], v[162:165], v[216:219], v[28:31]
	v_mfma_f32_16x16x32_bf16 v[24:27], v[170:173], v[216:219], v[24:27]
	v_mfma_f32_16x16x32_bf16 v[12:15], v[162:165], v[224:227], v[12:15]
	v_mfma_f32_16x16x32_bf16 v[8:11], v[170:173], v[224:227], v[8:11]
	v_mfma_f32_16x16x32_bf16 v[60:63], v[166:169], v[204:207], v[60:63]
	v_mfma_f32_16x16x32_bf16 v[56:59], v[174:177], v[204:207], v[56:59]
	v_mfma_f32_16x16x32_bf16 v[44:47], v[166:169], v[212:215], v[44:47]
	v_mfma_f32_16x16x32_bf16 v[40:43], v[174:177], v[212:215], v[40:43]
	v_mfma_f32_16x16x32_bf16 v[28:31], v[166:169], v[220:223], v[28:31]
	v_mfma_f32_16x16x32_bf16 v[24:27], v[174:177], v[220:223], v[24:27]
	v_mfma_f32_16x16x32_bf16 v[12:15], v[166:169], v[228:231], v[12:15]
	v_mfma_f32_16x16x32_bf16 v[8:11], v[174:177], v[228:231], v[8:11]
	v_mfma_f32_16x16x32_bf16 v[52:55], v[178:181], v[200:203], v[52:55]
	v_mfma_f32_16x16x32_bf16 v[48:51], v[186:189], v[200:203], v[48:51]
	v_mfma_f32_16x16x32_bf16 v[36:39], v[178:181], v[208:211], v[36:39]
	v_mfma_f32_16x16x32_bf16 v[32:35], v[186:189], v[208:211], v[32:35]
	v_mfma_f32_16x16x32_bf16 v[20:23], v[178:181], v[216:219], v[20:23]
	v_mfma_f32_16x16x32_bf16 v[16:19], v[186:189], v[216:219], v[16:19]
	v_mfma_f32_16x16x32_bf16 v[4:7], v[178:181], v[224:227], v[4:7]
	v_mfma_f32_16x16x32_bf16 v[0:3], v[186:189], v[224:227], v[0:3]
	v_mfma_f32_16x16x32_bf16 v[52:55], v[182:185], v[204:207], v[52:55]
	v_mfma_f32_16x16x32_bf16 v[48:51], v[190:193], v[204:207], v[48:51]
	v_mfma_f32_16x16x32_bf16 v[36:39], v[182:185], v[212:215], v[36:39]
	v_mfma_f32_16x16x32_bf16 v[32:35], v[190:193], v[212:215], v[32:35]
	v_mfma_f32_16x16x32_bf16 v[20:23], v[182:185], v[220:223], v[20:23]
	v_mfma_f32_16x16x32_bf16 v[16:19], v[190:193], v[220:223], v[16:19]
	v_mfma_f32_16x16x32_bf16 v[4:7], v[182:185], v[228:231], v[4:7]
	v_mfma_f32_16x16x32_bf16 v[0:3], v[190:193], v[228:231], v[0:3]
	s_barrier
	s_add_i32 s72, s72, 2
	s_add_u32 s51, s51, 0x100
	s_addc_u32 s53, s53, 0
	s_add_u32 s58, s58, 0x100
	s_addc_u32 s59, s59, 0
	s_cmp_gt_u32 s72, 13
	s_cbranch_scc0 .LBB0_152
	s_and_b64 vcc, exec, s[48:49]
	s_cbranch_vccz .LBB0_155
	s_barrier

; #define PG8_STAGE(bufoff, gbase, voff) do { _Pragma("unroll") for (int _i = 0; _i < 2; ++_i) \
;         __builtin_amdgcn_global_load_lds((const unsigned*)((const char*)(gbase) + (voff)[_i]), (PG8_LAS unsigned*)(lds + (bufoff) + ldsw + _i * 8192), 16, 0, 0); } while (0)
; #define PG8_LDA(dst, b, h) do { _Pragma("unroll") for (int m = 0; m < 4; ++m) _Pragma("unroll") for (int k = 0; k < 2; ++k) dst[m][k] = *(const PG8_LAS bf16x8*)(lds + PG8_SA(b, h) + aoff + m * 2048 + k * 1024); } while (0)
; #define PG8_LDB(dst, b, h) do { _Pragma("unroll") for (int n = 0; n < 2; ++n) _Pragma("unroll") for (int k = 0; k < 2; ++k) dst[n][k] = *(const PG8_LAS bf16x8*)(lds + PG8_SB(b, h) + boff + n * 2048 + k * 1024); } while (0)
; #define PG8_MMA(ai, bj, At, Bt) do { __builtin_amdgcn_s_setprio(1); _Pragma("unroll") for (int m = 0; m < 4; ++m) _Pragma("unroll") for (int n = 0; n < 2; ++n) _Pragma("unroll") for (int k = 0; k < 2; ++k) \
;         acc[ai][bj][m][n] = __builtin_amdgcn_mfma_f32_16x16x32_bf16(Bt[n][k], At[m][k], acc[ai][bj][m][n], 0, 0, 0); __builtin_amdgcn_s_setprio(0); } while (0)
; #define PG8_WAIT_V(n) asm volatile("s_waitcnt vmcnt(" #n ")" ::: "memory")
; #define PG8_BAR __builtin_amdgcn_s_barrier()
; template <class Epi, class Sched, bool ALIGN_EPI = false, bool SP2 = false>
; __device__ __forceinline__ void gemm_phase(PG8_LAS unsigned char* lds, const Gemm g, const Sched& S, const Epi& E) {
;     ...
;         for (int t = 0; t < nt; t += 2) {
;             const bool last = (t == nt - 2);
;             const char* a1 = cA + (size_t)(t + 1) * kstep;
;             const char* a2 = last ? nA : cA + (size_t)(t + 2) * kstep; const char* b2 = last ? nB : cB + (size_t)(t + 2) * kstep;
;             const char* a3 = a2 + kstep; const char* b3 = b2 + kstep;
;             if (last && has_next) S.a_ready(nxt);
;             if constexpr (SP2) {
;             PG8_LDB(B0, 0, 0); PG8_LDB(B1, 0, 1); PG8_SCHED; PG8_LDA(At, 0, 0); PG8_STAGE(PG8_SA(1, 1), a1 + hstep, voffA);
;             PG8_WAIT_V(8); PG8_WAIT_L(0); PG8_BAR; PG8_MMA(0, 0, At, B0); PG8_MMA(0, 1, At, B1); PG8_BAR; PG8_SCHED;
;             PG8_LDA(At, 0, 1); PG8_STAGE(PG8_SB(0, 0), b2, voffB); PG8_STAGE(PG8_SB(0, 1), b2 + hstep, voffB); PG8_STAGE(PG8_SA(0, 0), a2, voffA);
;             PG8_WAIT_V(8); PG8_WAIT_L(0); PG8_BAR; PG8_MMA(1, 0, At, B0); PG8_MMA(1, 1, At, B1); PG8_BAR; PG8_SCHED;
.Lpeel_g2:
	s_add_u32 s5, s60, 0xfffc0080
	s_addc_u32 s8, s61, -1
	s_add_i32 s10, 0, 0x10000
	s_cmp_eq_u32 s74, 12
	s_cselect_b32 s65, s26, s8
	s_cselect_b32 s64, s27, s5
	s_cselect_b32 s63, s39, s73
	s_cselect_b32 s62, s53, s55
	s_add_i32 s5, 0, 0x14000
	v_add_u32_e32 v124, s10, v240
	v_add_u32_e32 v156, s5, v240
	ds_read_b128 v[112:115], v124
	ds_read_b128 v[116:119], v124 offset:1024
	ds_read_b128 v[120:123], v124 offset:2048
	ds_read_b128 v[124:127], v124 offset:3072
	ds_read_b128 v[136:139], v156
	ds_read_b128 v[140:143], v156 offset:1024
	ds_read_b128 v[152:155], v156 offset:2048
	ds_read_b128 v[156:159], v156 offset:3072
	v_lshl_add_u64 v[214:215], s[60:61], 0, v[208:209]
	s_add_i32 m0, s67, 0xc000
	ds_read_b128 v[164:167], v242
	ds_read_b128 v[172:175], v242 offset:1024
	ds_read_b128 v[176:179], v242 offset:2048
	ds_read_b128 v[180:183], v242 offset:3072
	ds_read_b128 v[184:187], v242 offset:4096
	ds_read_b128 v[188:191], v242 offset:5120
	ds_read_b128 v[192:195], v242 offset:6144
	ds_read_b128 v[210:213], v242 offset:7168
	global_load_lds_dwordx4 v[214:215], off
	v_lshl_add_u64 v[214:215], s[60:61], 0, v[206:207]
	s_add_i32 m0, s67, 0xe000
	s_nop 0
	global_load_lds_dwordx4 v[214:215], off
	s_waitcnt vmcnt(8)
	s_waitcnt lgkmcnt(0)
	s_barrier
	s_waitcnt lgkmcnt(0)
	v_mfma_f32_16x16x32_bf16 v[168:171], v[112:115], v[164:167], 0
	v_mfma_f32_16x16x32_bf16 v[160:163], v[120:123], v[164:167], 0
	v_mfma_f32_16x16x32_bf16 v[108:111], v[112:115], v[176:179], 0
	v_mfma_f32_16x16x32_bf16 v[104:107], v[120:123], v[176:179], 0
	v_mfma_f32_16x16x32_bf16 v[92:95], v[112:115], v[184:187], 0
	v_mfma_f32_16x16x32_bf16 v[88:91], v[120:123], v[184:187], 0
	v_mfma_f32_16x16x32_bf16 v[76:79], v[112:115], v[192:195], 0
	v_mfma_f32_16x16x32_bf16 v[72:75], v[120:123], v[192:195], 0
	v_mfma_f32_16x16x32_bf16 v[168:171], v[116:119], v[172:175], v[168:171]
	v_mfma_f32_16x16x32_bf16 v[160:163], v[124:127], v[172:175], v[160:163]
	v_mfma_f32_16x16x32_bf16 v[108:111], v[116:119], v[180:183], v[108:111]
	v_mfma_f32_16x16x32_bf16 v[104:107], v[124:127], v[180:183], v[104:107]
	v_mfma_f32_16x16x32_bf16 v[92:95], v[116:119], v[188:191], v[92:95]
	v_mfma_f32_16x16x32_bf16 v[88:91], v[124:127], v[188:191], v[88:91]
	v_mfma_f32_16x16x32_bf16 v[76:79], v[116:119], v[210:213], v[76:79]
	v_mfma_f32_16x16x32_bf16 v[72:75], v[124:127], v[210:213], v[72:75]
	v_mfma_f32_16x16x32_bf16 v[132:135], v[136:139], v[164:167], 0
	v_mfma_f32_16x16x32_bf16 v[128:131], v[152:155], v[164:167], 0
	v_mfma_f32_16x16x32_bf16 v[100:103], v[136:139], v[176:179], 0
	v_mfma_f32_16x16x32_bf16 v[96:99], v[152:155], v[176:179], 0
	v_mfma_f32_16x16x32_bf16 v[84:87], v[136:139], v[184:187], 0
	v_mfma_f32_16x16x32_bf16 v[80:83], v[152:155], v[184:187], 0
	v_mfma_f32_16x16x32_bf16 v[68:71], v[136:139], v[192:195], 0
	v_mfma_f32_16x16x32_bf16 v[64:67], v[152:155], v[192:195], 0
	v_mfma_f32_16x16x32_bf16 v[132:135], v[140:143], v[172:175], v[132:135]
	v_mfma_f32_16x16x32_bf16 v[128:131], v[156:159], v[172:175], v[128:131]
	v_mfma_f32_16x16x32_bf16 v[100:103], v[140:143], v[180:183], v[100:103]
	v_mfma_f32_16x16x32_bf16 v[96:99], v[156:159], v[180:183], v[96:99]
	v_mfma_f32_16x16x32_bf16 v[84:87], v[140:143], v[188:191], v[84:87]
	v_mfma_f32_16x16x32_bf16 v[80:83], v[156:159], v[188:191], v[80:83]
	v_mfma_f32_16x16x32_bf16 v[68:71], v[140:143], v[210:213], v[68:71]
	v_mfma_f32_16x16x32_bf16 v[64:67], v[156:159], v[210:213], v[64:67]
	s_barrier
	s_add_i32 s8, s10, s66
	v_lshl_add_u64 v[214:215], s[62:63], 0, v[202:203]
	s_mov_b32 m0, s8
	ds_read_b128 v[164:167], v242 offset:16384
	ds_read_b128 v[172:175], v242 offset:17408
	ds_read_b128 v[176:179], v242 offset:18432
	ds_read_b128 v[180:183], v242 offset:19456
	ds_read_b128 v[184:187], v242 offset:20480
	ds_read_b128 v[188:191], v242 offset:21504
	ds_read_b128 v[192:195], v242 offset:22528
	ds_read_b128 v[210:213], v242 offset:23552
	global_load_lds_dwordx4 v[214:215], off
	s_add_i32 m0, s8, 0x2000
	s_add_u32 s20, s62, 0x40000
	v_lshl_add_u64 v[216:217], s[62:63], 0, v[146:147]
	s_addc_u32 s21, s63, 0
	s_add_i32 s5, s5, s66
	global_load_lds_dwordx4 v[216:217], off
	v_lshl_add_u64 v[218:219], s[20:21], 0, v[202:203]
	s_mov_b32 m0, s5
	v_lshl_add_u64 v[220:221], s[64:65], 0, v[200:201]
	global_load_lds_dwordx4 v[218:219], off
	v_lshl_add_u64 v[218:219], s[20:21], 0, v[146:147]
	s_add_i32 m0, s5, 0x2000
	s_nop 0
	global_load_lds_dwordx4 v[218:219], off
	v_lshl_add_u64 v[218:219], s[64:65], 0, v[204:205]
	s_mov_b32 m0, s67
	s_nop 0
	global_load_lds_dwordx4 v[218:219], off
	s_mov_b32 m0, s68
	s_nop 0
	global_load_lds_dwordx4 v[220:221], off
	s_waitcnt vmcnt(8)
	s_waitcnt lgkmcnt(0)
	s_barrier
	s_waitcnt lgkmcnt(0)
	v_mfma_f32_16x16x32_bf16 v[60:63], v[112:115], v[164:167], 0
	v_mfma_f32_16x16x32_bf16 v[56:59], v[120:123], v[164:167], 0
	v_mfma_f32_16x16x32_bf16 v[44:47], v[112:115], v[176:179], 0
	v_mfma_f32_16x16x32_bf16 v[40:43], v[120:123], v[176:179], 0
	v_mfma_f32_16x16x32_bf16 v[28:31], v[112:115], v[184:187], 0
	v_mfma_f32_16x16x32_bf16 v[24:27], v[120:123], v[184:187], 0
	v_mfma_f32_16x16x32_bf16 v[12:15], v[112:115], v[192:195], 0
	v_mfma_f32_16x16x32_bf16 v[8:11], v[120:123], v[192:195], 0
	v_mfma_f32_16x16x32_bf16 v[60:63], v[116:119], v[172:175], v[60:63]
	v_mfma_f32_16x16x32_bf16 v[56:59], v[124:127], v[172:175], v[56:59]
	v_mfma_f32_16x16x32_bf16 v[44:47], v[116:119], v[180:183], v[44:47]
	v_mfma_f32_16x16x32_bf16 v[40:43], v[124:127], v[180:183], v[40:43]
	v_mfma_f32_16x16x32_bf16 v[28:31], v[116:119], v[188:191], v[28:31]
	v_mfma_f32_16x16x32_bf16 v[24:27], v[124:127], v[188:191], v[24:27]
	v_mfma_f32_16x16x32_bf16 v[12:15], v[116:119], v[210:213], v[12:15]
	v_mfma_f32_16x16x32_bf16 v[8:11], v[124:127], v[210:213], v[8:11]
	v_mfma_f32_16x16x32_bf16 v[52:55], v[136:139], v[164:167], 0
	v_mfma_f32_16x16x32_bf16 v[48:51], v[152:155], v[164:167], 0
	v_mfma_f32_16x16x32_bf16 v[36:39], v[136:139], v[176:179], 0
	v_mfma_f32_16x16x32_bf16 v[32:35], v[152:155], v[176:179], 0
	v_mfma_f32_16x16x32_bf16 v[20:23], v[136:139], v[184:187], 0
	v_mfma_f32_16x16x32_bf16 v[16:19], v[152:155], v[184:187], 0
	v_mfma_f32_16x16x32_bf16 v[4:7], v[136:139], v[192:195], 0
	v_mfma_f32_16x16x32_bf16 v[0:3], v[152:155], v[192:195], 0
	v_mfma_f32_16x16x32_bf16 v[52:55], v[140:143], v[172:175], v[52:55]
	v_mfma_f32_16x16x32_bf16 v[48:51], v[156:159], v[172:175], v[48:51]
	v_mfma_f32_16x16x32_bf16 v[36:39], v[140:143], v[180:183], v[36:39]
	v_mfma_f32_16x16x32_bf16 v[32:35], v[156:159], v[180:183], v[32:35]
	v_mfma_f32_16x16x32_bf16 v[20:23], v[140:143], v[188:191], v[20:23]
	v_mfma_f32_16x16x32_bf16 v[16:19], v[156:159], v[188:191], v[16:19]
	v_mfma_f32_16x16x32_bf16 v[4:7], v[140:143], v[210:213], v[4:7]
	v_mfma_f32_16x16x32_bf16 v[0:3], v[156:159], v[210:213], v[0:3]
	s_barrier
	s_branch .Lmid_g2

; #define PG8_STAGE(bufoff, gbase, voff) do { _Pragma("unroll") for (int _i = 0; _i < 2; ++_i) \
;         __builtin_amdgcn_global_load_lds((const unsigned*)((const char*)(gbase) + (voff)[_i]), (PG8_LAS unsigned*)(lds + (bufoff) + ldsw + _i * 8192), 16, 0, 0); } while (0)
; #define PG8_LDA(dst, b, h) do { _Pragma("unroll") for (int m = 0; m < 4; ++m) _Pragma("unroll") for (int k = 0; k < 2; ++k) dst[m][k] = *(const PG8_LAS bf16x8*)(lds + PG8_SA(b, h) + aoff + m * 2048 + k * 1024); } while (0)
; #define PG8_LDB(dst, b, h) do { _Pragma("unroll") for (int n = 0; n < 2; ++n) _Pragma("unroll") for (int k = 0; k < 2; ++k) dst[n][k] = *(const PG8_LAS bf16x8*)(lds + PG8_SB(b, h) + boff + n * 2048 + k * 1024); } while (0)
; #define PG8_MMA(ai, bj, At, Bt) do { __builtin_amdgcn_s_setprio(1); _Pragma("unroll") for (int m = 0; m < 4; ++m) _Pragma("unroll") for (int n = 0; n < 2; ++n) _Pragma("unroll") for (int k = 0; k < 2; ++k) \
;         acc[ai][bj][m][n] = __builtin_amdgcn_mfma_f32_16x16x32_bf16(Bt[n][k], At[m][k], acc[ai][bj][m][n], 0, 0, 0); __builtin_amdgcn_s_setprio(0); } while (0)
; #define PG8_WAIT_V(n) asm volatile("s_waitcnt vmcnt(" #n ")" ::: "memory")
; #define PG8_WAIT_L(n) asm volatile("s_waitcnt lgkmcnt(" #n ")" ::: "memory")
; #define PG8_BAR __builtin_amdgcn_s_barrier()
; #define PG8_SCHED __builtin_amdgcn_sched_barrier(0)
; template <class Epi, class Sched, bool ALIGN_EPI = false, bool SP2 = false>
; __device__ __forceinline__ void gemm_phase(PG8_LAS unsigned char* lds, const Gemm g, const Sched& S, const Epi& E) {
;     ...
;             PG8_LDB(B0, 0, 0); PG8_LDB(B1, 0, 1); PG8_SCHED; PG8_LDA(At, 0, 0); PG8_STAGE(PG8_SA(1, 1), a1 + hstep, voffA);
;             PG8_WAIT_V(8); PG8_WAIT_L(0); PG8_BAR; PG8_MMA(0, 0, At, B0); PG8_MMA(0, 1, At, B1); PG8_BAR; PG8_SCHED;
;             PG8_LDA(At, 0, 1); PG8_STAGE(PG8_SB(0, 0), b2, voffB); PG8_STAGE(PG8_SB(0, 1), b2 + hstep, voffB); PG8_STAGE(PG8_SA(0, 0), a2, voffA);
;             PG8_WAIT_V(8); PG8_WAIT_L(0); PG8_BAR; PG8_MMA(1, 0, At, B0); PG8_MMA(1, 1, At, B1); PG8_BAR; PG8_SCHED;
.LBB0_174:
	s_add_u32 s5, s60, 0xfffc0080
	s_addc_u32 s8, s61, -1
	s_add_i32 s10, 0, 0x10000
	s_cmp_eq_u32 s74, 12
	s_cselect_b32 s65, s26, s8
	s_cselect_b32 s64, s27, s5
	s_cselect_b32 s63, s39, s73
	s_cselect_b32 s62, s53, s55
	s_add_i32 s5, 0, 0x14000
	v_add_u32_e32 v124, s10, v240
	v_add_u32_e32 v156, s5, v240
	ds_read_b128 v[112:115], v124
	ds_read_b128 v[116:119], v124 offset:1024
	ds_read_b128 v[120:123], v124 offset:2048
	ds_read_b128 v[124:127], v124 offset:3072
	ds_read_b128 v[136:139], v156
	ds_read_b128 v[140:143], v156 offset:1024
	ds_read_b128 v[152:155], v156 offset:2048
	ds_read_b128 v[156:159], v156 offset:3072
	v_lshl_add_u64 v[214:215], s[60:61], 0, v[208:209]
	s_add_i32 m0, s67, 0xc000
	ds_read_b128 v[164:167], v242
	ds_read_b128 v[172:175], v242 offset:1024
	ds_read_b128 v[176:179], v242 offset:2048
	ds_read_b128 v[180:183], v242 offset:3072
	ds_read_b128 v[184:187], v242 offset:4096
	ds_read_b128 v[188:191], v242 offset:5120
	ds_read_b128 v[192:195], v242 offset:6144
	ds_read_b128 v[210:213], v242 offset:7168
	global_load_lds_dwordx4 v[214:215], off
	v_lshl_add_u64 v[214:215], s[60:61], 0, v[206:207]
	s_add_i32 m0, s67, 0xe000
	s_nop 0
	global_load_lds_dwordx4 v[214:215], off
	s_waitcnt vmcnt(8)
	s_waitcnt lgkmcnt(0)
	s_barrier
	s_waitcnt lgkmcnt(0)
	v_mfma_f32_16x16x32_bf16 v[168:171], v[112:115], v[164:167], v[168:171]
	v_mfma_f32_16x16x32_bf16 v[160:163], v[120:123], v[164:167], v[160:163]
	v_mfma_f32_16x16x32_bf16 v[108:111], v[112:115], v[176:179], v[108:111]
	v_mfma_f32_16x16x32_bf16 v[104:107], v[120:123], v[176:179], v[104:107]
	v_mfma_f32_16x16x32_bf16 v[92:95], v[112:115], v[184:187], v[92:95]
	v_mfma_f32_16x16x32_bf16 v[88:91], v[120:123], v[184:187], v[88:91]
	v_mfma_f32_16x16x32_bf16 v[76:79], v[112:115], v[192:195], v[76:79]
	v_mfma_f32_16x16x32_bf16 v[72:75], v[120:123], v[192:195], v[72:75]
	v_mfma_f32_16x16x32_bf16 v[168:171], v[116:119], v[172:175], v[168:171]
	v_mfma_f32_16x16x32_bf16 v[160:163], v[124:127], v[172:175], v[160:163]
	v_mfma_f32_16x16x32_bf16 v[108:111], v[116:119], v[180:183], v[108:111]
	v_mfma_f32_16x16x32_bf16 v[104:107], v[124:127], v[180:183], v[104:107]
	v_mfma_f32_16x16x32_bf16 v[92:95], v[116:119], v[188:191], v[92:95]
	v_mfma_f32_16x16x32_bf16 v[88:91], v[124:127], v[188:191], v[88:91]
	v_mfma_f32_16x16x32_bf16 v[76:79], v[116:119], v[210:213], v[76:79]
	v_mfma_f32_16x16x32_bf16 v[72:75], v[124:127], v[210:213], v[72:75]
	v_mfma_f32_16x16x32_bf16 v[132:135], v[136:139], v[164:167], v[132:135]
	v_mfma_f32_16x16x32_bf16 v[128:131], v[152:155], v[164:167], v[128:131]
	v_mfma_f32_16x16x32_bf16 v[100:103], v[136:139], v[176:179], v[100:103]
	v_mfma_f32_16x16x32_bf16 v[96:99], v[152:155], v[176:179], v[96:99]
	v_mfma_f32_16x16x32_bf16 v[84:87], v[136:139], v[184:187], v[84:87]
	v_mfma_f32_16x16x32_bf16 v[80:83], v[152:155], v[184:187], v[80:83]
	v_mfma_f32_16x16x32_bf16 v[68:71], v[136:139], v[192:195], v[68:71]
	v_mfma_f32_16x16x32_bf16 v[64:67], v[152:155], v[192:195], v[64:67]
	v_mfma_f32_16x16x32_bf16 v[132:135], v[140:143], v[172:175], v[132:135]
	v_mfma_f32_16x16x32_bf16 v[128:131], v[156:159], v[172:175], v[128:131]
	v_mfma_f32_16x16x32_bf16 v[100:103], v[140:143], v[180:183], v[100:103]
	v_mfma_f32_16x16x32_bf16 v[96:99], v[156:159], v[180:183], v[96:99]
	v_mfma_f32_16x16x32_bf16 v[84:87], v[140:143], v[188:191], v[84:87]
	v_mfma_f32_16x16x32_bf16 v[80:83], v[156:159], v[188:191], v[80:83]
	v_mfma_f32_16x16x32_bf16 v[68:71], v[140:143], v[210:213], v[68:71]
	v_mfma_f32_16x16x32_bf16 v[64:67], v[156:159], v[210:213], v[64:67]
	s_barrier
	s_add_i32 s8, s10, s66
	v_lshl_add_u64 v[214:215], s[62:63], 0, v[202:203]
	s_mov_b32 m0, s8
	ds_read_b128 v[164:167], v242 offset:16384
	ds_read_b128 v[172:175], v242 offset:17408
	ds_read_b128 v[176:179], v242 offset:18432
	ds_read_b128 v[180:183], v242 offset:19456
	ds_read_b128 v[184:187], v242 offset:20480
	ds_read_b128 v[188:191], v242 offset:21504
	ds_read_b128 v[192:195], v242 offset:22528
	ds_read_b128 v[210:213], v242 offset:23552
	global_load_lds_dwordx4 v[214:215], off
	s_add_i32 m0, s8, 0x2000
	s_add_u32 s20, s62, 0x40000
	v_lshl_add_u64 v[216:217], s[62:63], 0, v[146:147]
	s_addc_u32 s21, s63, 0
	s_add_i32 s5, s5, s66
	global_load_lds_dwordx4 v[216:217], off
	v_lshl_add_u64 v[218:219], s[20:21], 0, v[202:203]
	s_mov_b32 m0, s5
	v_lshl_add_u64 v[220:221], s[64:65], 0, v[200:201]
	global_load_lds_dwordx4 v[218:219], off
	v_lshl_add_u64 v[218:219], s[20:21], 0, v[146:147]
	s_add_i32 m0, s5, 0x2000
	s_nop 0
	global_load_lds_dwordx4 v[218:219], off
	v_lshl_add_u64 v[218:219], s[64:65], 0, v[204:205]
	s_mov_b32 m0, s67
	s_nop 0
	global_load_lds_dwordx4 v[218:219], off
	s_mov_b32 m0, s68
	s_nop 0
	global_load_lds_dwordx4 v[220:221], off
	s_waitcnt vmcnt(8)
	s_waitcnt lgkmcnt(0)
	s_barrier
	s_waitcnt lgkmcnt(0)
	v_mfma_f32_16x16x32_bf16 v[60:63], v[112:115], v[164:167], v[60:63]
	v_mfma_f32_16x16x32_bf16 v[56:59], v[120:123], v[164:167], v[56:59]
	v_mfma_f32_16x16x32_bf16 v[44:47], v[112:115], v[176:179], v[44:47]
	v_mfma_f32_16x16x32_bf16 v[40:43], v[120:123], v[176:179], v[40:43]
	v_mfma_f32_16x16x32_bf16 v[28:31], v[112:115], v[184:187], v[28:31]
	v_mfma_f32_16x16x32_bf16 v[24:27], v[120:123], v[184:187], v[24:27]
	v_mfma_f32_16x16x32_bf16 v[12:15], v[112:115], v[192:195], v[12:15]
	v_mfma_f32_16x16x32_bf16 v[8:11], v[120:123], v[192:195], v[8:11]
	v_mfma_f32_16x16x32_bf16 v[60:63], v[116:119], v[172:175], v[60:63]
	v_mfma_f32_16x16x32_bf16 v[56:59], v[124:127], v[172:175], v[56:59]
	v_mfma_f32_16x16x32_bf16 v[44:47], v[116:119], v[180:183], v[44:47]
	v_mfma_f32_16x16x32_bf16 v[40:43], v[124:127], v[180:183], v[40:43]
	v_mfma_f32_16x16x32_bf16 v[28:31], v[116:119], v[188:191], v[28:31]
	v_mfma_f32_16x16x32_bf16 v[24:27], v[124:127], v[188:191], v[24:27]
	v_mfma_f32_16x16x32_bf16 v[12:15], v[116:119], v[210:213], v[12:15]
	v_mfma_f32_16x16x32_bf16 v[8:11], v[124:127], v[210:213], v[8:11]
	v_mfma_f32_16x16x32_bf16 v[52:55], v[136:139], v[164:167], v[52:55]
	v_mfma_f32_16x16x32_bf16 v[48:51], v[152:155], v[164:167], v[48:51]
	v_mfma_f32_16x16x32_bf16 v[36:39], v[136:139], v[176:179], v[36:39]
	v_mfma_f32_16x16x32_bf16 v[32:35], v[152:155], v[176:179], v[32:35]
	v_mfma_f32_16x16x32_bf16 v[20:23], v[136:139], v[184:187], v[20:23]
	v_mfma_f32_16x16x32_bf16 v[16:19], v[152:155], v[184:187], v[16:19]
	v_mfma_f32_16x16x32_bf16 v[4:7], v[136:139], v[192:195], v[4:7]
	v_mfma_f32_16x16x32_bf16 v[0:3], v[152:155], v[192:195], v[0:3]
	v_mfma_f32_16x16x32_bf16 v[52:55], v[140:143], v[172:175], v[52:55]
	v_mfma_f32_16x16x32_bf16 v[48:51], v[156:159], v[172:175], v[48:51]
	v_mfma_f32_16x16x32_bf16 v[36:39], v[140:143], v[180:183], v[36:39]
	v_mfma_f32_16x16x32_bf16 v[32:35], v[156:159], v[180:183], v[32:35]
	v_mfma_f32_16x16x32_bf16 v[20:23], v[140:143], v[188:191], v[20:23]
	v_mfma_f32_16x16x32_bf16 v[16:19], v[156:159], v[188:191], v[16:19]
	v_mfma_f32_16x16x32_bf16 v[4:7], v[140:143], v[210:213], v[4:7]
	v_mfma_f32_16x16x32_bf16 v[0:3], v[156:159], v[210:213], v[0:3]
	s_barrier
; #define PG8_STAGE(bufoff, gbase, voff) do { _Pragma("unroll") for (int _i = 0; _i < 2; ++_i) \
;         __builtin_amdgcn_global_load_lds((const unsigned*)((const char*)(gbase) + (voff)[_i]), (PG8_LAS unsigned*)(lds + (bufoff) + ldsw + _i * 8192), 16, 0, 0); } while (0)
; #define PG8_LDA(dst, b, h) do { _Pragma("unroll") for (int m = 0; m < 4; ++m) _Pragma("unroll") for (int k = 0; k < 2; ++k) dst[m][k] = *(const PG8_LAS bf16x8*)(lds + PG8_SA(b, h) + aoff + m * 2048 + k * 1024); } while (0)
; #define PG8_LDB(dst, b, h) do { _Pragma("unroll") for (int n = 0; n < 2; ++n) _Pragma("unroll") for (int k = 0; k < 2; ++k) dst[n][k] = *(const PG8_LAS bf16x8*)(lds + PG8_SB(b, h) + boff + n * 2048 + k * 1024); } while (0)
; #define PG8_MMA(ai, bj, At, Bt) do { __builtin_amdgcn_s_setprio(1); _Pragma("unroll") for (int m = 0; m < 4; ++m) _Pragma("unroll") for (int n = 0; n < 2; ++n) _Pragma("unroll") for (int k = 0; k < 2; ++k) \
;         acc[ai][bj][m][n] = __builtin_amdgcn_mfma_f32_16x16x32_bf16(Bt[n][k], At[m][k], acc[ai][bj][m][n], 0, 0, 0); __builtin_amdgcn_s_setprio(0); } while (0)
; #define PG8_WAIT_V(n) asm volatile("s_waitcnt vmcnt(" #n ")" ::: "memory")
; #define PG8_WAIT_L(n) asm volatile("s_waitcnt lgkmcnt(" #n ")" ::: "memory")
; #define PG8_BAR __builtin_amdgcn_s_barrier()
; #define PG8_SCHED __builtin_amdgcn_sched_barrier(0)
; template <class Epi, class Sched, bool ALIGN_EPI = false, bool SP2 = false>
; __device__ __forceinline__ void gemm_phase(PG8_LAS unsigned char* lds, const Gemm g, const Sched& S, const Epi& E) {
;     ...
;             PG8_LDB(B0, 1, 0); PG8_LDB(B1, 1, 1); PG8_SCHED; PG8_LDA(At, 1, 0); PG8_STAGE(PG8_SA(0, 1), a2 + hstep, voffA);
;             PG8_WAIT_V(8); PG8_WAIT_L(0); PG8_BAR; PG8_MMA(0, 0, At, B0); PG8_MMA(0, 1, At, B1); PG8_BAR; PG8_SCHED;
.Lmid_g2:
	s_add_i32 s5, 0, 0x18000
	s_add_i32 s8, 0, 0x1c000
	v_add_u32_e32 v124, s5, v240
	v_add_u32_e32 v156, s8, v240
	ds_read_b128 v[112:115], v124
	ds_read_b128 v[116:119], v124 offset:1024
	ds_read_b128 v[120:123], v124 offset:2048
	ds_read_b128 v[124:127], v124 offset:3072
	ds_read_b128 v[136:139], v156
	ds_read_b128 v[140:143], v156 offset:1024
	ds_read_b128 v[152:155], v156 offset:2048
	ds_read_b128 v[156:159], v156 offset:3072
	s_add_u32 s20, s64, 0x40000
	s_addc_u32 s21, s65, 0
	s_mov_b32 m0, s69
	v_lshl_add_u64 v[222:223], s[20:21], 0, v[204:205]
	ds_read_b128 v[164:167], v242 offset:32768
	ds_read_b128 v[172:175], v242 offset:33792
	ds_read_b128 v[176:179], v242 offset:34816
	ds_read_b128 v[180:183], v242 offset:35840
	ds_read_b128 v[184:187], v242 offset:36864
	ds_read_b128 v[188:191], v242 offset:37888
	ds_read_b128 v[192:195], v242 offset:38912
	ds_read_b128 v[210:213], v242 offset:39936
	global_load_lds_dwordx4 v[222:223], off
	v_lshl_add_u64 v[222:223], s[20:21], 0, v[200:201]
	s_mov_b32 m0, s70
	s_nop 0
	global_load_lds_dwordx4 v[222:223], off
	s_waitcnt vmcnt(8)
	s_waitcnt lgkmcnt(0)
	s_barrier
	s_waitcnt lgkmcnt(0)
	v_mfma_f32_16x16x32_bf16 v[168:171], v[112:115], v[164:167], v[168:171]
	v_mfma_f32_16x16x32_bf16 v[160:163], v[120:123], v[164:167], v[160:163]
	v_mfma_f32_16x16x32_bf16 v[108:111], v[112:115], v[176:179], v[108:111]
	v_mfma_f32_16x16x32_bf16 v[104:107], v[120:123], v[176:179], v[104:107]
	v_mfma_f32_16x16x32_bf16 v[92:95], v[112:115], v[184:187], v[92:95]
	v_mfma_f32_16x16x32_bf16 v[88:91], v[120:123], v[184:187], v[88:91]
	v_mfma_f32_16x16x32_bf16 v[76:79], v[112:115], v[192:195], v[76:79]
	v_mfma_f32_16x16x32_bf16 v[72:75], v[120:123], v[192:195], v[72:75]
	v_mfma_f32_16x16x32_bf16 v[168:171], v[116:119], v[172:175], v[168:171]
	v_mfma_f32_16x16x32_bf16 v[160:163], v[124:127], v[172:175], v[160:163]
	v_mfma_f32_16x16x32_bf16 v[108:111], v[116:119], v[180:183], v[108:111]
	v_mfma_f32_16x16x32_bf16 v[104:107], v[124:127], v[180:183], v[104:107]
	v_mfma_f32_16x16x32_bf16 v[92:95], v[116:119], v[188:191], v[92:95]
	v_mfma_f32_16x16x32_bf16 v[88:91], v[124:127], v[188:191], v[88:91]
	v_mfma_f32_16x16x32_bf16 v[76:79], v[116:119], v[210:213], v[76:79]
	v_mfma_f32_16x16x32_bf16 v[72:75], v[124:127], v[210:213], v[72:75]
	v_mfma_f32_16x16x32_bf16 v[132:135], v[136:139], v[164:167], v[132:135]
	v_mfma_f32_16x16x32_bf16 v[128:131], v[152:155], v[164:167], v[128:131]
	v_mfma_f32_16x16x32_bf16 v[100:103], v[136:139], v[176:179], v[100:103]
	v_mfma_f32_16x16x32_bf16 v[96:99], v[152:155], v[176:179], v[96:99]
	v_mfma_f32_16x16x32_bf16 v[84:87], v[136:139], v[184:187], v[84:87]
	v_mfma_f32_16x16x32_bf16 v[80:83], v[152:155], v[184:187], v[80:83]
	v_mfma_f32_16x16x32_bf16 v[68:71], v[136:139], v[192:195], v[68:71]
	v_mfma_f32_16x16x32_bf16 v[64:67], v[152:155], v[192:195], v[64:67]
	v_mfma_f32_16x16x32_bf16 v[132:135], v[140:143], v[172:175], v[132:135]
	v_mfma_f32_16x16x32_bf16 v[128:131], v[156:159], v[172:175], v[128:131]
	v_mfma_f32_16x16x32_bf16 v[100:103], v[140:143], v[180:183], v[100:103]
	v_mfma_f32_16x16x32_bf16 v[96:99], v[156:159], v[180:183], v[96:99]
	v_mfma_f32_16x16x32_bf16 v[84:87], v[140:143], v[188:191], v[84:87]
	v_mfma_f32_16x16x32_bf16 v[80:83], v[156:159], v[188:191], v[80:83]
	v_mfma_f32_16x16x32_bf16 v[68:71], v[140:143], v[210:213], v[68:71]
	v_mfma_f32_16x16x32_bf16 v[64:67], v[156:159], v[210:213], v[64:67]
	s_barrier
; #define PG8_STAGE(bufoff, gbase, voff) do { _Pragma("unroll") for (int _i = 0; _i < 2; ++_i) \
;         __builtin_amdgcn_global_load_lds((const unsigned*)((const char*)(gbase) + (voff)[_i]), (PG8_LAS unsigned*)(lds + (bufoff) + ldsw + _i * 8192), 16, 0, 0); } while (0)
; #define PG8_LDA(dst, b, h) do { _Pragma("unroll") for (int m = 0; m < 4; ++m) _Pragma("unroll") for (int k = 0; k < 2; ++k) dst[m][k] = *(const PG8_LAS bf16x8*)(lds + PG8_SA(b, h) + aoff + m * 2048 + k * 1024); } while (0)
; #define PG8_MMA(ai, bj, At, Bt) do { __builtin_amdgcn_s_setprio(1); _Pragma("unroll") for (int m = 0; m < 4; ++m) _Pragma("unroll") for (int n = 0; n < 2; ++n) _Pragma("unroll") for (int k = 0; k < 2; ++k) \
;         acc[ai][bj][m][n] = __builtin_amdgcn_mfma_f32_16x16x32_bf16(Bt[n][k], At[m][k], acc[ai][bj][m][n], 0, 0, 0); __builtin_amdgcn_s_setprio(0); } while (0)
; #define PG8_WAIT_V(n) asm volatile("s_waitcnt vmcnt(" #n ")" ::: "memory")
; #define PG8_WAIT_L(n) asm volatile("s_waitcnt lgkmcnt(" #n ")" ::: "memory")
; #define PG8_BAR __builtin_amdgcn_s_barrier()
; #define PG8_SCHED __builtin_amdgcn_sched_barrier(0)
; template <class Epi, class Sched, bool ALIGN_EPI = false, bool SP2 = false>
; __device__ __forceinline__ void gemm_phase(PG8_LAS unsigned char* lds, const Gemm g, const Sched& S, const Epi& E) {
;     ...
;             PG8_LDA(At, 1, 1); PG8_STAGE(PG8_SB(1, 0), b3, voffB); PG8_STAGE(PG8_SB(1, 1), b3 + hstep, voffB); PG8_STAGE(PG8_SA(1, 0), a3, voffA);
;             PG8_WAIT_V(8); PG8_WAIT_L(0); PG8_BAR; PG8_MMA(1, 0, At, B0); PG8_MMA(1, 1, At, B1); PG8_BAR; PG8_SCHED;
	s_add_i32 s5, s5, s66
	v_lshl_add_u64 v[214:215], v[214:215], 0, s[22:23]
	s_mov_b32 m0, s5
	ds_read_b128 v[164:167], v242 offset:49152
	ds_read_b128 v[172:175], v242 offset:50176
	ds_read_b128 v[176:179], v242 offset:51200
	ds_read_b128 v[180:183], v242 offset:52224
	ds_read_b128 v[184:187], v242 offset:53248
	ds_read_b128 v[188:191], v242 offset:54272
	ds_read_b128 v[192:195], v242 offset:55296
	ds_read_b128 v[210:213], v242 offset:56320
	global_load_lds_dwordx4 v[214:215], off
	s_add_i32 m0, s5, 0x2000
	s_add_u32 s20, s62, 0x40080
	v_lshl_add_u64 v[214:215], v[216:217], 0, s[22:23]
	s_addc_u32 s21, s63, 0
	s_add_i32 s5, s8, s66
	global_load_lds_dwordx4 v[214:215], off
	v_lshl_add_u64 v[214:215], s[20:21], 0, v[202:203]
	s_mov_b32 m0, s5
	s_nop 0
	global_load_lds_dwordx4 v[214:215], off
	v_lshl_add_u64 v[214:215], s[20:21], 0, v[146:147]
	s_add_i32 m0, s5, 0x2000
	s_nop 0
	global_load_lds_dwordx4 v[214:215], off
	v_lshl_add_u64 v[214:215], v[218:219], 0, s[22:23]
	s_mov_b32 m0, s34
	s_nop 0
	global_load_lds_dwordx4 v[214:215], off
	v_lshl_add_u64 v[214:215], v[220:221], 0, s[22:23]
	s_mov_b32 m0, s71
	s_nop 0
	global_load_lds_dwordx4 v[214:215], off
	s_waitcnt vmcnt(8)
	s_waitcnt lgkmcnt(0)
	s_barrier
	s_waitcnt lgkmcnt(0)
	v_mfma_f32_16x16x32_bf16 v[60:63], v[112:115], v[164:167], v[60:63]
	v_mfma_f32_16x16x32_bf16 v[56:59], v[120:123], v[164:167], v[56:59]
	v_mfma_f32_16x16x32_bf16 v[44:47], v[112:115], v[176:179], v[44:47]
	v_mfma_f32_16x16x32_bf16 v[40:43], v[120:123], v[176:179], v[40:43]
	v_mfma_f32_16x16x32_bf16 v[28:31], v[112:115], v[184:187], v[28:31]
	v_mfma_f32_16x16x32_bf16 v[24:27], v[120:123], v[184:187], v[24:27]
	v_mfma_f32_16x16x32_bf16 v[12:15], v[112:115], v[192:195], v[12:15]
	v_mfma_f32_16x16x32_bf16 v[8:11], v[120:123], v[192:195], v[8:11]
	v_mfma_f32_16x16x32_bf16 v[60:63], v[116:119], v[172:175], v[60:63]
	v_mfma_f32_16x16x32_bf16 v[56:59], v[124:127], v[172:175], v[56:59]
	v_mfma_f32_16x16x32_bf16 v[44:47], v[116:119], v[180:183], v[44:47]
	v_mfma_f32_16x16x32_bf16 v[40:43], v[124:127], v[180:183], v[40:43]
	v_mfma_f32_16x16x32_bf16 v[28:31], v[116:119], v[188:191], v[28:31]
	v_mfma_f32_16x16x32_bf16 v[24:27], v[124:127], v[188:191], v[24:27]
	v_mfma_f32_16x16x32_bf16 v[12:15], v[116:119], v[210:213], v[12:15]
	v_mfma_f32_16x16x32_bf16 v[8:11], v[124:127], v[210:213], v[8:11]
	v_mfma_f32_16x16x32_bf16 v[52:55], v[136:139], v[164:167], v[52:55]
	v_mfma_f32_16x16x32_bf16 v[48:51], v[152:155], v[164:167], v[48:51]
	v_mfma_f32_16x16x32_bf16 v[36:39], v[136:139], v[176:179], v[36:39]
	v_mfma_f32_16x16x32_bf16 v[32:35], v[152:155], v[176:179], v[32:35]
	v_mfma_f32_16x16x32_bf16 v[20:23], v[136:139], v[184:187], v[20:23]
	v_mfma_f32_16x16x32_bf16 v[16:19], v[152:155], v[184:187], v[16:19]
	v_mfma_f32_16x16x32_bf16 v[4:7], v[136:139], v[192:195], v[4:7]
	v_mfma_f32_16x16x32_bf16 v[0:3], v[152:155], v[192:195], v[0:3]
	v_mfma_f32_16x16x32_bf16 v[52:55], v[140:143], v[172:175], v[52:55]
	v_mfma_f32_16x16x32_bf16 v[48:51], v[156:159], v[172:175], v[48:51]
	v_mfma_f32_16x16x32_bf16 v[36:39], v[140:143], v[180:183], v[36:39]
	v_mfma_f32_16x16x32_bf16 v[32:35], v[156:159], v[180:183], v[32:35]
	v_mfma_f32_16x16x32_bf16 v[20:23], v[140:143], v[188:191], v[20:23]
	v_mfma_f32_16x16x32_bf16 v[16:19], v[156:159], v[188:191], v[16:19]
	v_mfma_f32_16x16x32_bf16 v[4:7], v[140:143], v[210:213], v[4:7]
	v_mfma_f32_16x16x32_bf16 v[0:3], v[156:159], v[210:213], v[0:3]
	s_barrier
	s_add_i32 s74, s74, 2
	s_add_u32 s55, s55, 0x100
	s_addc_u32 s73, s73, 0
	s_add_u32 s60, s60, 0x100
	s_addc_u32 s61, s61, 0
	s_cmp_gt_u32 s74, 13
	s_cbranch_scc0 .LBB0_174
	s_and_b64 vcc, exec, s[50:51]
	s_cbranch_vccz .LBB0_177
	s_barrier

; #define PG8_STAGE(bufoff, gbase, voff) do { _Pragma("unroll") for (int _i = 0; _i < 2; ++_i) \
;         __builtin_amdgcn_global_load_lds((const unsigned*)((const char*)(gbase) + (voff)[_i]), (PG8_LAS unsigned*)(lds + (bufoff) + ldsw + _i * 8192), 16, 0, 0); } while (0)
; #define PG8_LDA(dst, b, h) do { _Pragma("unroll") for (int m = 0; m < 4; ++m) _Pragma("unroll") for (int k = 0; k < 2; ++k) dst[m][k] = *(const PG8_LAS bf16x8*)(lds + PG8_SA(b, h) + aoff + m * 2048 + k * 1024); } while (0)
; #define PG8_LDB(dst, b, h) do { _Pragma("unroll") for (int n = 0; n < 2; ++n) _Pragma("unroll") for (int k = 0; k < 2; ++k) dst[n][k] = *(const PG8_LAS bf16x8*)(lds + PG8_SB(b, h) + boff + n * 2048 + k * 1024); } while (0)
; #define PG8_MMA(ai, bj, At, Bt) do { __builtin_amdgcn_s_setprio(1); _Pragma("unroll") for (int m = 0; m < 4; ++m) _Pragma("unroll") for (int n = 0; n < 2; ++n) _Pragma("unroll") for (int k = 0; k < 2; ++k) \
;         acc[ai][bj][m][n] = __builtin_amdgcn_mfma_f32_16x16x32_bf16(Bt[n][k], At[m][k], acc[ai][bj][m][n], 0, 0, 0); __builtin_amdgcn_s_setprio(0); } while (0)
; #define PG8_WAIT_V(n) asm volatile("s_waitcnt vmcnt(" #n ")" ::: "memory")
; #define PG8_BAR __builtin_amdgcn_s_barrier()
; template <class Epi, class Sched, bool ALIGN_EPI = false, bool SP2 = false>
; __device__ __forceinline__ void gemm_phase(PG8_LAS unsigned char* lds, const Gemm g, const Sched& S, const Epi& E) {
;     ...
;         for (int t = 0; t < nt; t += 2) {
;             const bool last = (t == nt - 2);
;             const char* a1 = cA + (size_t)(t + 1) * kstep;
;             const char* a2 = last ? nA : cA + (size_t)(t + 2) * kstep; const char* b2 = last ? nB : cB + (size_t)(t + 2) * kstep;
;             const char* a3 = a2 + kstep; const char* b3 = b2 + kstep;
;             if (last && has_next) S.a_ready(nxt);
;             if constexpr (SP2) {
;             PG8_LDB(B0, 0, 0); PG8_LDB(B1, 0, 1); PG8_SCHED; PG8_LDA(At, 0, 0); PG8_STAGE(PG8_SA(1, 1), a1 + hstep, voffA);
;             PG8_WAIT_V(8); PG8_WAIT_L(0); PG8_BAR; PG8_MMA(0, 0, At, B0); PG8_MMA(0, 1, At, B1); PG8_BAR; PG8_SCHED;
;             PG8_LDA(At, 0, 1); PG8_STAGE(PG8_SB(0, 0), b2, voffB); PG8_STAGE(PG8_SB(0, 1), b2 + hstep, voffB); PG8_STAGE(PG8_SA(0, 0), a2, voffA);
;             PG8_WAIT_V(8); PG8_WAIT_L(0); PG8_BAR; PG8_MMA(1, 0, At, B0); PG8_MMA(1, 1, At, B1); PG8_BAR; PG8_SCHED;
.Lpeel_g1e:
	s_add_u32 s8, s44, 0xfffc0080
	s_addc_u32 s10, s45, -1
	s_add_i32 s12, 0, 0x10000
	s_cmp_eq_u32 s69, 12
	s_cselect_b32 s57, s4, s10
	s_cselect_b32 s56, s26, s8
	v_add_u32_e32 v154, s12, v157
	s_cselect_b32 s55, s27, s49
	s_cselect_b32 s54, s36, s47
	s_add_i32 s8, 0, 0x14000
	ds_read_b128 v[162:165], v154
	ds_read_b128 v[166:169], v154 offset:1024
	ds_read_b128 v[170:173], v154 offset:2048
	ds_read_b128 v[174:177], v154 offset:3072
	v_add_u32_e32 v154, s8, v157
	ds_read_b128 v[178:181], v154
	ds_read_b128 v[182:185], v154 offset:1024
	ds_read_b128 v[186:189], v154 offset:2048
	ds_read_b128 v[190:193], v154 offset:3072
	v_lshl_add_u64 v[194:195], s[44:45], 0, v[140:141]
	s_add_i32 m0, s58, 0xc000
	ds_read_b128 v[200:203], v161
	ds_read_b128 v[204:207], v161 offset:1024
	ds_read_b128 v[208:211], v161 offset:2048
	ds_read_b128 v[212:215], v161 offset:3072
	ds_read_b128 v[216:219], v161 offset:4096
	ds_read_b128 v[220:223], v161 offset:5120
	ds_read_b128 v[224:227], v161 offset:6144
	ds_read_b128 v[228:231], v161 offset:7168
	global_load_lds_dwordx4 v[194:195], off
	v_lshl_add_u64 v[194:195], s[44:45], 0, v[138:139]
	s_add_i32 m0, s58, 0xe000
	s_nop 0
	global_load_lds_dwordx4 v[194:195], off
	s_waitcnt vmcnt(10)
	s_waitcnt lgkmcnt(0)
	s_barrier
	s_waitcnt lgkmcnt(0)
	v_mfma_f32_16x16x32_bf16 v[124:127], v[162:165], v[200:203], 0
	v_mfma_f32_16x16x32_bf16 v[120:123], v[170:173], v[200:203], 0
	v_mfma_f32_16x16x32_bf16 v[108:111], v[162:165], v[208:211], 0
	v_mfma_f32_16x16x32_bf16 v[104:107], v[170:173], v[208:211], 0
	v_mfma_f32_16x16x32_bf16 v[92:95], v[162:165], v[216:219], 0
	v_mfma_f32_16x16x32_bf16 v[88:91], v[170:173], v[216:219], 0
	v_mfma_f32_16x16x32_bf16 v[76:79], v[162:165], v[224:227], 0
	v_mfma_f32_16x16x32_bf16 v[72:75], v[170:173], v[224:227], 0
	v_mfma_f32_16x16x32_bf16 v[124:127], v[166:169], v[204:207], v[124:127]
	v_mfma_f32_16x16x32_bf16 v[120:123], v[174:177], v[204:207], v[120:123]
	v_mfma_f32_16x16x32_bf16 v[108:111], v[166:169], v[212:215], v[108:111]
	v_mfma_f32_16x16x32_bf16 v[104:107], v[174:177], v[212:215], v[104:107]
	v_mfma_f32_16x16x32_bf16 v[92:95], v[166:169], v[220:223], v[92:95]
	v_mfma_f32_16x16x32_bf16 v[88:91], v[174:177], v[220:223], v[88:91]
	v_mfma_f32_16x16x32_bf16 v[76:79], v[166:169], v[228:231], v[76:79]
	v_mfma_f32_16x16x32_bf16 v[72:75], v[174:177], v[228:231], v[72:75]
	v_mfma_f32_16x16x32_bf16 v[116:119], v[178:181], v[200:203], 0
	v_mfma_f32_16x16x32_bf16 v[112:115], v[186:189], v[200:203], 0
	v_mfma_f32_16x16x32_bf16 v[100:103], v[178:181], v[208:211], 0
	v_mfma_f32_16x16x32_bf16 v[96:99], v[186:189], v[208:211], 0
	v_mfma_f32_16x16x32_bf16 v[84:87], v[178:181], v[216:219], 0
	v_mfma_f32_16x16x32_bf16 v[80:83], v[186:189], v[216:219], 0
	v_mfma_f32_16x16x32_bf16 v[68:71], v[178:181], v[224:227], 0
	v_mfma_f32_16x16x32_bf16 v[64:67], v[186:189], v[224:227], 0
	v_mfma_f32_16x16x32_bf16 v[116:119], v[182:185], v[204:207], v[116:119]
	v_mfma_f32_16x16x32_bf16 v[112:115], v[190:193], v[204:207], v[112:115]
	v_mfma_f32_16x16x32_bf16 v[100:103], v[182:185], v[212:215], v[100:103]
	v_mfma_f32_16x16x32_bf16 v[96:99], v[190:193], v[212:215], v[96:99]
	v_mfma_f32_16x16x32_bf16 v[84:87], v[182:185], v[220:223], v[84:87]
	v_mfma_f32_16x16x32_bf16 v[80:83], v[190:193], v[220:223], v[80:83]
	v_mfma_f32_16x16x32_bf16 v[68:71], v[182:185], v[228:231], v[68:71]
	v_mfma_f32_16x16x32_bf16 v[64:67], v[190:193], v[228:231], v[64:67]
	s_barrier
	s_add_i32 s10, s12, s39
	v_lshl_add_u64 v[194:195], s[54:55], 0, v[132:133]
	s_mov_b32 m0, s10
	ds_read_b128 v[200:203], v161 offset:16384
	ds_read_b128 v[204:207], v161 offset:17408
	ds_read_b128 v[208:211], v161 offset:18432
	ds_read_b128 v[212:215], v161 offset:19456
	ds_read_b128 v[216:219], v161 offset:20480
	ds_read_b128 v[220:223], v161 offset:21504
	ds_read_b128 v[224:227], v161 offset:22528
	ds_read_b128 v[228:231], v161 offset:23552
	global_load_lds_dwordx4 v[194:195], off
	s_add_i32 m0, s10, 0x2000
	s_add_u32 s70, s54, 0x40000
	v_lshl_add_u64 v[240:241], s[54:55], 0, v[128:129]
	s_addc_u32 s71, s55, 0
	s_add_i32 s8, s8, s39
	global_load_lds_dwordx4 v[240:241], off
	v_lshl_add_u64 v[242:243], s[70:71], 0, v[132:133]
	s_mov_b32 m0, s8
	v_lshl_add_u64 v[244:245], s[56:57], 0, v[130:131]
	global_load_lds_dwordx4 v[242:243], off
	v_lshl_add_u64 v[242:243], s[70:71], 0, v[128:129]
	s_add_i32 m0, s8, 0x2000
	s_nop 0
	global_load_lds_dwordx4 v[242:243], off
	v_lshl_add_u64 v[242:243], s[56:57], 0, v[134:135]
	s_mov_b32 m0, s58
	s_nop 0
	global_load_lds_dwordx4 v[242:243], off
	s_mov_b32 m0, s59
	s_nop 0
	global_load_lds_dwordx4 v[244:245], off
	s_waitcnt vmcnt(10)
	s_waitcnt lgkmcnt(0)
	s_barrier
	s_waitcnt lgkmcnt(0)
	v_mfma_f32_16x16x32_bf16 v[60:63], v[162:165], v[200:203], 0
	v_mfma_f32_16x16x32_bf16 v[56:59], v[170:173], v[200:203], 0
	v_mfma_f32_16x16x32_bf16 v[44:47], v[162:165], v[208:211], 0
	v_mfma_f32_16x16x32_bf16 v[40:43], v[170:173], v[208:211], 0
	v_mfma_f32_16x16x32_bf16 v[28:31], v[162:165], v[216:219], 0
	v_mfma_f32_16x16x32_bf16 v[24:27], v[170:173], v[216:219], 0
	v_mfma_f32_16x16x32_bf16 v[12:15], v[162:165], v[224:227], 0
	v_mfma_f32_16x16x32_bf16 v[8:11], v[170:173], v[224:227], 0
	v_mfma_f32_16x16x32_bf16 v[60:63], v[166:169], v[204:207], v[60:63]
	v_mfma_f32_16x16x32_bf16 v[56:59], v[174:177], v[204:207], v[56:59]
	v_mfma_f32_16x16x32_bf16 v[44:47], v[166:169], v[212:215], v[44:47]
	v_mfma_f32_16x16x32_bf16 v[40:43], v[174:177], v[212:215], v[40:43]
	v_mfma_f32_16x16x32_bf16 v[28:31], v[166:169], v[220:223], v[28:31]
	v_mfma_f32_16x16x32_bf16 v[24:27], v[174:177], v[220:223], v[24:27]
	v_mfma_f32_16x16x32_bf16 v[12:15], v[166:169], v[228:231], v[12:15]
	v_mfma_f32_16x16x32_bf16 v[8:11], v[174:177], v[228:231], v[8:11]
	v_mfma_f32_16x16x32_bf16 v[52:55], v[178:181], v[200:203], 0
	v_mfma_f32_16x16x32_bf16 v[48:51], v[186:189], v[200:203], 0
	v_mfma_f32_16x16x32_bf16 v[36:39], v[178:181], v[208:211], 0
	v_mfma_f32_16x16x32_bf16 v[32:35], v[186:189], v[208:211], 0
	v_mfma_f32_16x16x32_bf16 v[20:23], v[178:181], v[216:219], 0
	v_mfma_f32_16x16x32_bf16 v[16:19], v[186:189], v[216:219], 0
	v_mfma_f32_16x16x32_bf16 v[4:7], v[178:181], v[224:227], 0
	v_mfma_f32_16x16x32_bf16 v[0:3], v[186:189], v[224:227], 0
	v_mfma_f32_16x16x32_bf16 v[52:55], v[182:185], v[204:207], v[52:55]
	v_mfma_f32_16x16x32_bf16 v[48:51], v[190:193], v[204:207], v[48:51]
	v_mfma_f32_16x16x32_bf16 v[36:39], v[182:185], v[212:215], v[36:39]
	v_mfma_f32_16x16x32_bf16 v[32:35], v[190:193], v[212:215], v[32:35]
	v_mfma_f32_16x16x32_bf16 v[20:23], v[182:185], v[220:223], v[20:23]
	v_mfma_f32_16x16x32_bf16 v[16:19], v[190:193], v[220:223], v[16:19]
	v_mfma_f32_16x16x32_bf16 v[4:7], v[182:185], v[228:231], v[4:7]
	v_mfma_f32_16x16x32_bf16 v[0:3], v[190:193], v[228:231], v[0:3]
	s_barrier
	s_branch .Lmid_g1e

; #define PG8_STAGE(bufoff, gbase, voff) do { _Pragma("unroll") for (int _i = 0; _i < 2; ++_i) \
;         __builtin_amdgcn_global_load_lds((const unsigned*)((const char*)(gbase) + (voff)[_i]), (PG8_LAS unsigned*)(lds + (bufoff) + ldsw + _i * 8192), 16, 0, 0); } while (0)
; #define PG8_LDA(dst, b, h) do { _Pragma("unroll") for (int m = 0; m < 4; ++m) _Pragma("unroll") for (int k = 0; k < 2; ++k) dst[m][k] = *(const PG8_LAS bf16x8*)(lds + PG8_SA(b, h) + aoff + m * 2048 + k * 1024); } while (0)
; #define PG8_LDB(dst, b, h) do { _Pragma("unroll") for (int n = 0; n < 2; ++n) _Pragma("unroll") for (int k = 0; k < 2; ++k) dst[n][k] = *(const PG8_LAS bf16x8*)(lds + PG8_SB(b, h) + boff + n * 2048 + k * 1024); } while (0)
; #define PG8_MMA(ai, bj, At, Bt) do { __builtin_amdgcn_s_setprio(1); _Pragma("unroll") for (int m = 0; m < 4; ++m) _Pragma("unroll") for (int n = 0; n < 2; ++n) _Pragma("unroll") for (int k = 0; k < 2; ++k) \
;         acc[ai][bj][m][n] = __builtin_amdgcn_mfma_f32_16x16x32_bf16(Bt[n][k], At[m][k], acc[ai][bj][m][n], 0, 0, 0); __builtin_amdgcn_s_setprio(0); } while (0)
; #define PG8_WAIT_V(n) asm volatile("s_waitcnt vmcnt(" #n ")" ::: "memory")
; #define PG8_WAIT_L(n) asm volatile("s_waitcnt lgkmcnt(" #n ")" ::: "memory")
; #define PG8_BAR __builtin_amdgcn_s_barrier()
; #define PG8_SCHED __builtin_amdgcn_sched_barrier(0)
; template <class Epi, class Sched, bool ALIGN_EPI = false, bool SP2 = false>
; __device__ __forceinline__ void gemm_phase(PG8_LAS unsigned char* lds, const Gemm g, const Sched& S, const Epi& E) {
;     ...
;             PG8_LDB(B0, 0, 0); PG8_LDB(B1, 0, 1); PG8_SCHED; PG8_LDA(At, 0, 0); PG8_STAGE(PG8_SA(1, 1), a1 + hstep, voffA);
;             PG8_WAIT_V(8); PG8_WAIT_L(0); PG8_BAR; PG8_MMA(0, 0, At, B0); PG8_MMA(0, 1, At, B1); PG8_BAR; PG8_SCHED;
;             PG8_LDA(At, 0, 1); PG8_STAGE(PG8_SB(0, 0), b2, voffB); PG8_STAGE(PG8_SB(0, 1), b2 + hstep, voffB); PG8_STAGE(PG8_SA(0, 0), a2, voffA);
;             PG8_WAIT_V(8); PG8_WAIT_L(0); PG8_BAR; PG8_MMA(1, 0, At, B0); PG8_MMA(1, 1, At, B1); PG8_BAR; PG8_SCHED;
.LBB0_414:
	s_add_u32 s8, s44, 0xfffc0080
	s_addc_u32 s10, s45, -1
	s_add_i32 s12, 0, 0x10000
	s_cmp_eq_u32 s69, 12
	s_cselect_b32 s57, s4, s10
	s_cselect_b32 s56, s26, s8
	v_add_u32_e32 v154, s12, v157
	s_cselect_b32 s55, s27, s49
	s_cselect_b32 s54, s36, s47
	s_add_i32 s8, 0, 0x14000
	ds_read_b128 v[162:165], v154
	ds_read_b128 v[166:169], v154 offset:1024
	ds_read_b128 v[170:173], v154 offset:2048
	ds_read_b128 v[174:177], v154 offset:3072
	v_add_u32_e32 v154, s8, v157
	ds_read_b128 v[178:181], v154
	ds_read_b128 v[182:185], v154 offset:1024
	ds_read_b128 v[186:189], v154 offset:2048
	ds_read_b128 v[190:193], v154 offset:3072
	v_lshl_add_u64 v[194:195], s[44:45], 0, v[140:141]
	s_add_i32 m0, s58, 0xc000
	ds_read_b128 v[200:203], v161
	ds_read_b128 v[204:207], v161 offset:1024
	ds_read_b128 v[208:211], v161 offset:2048
	ds_read_b128 v[212:215], v161 offset:3072
	ds_read_b128 v[216:219], v161 offset:4096
	ds_read_b128 v[220:223], v161 offset:5120
	ds_read_b128 v[224:227], v161 offset:6144
	ds_read_b128 v[228:231], v161 offset:7168
	global_load_lds_dwordx4 v[194:195], off
	v_lshl_add_u64 v[194:195], s[44:45], 0, v[138:139]
	s_add_i32 m0, s58, 0xe000
	s_nop 0
	global_load_lds_dwordx4 v[194:195], off
	s_waitcnt vmcnt(8)
	s_waitcnt lgkmcnt(0)
	s_barrier
	s_waitcnt lgkmcnt(0)
	v_mfma_f32_16x16x32_bf16 v[124:127], v[162:165], v[200:203], v[124:127]
	v_mfma_f32_16x16x32_bf16 v[120:123], v[170:173], v[200:203], v[120:123]
	v_mfma_f32_16x16x32_bf16 v[108:111], v[162:165], v[208:211], v[108:111]
	v_mfma_f32_16x16x32_bf16 v[104:107], v[170:173], v[208:211], v[104:107]
	v_mfma_f32_16x16x32_bf16 v[92:95], v[162:165], v[216:219], v[92:95]
	v_mfma_f32_16x16x32_bf16 v[88:91], v[170:173], v[216:219], v[88:91]
	v_mfma_f32_16x16x32_bf16 v[76:79], v[162:165], v[224:227], v[76:79]
	v_mfma_f32_16x16x32_bf16 v[72:75], v[170:173], v[224:227], v[72:75]
	v_mfma_f32_16x16x32_bf16 v[124:127], v[166:169], v[204:207], v[124:127]
	v_mfma_f32_16x16x32_bf16 v[120:123], v[174:177], v[204:207], v[120:123]
	v_mfma_f32_16x16x32_bf16 v[108:111], v[166:169], v[212:215], v[108:111]
	v_mfma_f32_16x16x32_bf16 v[104:107], v[174:177], v[212:215], v[104:107]
	v_mfma_f32_16x16x32_bf16 v[92:95], v[166:169], v[220:223], v[92:95]
	v_mfma_f32_16x16x32_bf16 v[88:91], v[174:177], v[220:223], v[88:91]
	v_mfma_f32_16x16x32_bf16 v[76:79], v[166:169], v[228:231], v[76:79]
	v_mfma_f32_16x16x32_bf16 v[72:75], v[174:177], v[228:231], v[72:75]
	v_mfma_f32_16x16x32_bf16 v[116:119], v[178:181], v[200:203], v[116:119]
	v_mfma_f32_16x16x32_bf16 v[112:115], v[186:189], v[200:203], v[112:115]
	v_mfma_f32_16x16x32_bf16 v[100:103], v[178:181], v[208:211], v[100:103]
	v_mfma_f32_16x16x32_bf16 v[96:99], v[186:189], v[208:211], v[96:99]
	v_mfma_f32_16x16x32_bf16 v[84:87], v[178:181], v[216:219], v[84:87]
	v_mfma_f32_16x16x32_bf16 v[80:83], v[186:189], v[216:219], v[80:83]
	v_mfma_f32_16x16x32_bf16 v[68:71], v[178:181], v[224:227], v[68:71]
	v_mfma_f32_16x16x32_bf16 v[64:67], v[186:189], v[224:227], v[64:67]
	v_mfma_f32_16x16x32_bf16 v[116:119], v[182:185], v[204:207], v[116:119]
	v_mfma_f32_16x16x32_bf16 v[112:115], v[190:193], v[204:207], v[112:115]
	v_mfma_f32_16x16x32_bf16 v[100:103], v[182:185], v[212:215], v[100:103]
	v_mfma_f32_16x16x32_bf16 v[96:99], v[190:193], v[212:215], v[96:99]
	v_mfma_f32_16x16x32_bf16 v[84:87], v[182:185], v[220:223], v[84:87]
	v_mfma_f32_16x16x32_bf16 v[80:83], v[190:193], v[220:223], v[80:83]
	v_mfma_f32_16x16x32_bf16 v[68:71], v[182:185], v[228:231], v[68:71]
	v_mfma_f32_16x16x32_bf16 v[64:67], v[190:193], v[228:231], v[64:67]
	s_barrier
	s_add_i32 s10, s12, s39
	v_lshl_add_u64 v[194:195], s[54:55], 0, v[132:133]
	s_mov_b32 m0, s10
	ds_read_b128 v[200:203], v161 offset:16384
	ds_read_b128 v[204:207], v161 offset:17408
	ds_read_b128 v[208:211], v161 offset:18432
	ds_read_b128 v[212:215], v161 offset:19456
	ds_read_b128 v[216:219], v161 offset:20480
	ds_read_b128 v[220:223], v161 offset:21504
	ds_read_b128 v[224:227], v161 offset:22528
	ds_read_b128 v[228:231], v161 offset:23552
	global_load_lds_dwordx4 v[194:195], off
	s_add_i32 m0, s10, 0x2000
	s_add_u32 s70, s54, 0x40000
	v_lshl_add_u64 v[240:241], s[54:55], 0, v[128:129]
	s_addc_u32 s71, s55, 0
	s_add_i32 s8, s8, s39
	global_load_lds_dwordx4 v[240:241], off
	v_lshl_add_u64 v[242:243], s[70:71], 0, v[132:133]
	s_mov_b32 m0, s8
	v_lshl_add_u64 v[244:245], s[56:57], 0, v[130:131]
	global_load_lds_dwordx4 v[242:243], off
	v_lshl_add_u64 v[242:243], s[70:71], 0, v[128:129]
	s_add_i32 m0, s8, 0x2000
	s_nop 0
	global_load_lds_dwordx4 v[242:243], off
	v_lshl_add_u64 v[242:243], s[56:57], 0, v[134:135]
	s_mov_b32 m0, s58
	s_nop 0
	global_load_lds_dwordx4 v[242:243], off
	s_mov_b32 m0, s59
	s_nop 0
	global_load_lds_dwordx4 v[244:245], off
	s_waitcnt vmcnt(8)
	s_waitcnt lgkmcnt(0)
	s_barrier
	s_waitcnt lgkmcnt(0)
	v_mfma_f32_16x16x32_bf16 v[60:63], v[162:165], v[200:203], v[60:63]
	v_mfma_f32_16x16x32_bf16 v[56:59], v[170:173], v[200:203], v[56:59]
	v_mfma_f32_16x16x32_bf16 v[44:47], v[162:165], v[208:211], v[44:47]
	v_mfma_f32_16x16x32_bf16 v[40:43], v[170:173], v[208:211], v[40:43]
	v_mfma_f32_16x16x32_bf16 v[28:31], v[162:165], v[216:219], v[28:31]
	v_mfma_f32_16x16x32_bf16 v[24:27], v[170:173], v[216:219], v[24:27]
	v_mfma_f32_16x16x32_bf16 v[12:15], v[162:165], v[224:227], v[12:15]
	v_mfma_f32_16x16x32_bf16 v[8:11], v[170:173], v[224:227], v[8:11]
	v_mfma_f32_16x16x32_bf16 v[60:63], v[166:169], v[204:207], v[60:63]
	v_mfma_f32_16x16x32_bf16 v[56:59], v[174:177], v[204:207], v[56:59]
	v_mfma_f32_16x16x32_bf16 v[44:47], v[166:169], v[212:215], v[44:47]
	v_mfma_f32_16x16x32_bf16 v[40:43], v[174:177], v[212:215], v[40:43]
	v_mfma_f32_16x16x32_bf16 v[28:31], v[166:169], v[220:223], v[28:31]
	v_mfma_f32_16x16x32_bf16 v[24:27], v[174:177], v[220:223], v[24:27]
	v_mfma_f32_16x16x32_bf16 v[12:15], v[166:169], v[228:231], v[12:15]
	v_mfma_f32_16x16x32_bf16 v[8:11], v[174:177], v[228:231], v[8:11]
	v_mfma_f32_16x16x32_bf16 v[52:55], v[178:181], v[200:203], v[52:55]
	v_mfma_f32_16x16x32_bf16 v[48:51], v[186:189], v[200:203], v[48:51]
	v_mfma_f32_16x16x32_bf16 v[36:39], v[178:181], v[208:211], v[36:39]
	v_mfma_f32_16x16x32_bf16 v[32:35], v[186:189], v[208:211], v[32:35]
	v_mfma_f32_16x16x32_bf16 v[20:23], v[178:181], v[216:219], v[20:23]
	v_mfma_f32_16x16x32_bf16 v[16:19], v[186:189], v[216:219], v[16:19]
	v_mfma_f32_16x16x32_bf16 v[4:7], v[178:181], v[224:227], v[4:7]
	v_mfma_f32_16x16x32_bf16 v[0:3], v[186:189], v[224:227], v[0:3]
	v_mfma_f32_16x16x32_bf16 v[52:55], v[182:185], v[204:207], v[52:55]
	v_mfma_f32_16x16x32_bf16 v[48:51], v[190:193], v[204:207], v[48:51]
	v_mfma_f32_16x16x32_bf16 v[36:39], v[182:185], v[212:215], v[36:39]
	v_mfma_f32_16x16x32_bf16 v[32:35], v[190:193], v[212:215], v[32:35]
	v_mfma_f32_16x16x32_bf16 v[20:23], v[182:185], v[220:223], v[20:23]
	v_mfma_f32_16x16x32_bf16 v[16:19], v[190:193], v[220:223], v[16:19]
	v_mfma_f32_16x16x32_bf16 v[4:7], v[182:185], v[228:231], v[4:7]
	v_mfma_f32_16x16x32_bf16 v[0:3], v[190:193], v[228:231], v[0:3]
	s_barrier
; #define PG8_STAGE(bufoff, gbase, voff) do { _Pragma("unroll") for (int _i = 0; _i < 2; ++_i) \
;         __builtin_amdgcn_global_load_lds((const unsigned*)((const char*)(gbase) + (voff)[_i]), (PG8_LAS unsigned*)(lds + (bufoff) + ldsw + _i * 8192), 16, 0, 0); } while (0)
; #define PG8_LDA(dst, b, h) do { _Pragma("unroll") for (int m = 0; m < 4; ++m) _Pragma("unroll") for (int k = 0; k < 2; ++k) dst[m][k] = *(const PG8_LAS bf16x8*)(lds + PG8_SA(b, h) + aoff + m * 2048 + k * 1024); } while (0)
; #define PG8_LDB(dst, b, h) do { _Pragma("unroll") for (int n = 0; n < 2; ++n) _Pragma("unroll") for (int k = 0; k < 2; ++k) dst[n][k] = *(const PG8_LAS bf16x8*)(lds + PG8_SB(b, h) + boff + n * 2048 + k * 1024); } while (0)
; #define PG8_MMA(ai, bj, At, Bt) do { __builtin_amdgcn_s_setprio(1); _Pragma("unroll") for (int m = 0; m < 4; ++m) _Pragma("unroll") for (int n = 0; n < 2; ++n) _Pragma("unroll") for (int k = 0; k < 2; ++k) \
;         acc[ai][bj][m][n] = __builtin_amdgcn_mfma_f32_16x16x32_bf16(Bt[n][k], At[m][k], acc[ai][bj][m][n], 0, 0, 0); __builtin_amdgcn_s_setprio(0); } while (0)
; #define PG8_WAIT_V(n) asm volatile("s_waitcnt vmcnt(" #n ")" ::: "memory")
; #define PG8_WAIT_L(n) asm volatile("s_waitcnt lgkmcnt(" #n ")" ::: "memory")
; #define PG8_BAR __builtin_amdgcn_s_barrier()
; #define PG8_SCHED __builtin_amdgcn_sched_barrier(0)
; template <class Epi, class Sched, bool ALIGN_EPI = false, bool SP2 = false>
; __device__ __forceinline__ void gemm_phase(PG8_LAS unsigned char* lds, const Gemm g, const Sched& S, const Epi& E) {
;     ...
;             PG8_LDB(B0, 1, 0); PG8_LDB(B1, 1, 1); PG8_SCHED; PG8_LDA(At, 1, 0); PG8_STAGE(PG8_SA(0, 1), a2 + hstep, voffA);
;             PG8_WAIT_V(8); PG8_WAIT_L(0); PG8_BAR; PG8_MMA(0, 0, At, B0); PG8_MMA(0, 1, At, B1); PG8_BAR; PG8_SCHED;
.Lmid_g1e:
	s_add_i32 s8, 0, 0x18000
	v_add_u32_e32 v154, s8, v157
	s_add_i32 s10, 0, 0x1c000
	ds_read_b128 v[162:165], v154
	ds_read_b128 v[166:169], v154 offset:1024
	ds_read_b128 v[170:173], v154 offset:2048
	ds_read_b128 v[174:177], v154 offset:3072
	v_add_u32_e32 v154, s10, v157
	ds_read_b128 v[178:181], v154
	ds_read_b128 v[182:185], v154 offset:1024
	ds_read_b128 v[186:189], v154 offset:2048
	ds_read_b128 v[190:193], v154 offset:3072
	s_add_u32 s56, s56, 0x40000
	s_addc_u32 s57, s57, 0
	s_mov_b32 m0, s60
	v_lshl_add_u64 v[246:247], s[56:57], 0, v[134:135]
	ds_read_b128 v[200:203], v161 offset:32768
	ds_read_b128 v[204:207], v161 offset:33792
	ds_read_b128 v[208:211], v161 offset:34816
	ds_read_b128 v[212:215], v161 offset:35840
	ds_read_b128 v[216:219], v161 offset:36864
	ds_read_b128 v[220:223], v161 offset:37888
	ds_read_b128 v[224:227], v161 offset:38912
	ds_read_b128 v[228:231], v161 offset:39936
	global_load_lds_dwordx4 v[246:247], off
	v_lshl_add_u64 v[246:247], s[56:57], 0, v[130:131]
	s_mov_b32 m0, s61
	s_nop 0
	global_load_lds_dwordx4 v[246:247], off
	s_waitcnt vmcnt(8)
	s_waitcnt lgkmcnt(0)
	s_barrier
	s_waitcnt lgkmcnt(0)
	v_mfma_f32_16x16x32_bf16 v[124:127], v[162:165], v[200:203], v[124:127]
	v_mfma_f32_16x16x32_bf16 v[120:123], v[170:173], v[200:203], v[120:123]
	v_mfma_f32_16x16x32_bf16 v[108:111], v[162:165], v[208:211], v[108:111]
	v_mfma_f32_16x16x32_bf16 v[104:107], v[170:173], v[208:211], v[104:107]
	v_mfma_f32_16x16x32_bf16 v[92:95], v[162:165], v[216:219], v[92:95]
	v_mfma_f32_16x16x32_bf16 v[88:91], v[170:173], v[216:219], v[88:91]
	v_mfma_f32_16x16x32_bf16 v[76:79], v[162:165], v[224:227], v[76:79]
	v_mfma_f32_16x16x32_bf16 v[72:75], v[170:173], v[224:227], v[72:75]
	v_mfma_f32_16x16x32_bf16 v[124:127], v[166:169], v[204:207], v[124:127]
	v_mfma_f32_16x16x32_bf16 v[120:123], v[174:177], v[204:207], v[120:123]
	v_mfma_f32_16x16x32_bf16 v[108:111], v[166:169], v[212:215], v[108:111]
	v_mfma_f32_16x16x32_bf16 v[104:107], v[174:177], v[212:215], v[104:107]
	v_mfma_f32_16x16x32_bf16 v[92:95], v[166:169], v[220:223], v[92:95]
	v_mfma_f32_16x16x32_bf16 v[88:91], v[174:177], v[220:223], v[88:91]
	v_mfma_f32_16x16x32_bf16 v[76:79], v[166:169], v[228:231], v[76:79]
	v_mfma_f32_16x16x32_bf16 v[72:75], v[174:177], v[228:231], v[72:75]
	v_mfma_f32_16x16x32_bf16 v[116:119], v[178:181], v[200:203], v[116:119]
	v_mfma_f32_16x16x32_bf16 v[112:115], v[186:189], v[200:203], v[112:115]
	v_mfma_f32_16x16x32_bf16 v[100:103], v[178:181], v[208:211], v[100:103]
	v_mfma_f32_16x16x32_bf16 v[96:99], v[186:189], v[208:211], v[96:99]
	v_mfma_f32_16x16x32_bf16 v[84:87], v[178:181], v[216:219], v[84:87]
	v_mfma_f32_16x16x32_bf16 v[80:83], v[186:189], v[216:219], v[80:83]
	v_mfma_f32_16x16x32_bf16 v[68:71], v[178:181], v[224:227], v[68:71]
	v_mfma_f32_16x16x32_bf16 v[64:67], v[186:189], v[224:227], v[64:67]
	v_mfma_f32_16x16x32_bf16 v[116:119], v[182:185], v[204:207], v[116:119]
	v_mfma_f32_16x16x32_bf16 v[112:115], v[190:193], v[204:207], v[112:115]
	v_mfma_f32_16x16x32_bf16 v[100:103], v[182:185], v[212:215], v[100:103]
	v_mfma_f32_16x16x32_bf16 v[96:99], v[190:193], v[212:215], v[96:99]
	v_mfma_f32_16x16x32_bf16 v[84:87], v[182:185], v[220:223], v[84:87]
	v_mfma_f32_16x16x32_bf16 v[80:83], v[190:193], v[220:223], v[80:83]
	v_mfma_f32_16x16x32_bf16 v[68:71], v[182:185], v[228:231], v[68:71]
	v_mfma_f32_16x16x32_bf16 v[64:67], v[190:193], v[228:231], v[64:67]
	s_barrier
; #define PG8_STAGE(bufoff, gbase, voff) do { _Pragma("unroll") for (int _i = 0; _i < 2; ++_i) \
;         __builtin_amdgcn_global_load_lds((const unsigned*)((const char*)(gbase) + (voff)[_i]), (PG8_LAS unsigned*)(lds + (bufoff) + ldsw + _i * 8192), 16, 0, 0); } while (0)
; #define PG8_LDA(dst, b, h) do { _Pragma("unroll") for (int m = 0; m < 4; ++m) _Pragma("unroll") for (int k = 0; k < 2; ++k) dst[m][k] = *(const PG8_LAS bf16x8*)(lds + PG8_SA(b, h) + aoff + m * 2048 + k * 1024); } while (0)
; #define PG8_MMA(ai, bj, At, Bt) do { __builtin_amdgcn_s_setprio(1); _Pragma("unroll") for (int m = 0; m < 4; ++m) _Pragma("unroll") for (int n = 0; n < 2; ++n) _Pragma("unroll") for (int k = 0; k < 2; ++k) \
;         acc[ai][bj][m][n] = __builtin_amdgcn_mfma_f32_16x16x32_bf16(Bt[n][k], At[m][k], acc[ai][bj][m][n], 0, 0, 0); __builtin_amdgcn_s_setprio(0); } while (0)
; #define PG8_WAIT_V(n) asm volatile("s_waitcnt vmcnt(" #n ")" ::: "memory")
; #define PG8_WAIT_L(n) asm volatile("s_waitcnt lgkmcnt(" #n ")" ::: "memory")
; #define PG8_BAR __builtin_amdgcn_s_barrier()
; #define PG8_SCHED __builtin_amdgcn_sched_barrier(0)
; template <class Epi, class Sched, bool ALIGN_EPI = false, bool SP2 = false>
; __device__ __forceinline__ void gemm_phase(PG8_LAS unsigned char* lds, const Gemm g, const Sched& S, const Epi& E) {
;     ...
;             PG8_LDA(At, 1, 1); PG8_STAGE(PG8_SB(1, 0), b3, voffB); PG8_STAGE(PG8_SB(1, 1), b3 + hstep, voffB); PG8_STAGE(PG8_SA(1, 0), a3, voffA);
;             PG8_WAIT_V(8); PG8_WAIT_L(0); PG8_BAR; PG8_MMA(1, 0, At, B0); PG8_MMA(1, 1, At, B1); PG8_BAR; PG8_SCHED;
	s_add_i32 s8, s8, s39
	v_lshl_add_u64 v[194:195], v[194:195], 0, s[22:23]
	s_mov_b32 m0, s8
	ds_read_b128 v[200:203], v161 offset:49152
	ds_read_b128 v[204:207], v161 offset:50176
	ds_read_b128 v[208:211], v161 offset:51200
	ds_read_b128 v[212:215], v161 offset:52224
	ds_read_b128 v[216:219], v161 offset:53248
	ds_read_b128 v[220:223], v161 offset:54272
	ds_read_b128 v[224:227], v161 offset:55296
	ds_read_b128 v[228:231], v161 offset:56320
	global_load_lds_dwordx4 v[194:195], off
	s_add_i32 m0, s8, 0x2000
	s_add_u32 s54, s54, 0x40080
	v_lshl_add_u64 v[194:195], v[240:241], 0, s[22:23]
	s_addc_u32 s55, s55, 0
	s_add_i32 s8, s10, s39
	global_load_lds_dwordx4 v[194:195], off
	v_lshl_add_u64 v[194:195], s[54:55], 0, v[132:133]
	s_mov_b32 m0, s8
	s_nop 0
	global_load_lds_dwordx4 v[194:195], off
	v_lshl_add_u64 v[194:195], s[54:55], 0, v[128:129]
	s_add_i32 m0, s8, 0x2000
	s_nop 0
	global_load_lds_dwordx4 v[194:195], off
	v_lshl_add_u64 v[194:195], v[242:243], 0, s[22:23]
	s_mov_b32 m0, s64
	s_nop 0
	global_load_lds_dwordx4 v[194:195], off
	v_lshl_add_u64 v[194:195], v[244:245], 0, s[22:23]
	s_mov_b32 m0, s65
	s_nop 0
	global_load_lds_dwordx4 v[194:195], off
	s_waitcnt vmcnt(8)
	s_waitcnt lgkmcnt(0)
	s_barrier
	s_waitcnt lgkmcnt(0)
	v_mfma_f32_16x16x32_bf16 v[60:63], v[162:165], v[200:203], v[60:63]
	v_mfma_f32_16x16x32_bf16 v[56:59], v[170:173], v[200:203], v[56:59]
	v_mfma_f32_16x16x32_bf16 v[44:47], v[162:165], v[208:211], v[44:47]
	v_mfma_f32_16x16x32_bf16 v[40:43], v[170:173], v[208:211], v[40:43]
	v_mfma_f32_16x16x32_bf16 v[28:31], v[162:165], v[216:219], v[28:31]
	v_mfma_f32_16x16x32_bf16 v[24:27], v[170:173], v[216:219], v[24:27]
	v_mfma_f32_16x16x32_bf16 v[12:15], v[162:165], v[224:227], v[12:15]
	v_mfma_f32_16x16x32_bf16 v[8:11], v[170:173], v[224:227], v[8:11]
	v_mfma_f32_16x16x32_bf16 v[60:63], v[166:169], v[204:207], v[60:63]
	v_mfma_f32_16x16x32_bf16 v[56:59], v[174:177], v[204:207], v[56:59]
	v_mfma_f32_16x16x32_bf16 v[44:47], v[166:169], v[212:215], v[44:47]
	v_mfma_f32_16x16x32_bf16 v[40:43], v[174:177], v[212:215], v[40:43]
	v_mfma_f32_16x16x32_bf16 v[28:31], v[166:169], v[220:223], v[28:31]
	v_mfma_f32_16x16x32_bf16 v[24:27], v[174:177], v[220:223], v[24:27]
	v_mfma_f32_16x16x32_bf16 v[12:15], v[166:169], v[228:231], v[12:15]
	v_mfma_f32_16x16x32_bf16 v[8:11], v[174:177], v[228:231], v[8:11]
	v_mfma_f32_16x16x32_bf16 v[52:55], v[178:181], v[200:203], v[52:55]
	v_mfma_f32_16x16x32_bf16 v[48:51], v[186:189], v[200:203], v[48:51]
	v_mfma_f32_16x16x32_bf16 v[36:39], v[178:181], v[208:211], v[36:39]
	v_mfma_f32_16x16x32_bf16 v[32:35], v[186:189], v[208:211], v[32:35]
	v_mfma_f32_16x16x32_bf16 v[20:23], v[178:181], v[216:219], v[20:23]
	v_mfma_f32_16x16x32_bf16 v[16:19], v[186:189], v[216:219], v[16:19]
	v_mfma_f32_16x16x32_bf16 v[4:7], v[178:181], v[224:227], v[4:7]
	v_mfma_f32_16x16x32_bf16 v[0:3], v[186:189], v[224:227], v[0:3]
	v_mfma_f32_16x16x32_bf16 v[52:55], v[182:185], v[204:207], v[52:55]
	v_mfma_f32_16x16x32_bf16 v[48:51], v[190:193], v[204:207], v[48:51]
	v_mfma_f32_16x16x32_bf16 v[36:39], v[182:185], v[212:215], v[36:39]
	v_mfma_f32_16x16x32_bf16 v[32:35], v[190:193], v[212:215], v[32:35]
	v_mfma_f32_16x16x32_bf16 v[20:23], v[182:185], v[220:223], v[20:23]
	v_mfma_f32_16x16x32_bf16 v[16:19], v[190:193], v[220:223], v[16:19]
	v_mfma_f32_16x16x32_bf16 v[4:7], v[182:185], v[228:231], v[4:7]
	v_mfma_f32_16x16x32_bf16 v[0:3], v[190:193], v[228:231], v[0:3]
	s_barrier
	s_add_i32 s69, s69, 2
	s_add_u32 s47, s47, 0x100
	s_addc_u32 s49, s49, 0
	s_add_u32 s44, s44, 0x100
	s_addc_u32 s45, s45, 0
	s_cmp_gt_u32 s69, 13
	s_cbranch_scc0 .LBB0_414
	s_and_b64 vcc, exec, s[20:21]
	s_cbranch_vccz .LBB0_417
	s_barrier
